# GEMM K-loops: per-segment s_setprio flips deleted; one static s_setprio 1 for waves 4-7 before each K-loop, reset after
# speedup vs baseline: 1.0094x; 1.0008x over previous
; #define PG8_STAGE(bufoff, gbase, voff) do { _Pragma("unroll") for (int _i = 0; _i < 2; ++_i) \
;         __builtin_amdgcn_global_load_lds((const unsigned*)((const char*)(gbase) + (voff)[_i]), (PG8_LAS unsigned*)(lds + (bufoff) + ldsw + _i * 8192), 16, 0, 0); } while (0)
; #define PG8_LDA(dst, b, h) do { _Pragma("unroll") for (int m = 0; m < 4; ++m) _Pragma("unroll") for (int k = 0; k < 2; ++k) dst[m][k] = *(const PG8_LAS bf16x8*)(lds + PG8_SA(b, h) + aoff + m * 2048 + k * 1024); } while (0)
; #define PG8_LDB(dst, b, h) do { _Pragma("unroll") for (int n = 0; n < 2; ++n) _Pragma("unroll") for (int k = 0; k < 2; ++k) dst[n][k] = *(const PG8_LAS bf16x8*)(lds + PG8_SB(b, h) + boff + n * 2048 + k * 1024); } while (0)
; #define PG8_SCHED __builtin_amdgcn_sched_barrier(0)
; template <class Epi, class Sched, bool ALIGN_EPI = false, bool SP2 = false>
; __device__ __forceinline__ void gemm_phase(PG8_LAS unsigned char* lds, const Gemm g, const Sched& S, const Epi& E) {
;     ...
;         const bool has_next = S.next(ui + 1, nxt);
;         const char* nA = has_next ? (const char*)g.A + (size_t)nxt.pm * tstep : cA; const char* nB = has_next ? (const char*)g.Bt + (size_t)nxt.pn * tstep : cB;
;         for (int t = 0; t < nt; t += 2) {
;             const bool last = (t == nt - 2);
;             const char* a1 = cA + (size_t)(t + 1) * kstep;
;             const char* a2 = last ? nA : cA + (size_t)(t + 2) * kstep; const char* b2 = last ? nB : cB + (size_t)(t + 2) * kstep;
;             const char* a3 = a2 + kstep; const char* b3 = b2 + kstep;
;             if (last && has_next) S.a_ready(nxt);
;             if constexpr (SP2) {
;             PG8_LDB(B0, 0, 0); PG8_LDB(B1, 0, 1); PG8_SCHED; PG8_LDA(At, 0, 0); PG8_STAGE(PG8_SA(1, 1), a1 + hstep, voffA);
;     ...
;         for (int a = 0; a < 2; ++a)
; #pragma unroll
;             for (int b = 0; b < 2; ++b)
; #pragma unroll
;                 for (int m = 0; m < 4; ++m)
; #pragma unroll
;                     for (int n = 0; n < 2; ++n) acc[a][b][m][n] = (f32x4){0.f, 0.f, 0.f, 0.f};
.LBB0_292:
	s_ashr_i32 s17, s16, 31
	s_lshl_b64 s[18:19], s[16:17], 19
	v_readlane_b32 s20, v253, 45
	v_readlane_b32 s21, v253, 46
	s_add_u32 s18, s20, s18
	s_addc_u32 s19, s21, s19
	s_and_b64 s[20:21], s[0:1], exec
	s_cselect_b32 s17, s19, s25
	s_cselect_b32 s46, s18, s24
	s_ashr_i32 s15, s14, 31
	s_lshl_b64 s[20:21], s[14:15], 19
	s_add_u32 s20, s64, s20
	s_addc_u32 s21, s65, s21
	s_and_b64 s[28:29], s[0:1], exec
	s_cselect_b32 s15, s21, s27
	s_cselect_b32 s47, s20, s26
	s_add_u32 s24, s24, 0x40080
	s_addc_u32 s25, s25, 0
	s_add_u32 s48, s26, 0x100
	v_mov_b32_e32 v0, 0
	s_addc_u32 s49, s27, 0
	s_mov_b32 s50, -2
	v_mov_b32_e32 v1, v0
	v_mov_b32_e32 v2, v0
	v_mov_b32_e32 v3, v0
	v_mov_b32_e32 v4, v0
	v_mov_b32_e32 v5, v0
	v_mov_b32_e32 v6, v0
	v_mov_b32_e32 v7, v0
	v_mov_b32_e32 v16, v0
	v_mov_b32_e32 v17, v0
	v_mov_b32_e32 v18, v0
	v_mov_b32_e32 v19, v0
	v_mov_b32_e32 v20, v0
	v_mov_b32_e32 v21, v0
	v_mov_b32_e32 v22, v0
	v_mov_b32_e32 v23, v0
	v_mov_b32_e32 v32, v0
	v_mov_b32_e32 v33, v0
	v_mov_b32_e32 v34, v0
	v_mov_b32_e32 v35, v0
	v_mov_b32_e32 v36, v0
	v_mov_b32_e32 v37, v0
	v_mov_b32_e32 v38, v0
	v_mov_b32_e32 v39, v0
	v_mov_b32_e32 v48, v0
	v_mov_b32_e32 v49, v0
	v_mov_b32_e32 v50, v0
	v_mov_b32_e32 v51, v0
	v_mov_b32_e32 v52, v0
	v_mov_b32_e32 v53, v0
	v_mov_b32_e32 v54, v0
	v_mov_b32_e32 v55, v0
	v_mov_b32_e32 v8, v0
	v_mov_b32_e32 v9, v0
	v_mov_b32_e32 v10, v0
	v_mov_b32_e32 v11, v0
	v_mov_b32_e32 v12, v0
	v_mov_b32_e32 v13, v0
	v_mov_b32_e32 v14, v0
	v_mov_b32_e32 v15, v0
	v_mov_b32_e32 v24, v0
	v_mov_b32_e32 v25, v0
	v_mov_b32_e32 v26, v0
	v_mov_b32_e32 v27, v0
	v_mov_b32_e32 v28, v0
	v_mov_b32_e32 v29, v0
	v_mov_b32_e32 v30, v0
	v_mov_b32_e32 v31, v0
	v_mov_b32_e32 v40, v0
	v_mov_b32_e32 v41, v0
	v_mov_b32_e32 v42, v0
	v_mov_b32_e32 v43, v0
	v_mov_b32_e32 v44, v0
	v_mov_b32_e32 v45, v0
	v_mov_b32_e32 v46, v0
	v_mov_b32_e32 v47, v0
	v_mov_b32_e32 v56, v0
	v_mov_b32_e32 v57, v0
	v_mov_b32_e32 v58, v0
	v_mov_b32_e32 v59, v0
	v_mov_b32_e32 v60, v0
	v_mov_b32_e32 v61, v0
	v_mov_b32_e32 v62, v0
	v_mov_b32_e32 v63, v0
	v_mov_b32_e32 v64, v0
	v_mov_b32_e32 v65, v0
	v_mov_b32_e32 v66, v0
	v_mov_b32_e32 v67, v0
	v_mov_b32_e32 v68, v0
	v_mov_b32_e32 v69, v0
	v_mov_b32_e32 v70, v0
	v_mov_b32_e32 v71, v0
	v_mov_b32_e32 v80, v0
	v_mov_b32_e32 v81, v0
	v_mov_b32_e32 v82, v0
	v_mov_b32_e32 v83, v0
	v_mov_b32_e32 v84, v0
	v_mov_b32_e32 v85, v0
	v_mov_b32_e32 v86, v0
	v_mov_b32_e32 v87, v0
	v_mov_b32_e32 v96, v0
	v_mov_b32_e32 v97, v0
	v_mov_b32_e32 v98, v0
	v_mov_b32_e32 v99, v0
	v_mov_b32_e32 v100, v0
	v_mov_b32_e32 v101, v0
	v_mov_b32_e32 v102, v0
	v_mov_b32_e32 v103, v0
	v_mov_b32_e32 v112, v0
	v_mov_b32_e32 v113, v0
	v_mov_b32_e32 v114, v0
	v_mov_b32_e32 v115, v0
	v_mov_b32_e32 v116, v0
	v_mov_b32_e32 v117, v0
	v_mov_b32_e32 v118, v0
	v_mov_b32_e32 v119, v0
	v_mov_b32_e32 v72, v0
	v_mov_b32_e32 v73, v0
	v_mov_b32_e32 v74, v0
	v_mov_b32_e32 v75, v0
	v_mov_b32_e32 v76, v0
	v_mov_b32_e32 v77, v0
	v_mov_b32_e32 v78, v0
	v_mov_b32_e32 v79, v0
	v_mov_b32_e32 v88, v0
	v_mov_b32_e32 v89, v0
	v_mov_b32_e32 v90, v0
	v_mov_b32_e32 v91, v0
	v_mov_b32_e32 v92, v0
	v_mov_b32_e32 v93, v0
	v_mov_b32_e32 v94, v0
	v_mov_b32_e32 v95, v0
	v_mov_b32_e32 v104, v0
	v_mov_b32_e32 v105, v0
	v_mov_b32_e32 v106, v0
	v_mov_b32_e32 v107, v0
	v_mov_b32_e32 v108, v0
	v_mov_b32_e32 v109, v0
	v_mov_b32_e32 v110, v0
	v_mov_b32_e32 v111, v0
	v_mov_b32_e32 v120, v0
	v_mov_b32_e32 v121, v0
	v_mov_b32_e32 v122, v0
	v_mov_b32_e32 v123, v0
	v_mov_b32_e32 v124, v0
	v_mov_b32_e32 v125, v0
	v_mov_b32_e32 v126, v0
	v_mov_b32_e32 v127, v0
	v_readfirstlane_b32 s98, v197
	s_nop 3
	s_cmpk_gt_u32 s98, 0xff
	s_cbranch_scc0 .Lkp_8
	s_setprio 1
.Lkp_8:
.LBB0_293:
	ds_read_b128 v[144:147], v151
	ds_read_b128 v[154:157], v151 offset:1024
	ds_read_b128 v[158:161], v151 offset:2048
	ds_read_b128 v[162:165], v151 offset:3072
	ds_read_b128 v[166:169], v152
	ds_read_b128 v[170:173], v152 offset:1024
	ds_read_b128 v[174:177], v152 offset:2048
	ds_read_b128 v[178:181], v152 offset:3072
	s_add_u32 s26, s24, 0xfffc0080
	s_addc_u32 s27, s25, -1
	s_cmp_eq_u32 s50, 12
	s_cselect_b32 s29, s17, s27
	s_cselect_b32 s28, s46, s26
	s_cselect_b32 s27, s15, s49
	s_cselect_b32 s26, s47, s48
	v_lshl_add_u64 v[194:195], s[24:25], 0, v[136:137]
	s_add_i32 m0, s23, 0xc000
	ds_read_b128 v[182:185], v153
	ds_read_b128 v[186:189], v153 offset:1024
	ds_read_b128 v[190:193], v153 offset:2048
	ds_read_b128 v[198:201], v153 offset:3072
	ds_read_b128 v[202:205], v153 offset:4096
	ds_read_b128 v[206:209], v153 offset:5120
	ds_read_b128 v[210:213], v153 offset:6144
	ds_read_b128 v[214:217], v153 offset:7168
	global_load_lds_dwordx4 v[194:195], off
	v_lshl_add_u64 v[194:195], s[24:25], 0, v[138:139]
	s_add_i32 m0, s23, 0xe000
	s_nop 0
	global_load_lds_dwordx4 v[194:195], off
	s_waitcnt vmcnt(8)
	s_waitcnt lgkmcnt(0)
	s_barrier
; #define PG8_STAGE(bufoff, gbase, voff) do { _Pragma("unroll") for (int _i = 0; _i < 2; ++_i) \
;         __builtin_amdgcn_global_load_lds((const unsigned*)((const char*)(gbase) + (voff)[_i]), (PG8_LAS unsigned*)(lds + (bufoff) + ldsw + _i * 8192), 16, 0, 0); } while (0)
; #define PG8_LDA(dst, b, h) do { _Pragma("unroll") for (int m = 0; m < 4; ++m) _Pragma("unroll") for (int k = 0; k < 2; ++k) dst[m][k] = *(const PG8_LAS bf16x8*)(lds + PG8_SA(b, h) + aoff + m * 2048 + k * 1024); } while (0)
; #define PG8_MMA(ai, bj, At, Bt) do { __builtin_amdgcn_s_setprio(1); _Pragma("unroll") for (int m = 0; m < 4; ++m) _Pragma("unroll") for (int n = 0; n < 2; ++n) _Pragma("unroll") for (int k = 0; k < 2; ++k) \
;         acc[ai][bj][m][n] = __builtin_amdgcn_mfma_f32_16x16x32_bf16(Bt[n][k], At[m][k], acc[ai][bj][m][n], 0, 0, 0); __builtin_amdgcn_s_setprio(0); } while (0)
; #define PG8_WAIT_V(n) asm volatile("s_waitcnt vmcnt(" #n ")" ::: "memory")
; #define PG8_WAIT_L(n) asm volatile("s_waitcnt lgkmcnt(" #n ")" ::: "memory")
; #define PG8_BAR __builtin_amdgcn_s_barrier()
; #define PG8_SCHED __builtin_amdgcn_sched_barrier(0)
; template <class Epi, class Sched, bool ALIGN_EPI = false, bool SP2 = false>
; __device__ __forceinline__ void gemm_phase(PG8_LAS unsigned char* lds, const Gemm g, const Sched& S, const Epi& E) {
;     ...
;             PG8_WAIT_V(8); PG8_WAIT_L(0); PG8_BAR; PG8_MMA(0, 0, At, B0); PG8_MMA(0, 1, At, B1); PG8_BAR; PG8_SCHED;
;             PG8_LDA(At, 0, 1); PG8_STAGE(PG8_SB(0, 0), b2, voffB); PG8_STAGE(PG8_SB(0, 1), b2 + hstep, voffB); PG8_STAGE(PG8_SA(0, 0), a2, voffA);
;             PG8_WAIT_V(8); PG8_WAIT_L(0); PG8_BAR; PG8_MMA(1, 0, At, B0); PG8_MMA(1, 1, At, B1); PG8_BAR; PG8_SCHED;
	s_waitcnt lgkmcnt(0)
	v_mfma_f32_16x16x32_bf16 v[124:127], v[144:147], v[182:185], v[124:127]
	v_mfma_f32_16x16x32_bf16 v[120:123], v[158:161], v[182:185], v[120:123]
	v_mfma_f32_16x16x32_bf16 v[108:111], v[144:147], v[190:193], v[108:111]
	v_mfma_f32_16x16x32_bf16 v[104:107], v[158:161], v[190:193], v[104:107]
	v_mfma_f32_16x16x32_bf16 v[92:95], v[144:147], v[202:205], v[92:95]
	v_mfma_f32_16x16x32_bf16 v[88:91], v[158:161], v[202:205], v[88:91]
	v_mfma_f32_16x16x32_bf16 v[76:79], v[144:147], v[210:213], v[76:79]
	v_mfma_f32_16x16x32_bf16 v[72:75], v[158:161], v[210:213], v[72:75]
	v_mfma_f32_16x16x32_bf16 v[124:127], v[154:157], v[186:189], v[124:127]
	v_mfma_f32_16x16x32_bf16 v[120:123], v[162:165], v[186:189], v[120:123]
	v_mfma_f32_16x16x32_bf16 v[108:111], v[154:157], v[198:201], v[108:111]
	v_mfma_f32_16x16x32_bf16 v[104:107], v[162:165], v[198:201], v[104:107]
	v_mfma_f32_16x16x32_bf16 v[92:95], v[154:157], v[206:209], v[92:95]
	v_mfma_f32_16x16x32_bf16 v[88:91], v[162:165], v[206:209], v[88:91]
	v_mfma_f32_16x16x32_bf16 v[76:79], v[154:157], v[214:217], v[76:79]
	v_mfma_f32_16x16x32_bf16 v[72:75], v[162:165], v[214:217], v[72:75]
	v_mfma_f32_16x16x32_bf16 v[116:119], v[166:169], v[182:185], v[116:119]
	v_mfma_f32_16x16x32_bf16 v[112:115], v[174:177], v[182:185], v[112:115]
	v_mfma_f32_16x16x32_bf16 v[100:103], v[166:169], v[190:193], v[100:103]
	v_mfma_f32_16x16x32_bf16 v[96:99], v[174:177], v[190:193], v[96:99]
	v_mfma_f32_16x16x32_bf16 v[84:87], v[166:169], v[202:205], v[84:87]
	v_mfma_f32_16x16x32_bf16 v[80:83], v[174:177], v[202:205], v[80:83]
	v_mfma_f32_16x16x32_bf16 v[68:71], v[166:169], v[210:213], v[68:71]
	v_mfma_f32_16x16x32_bf16 v[64:67], v[174:177], v[210:213], v[64:67]
	v_mfma_f32_16x16x32_bf16 v[116:119], v[170:173], v[186:189], v[116:119]
	v_mfma_f32_16x16x32_bf16 v[112:115], v[178:181], v[186:189], v[112:115]
	v_mfma_f32_16x16x32_bf16 v[100:103], v[170:173], v[198:201], v[100:103]
	v_mfma_f32_16x16x32_bf16 v[96:99], v[178:181], v[198:201], v[96:99]
	v_mfma_f32_16x16x32_bf16 v[84:87], v[170:173], v[206:209], v[84:87]
	v_mfma_f32_16x16x32_bf16 v[80:83], v[178:181], v[206:209], v[80:83]
	v_mfma_f32_16x16x32_bf16 v[68:71], v[170:173], v[214:217], v[68:71]
	v_mfma_f32_16x16x32_bf16 v[64:67], v[178:181], v[214:217], v[64:67]
	s_barrier
	s_add_i32 s51, s42, s30
	v_lshl_add_u64 v[194:195], s[26:27], 0, v[130:131]
	s_mov_b32 m0, s51
	ds_read_b128 v[182:185], v153 offset:16384
	ds_read_b128 v[186:189], v153 offset:17408
	ds_read_b128 v[190:193], v153 offset:18432
	ds_read_b128 v[198:201], v153 offset:19456
	ds_read_b128 v[202:205], v153 offset:20480
	ds_read_b128 v[206:209], v153 offset:21504
	ds_read_b128 v[210:213], v153 offset:22528
	ds_read_b128 v[214:217], v153 offset:23552
	global_load_lds_dwordx4 v[194:195], off
	s_add_i32 m0, s51, 0x2000
	s_add_u32 s52, s26, 0x40000
	v_lshl_add_u64 v[218:219], s[26:27], 0, v[134:135]
	s_addc_u32 s53, s27, 0
	s_add_i32 s51, s43, s30
	global_load_lds_dwordx4 v[218:219], off
	v_lshl_add_u64 v[220:221], s[52:53], 0, v[130:131]
	s_mov_b32 m0, s51
	v_lshl_add_u64 v[222:223], s[28:29], 0, v[132:133]
	global_load_lds_dwordx4 v[220:221], off
	v_lshl_add_u64 v[220:221], s[52:53], 0, v[134:135]
	s_add_i32 m0, s51, 0x2000
	s_nop 0
	global_load_lds_dwordx4 v[220:221], off
	v_lshl_add_u64 v[220:221], s[28:29], 0, v[128:129]
	s_mov_b32 m0, s23
	s_nop 0
	global_load_lds_dwordx4 v[220:221], off
	s_mov_b32 m0, s34
	s_nop 0
	global_load_lds_dwordx4 v[222:223], off
	s_waitcnt vmcnt(8)
	s_waitcnt lgkmcnt(0)
	s_barrier
	s_waitcnt lgkmcnt(0)
	v_mfma_f32_16x16x32_bf16 v[60:63], v[144:147], v[182:185], v[60:63]
	v_mfma_f32_16x16x32_bf16 v[56:59], v[158:161], v[182:185], v[56:59]
	v_mfma_f32_16x16x32_bf16 v[44:47], v[144:147], v[190:193], v[44:47]
	v_mfma_f32_16x16x32_bf16 v[40:43], v[158:161], v[190:193], v[40:43]
	v_mfma_f32_16x16x32_bf16 v[28:31], v[144:147], v[202:205], v[28:31]
	v_mfma_f32_16x16x32_bf16 v[24:27], v[158:161], v[202:205], v[24:27]
	v_mfma_f32_16x16x32_bf16 v[12:15], v[144:147], v[210:213], v[12:15]
	v_mfma_f32_16x16x32_bf16 v[8:11], v[158:161], v[210:213], v[8:11]
	v_mfma_f32_16x16x32_bf16 v[60:63], v[154:157], v[186:189], v[60:63]
	v_mfma_f32_16x16x32_bf16 v[56:59], v[162:165], v[186:189], v[56:59]
	v_mfma_f32_16x16x32_bf16 v[44:47], v[154:157], v[198:201], v[44:47]
	v_mfma_f32_16x16x32_bf16 v[40:43], v[162:165], v[198:201], v[40:43]
	v_mfma_f32_16x16x32_bf16 v[28:31], v[154:157], v[206:209], v[28:31]
	v_mfma_f32_16x16x32_bf16 v[24:27], v[162:165], v[206:209], v[24:27]
	v_mfma_f32_16x16x32_bf16 v[12:15], v[154:157], v[214:217], v[12:15]
	v_mfma_f32_16x16x32_bf16 v[8:11], v[162:165], v[214:217], v[8:11]
	v_mfma_f32_16x16x32_bf16 v[52:55], v[166:169], v[182:185], v[52:55]
	v_mfma_f32_16x16x32_bf16 v[48:51], v[174:177], v[182:185], v[48:51]
	v_mfma_f32_16x16x32_bf16 v[36:39], v[166:169], v[190:193], v[36:39]
	v_mfma_f32_16x16x32_bf16 v[32:35], v[174:177], v[190:193], v[32:35]
	v_mfma_f32_16x16x32_bf16 v[20:23], v[166:169], v[202:205], v[20:23]
	v_mfma_f32_16x16x32_bf16 v[16:19], v[174:177], v[202:205], v[16:19]
	v_mfma_f32_16x16x32_bf16 v[4:7], v[166:169], v[210:213], v[4:7]
	v_mfma_f32_16x16x32_bf16 v[0:3], v[174:177], v[210:213], v[0:3]
	v_mfma_f32_16x16x32_bf16 v[52:55], v[170:173], v[186:189], v[52:55]
	v_mfma_f32_16x16x32_bf16 v[48:51], v[178:181], v[186:189], v[48:51]
	v_mfma_f32_16x16x32_bf16 v[36:39], v[170:173], v[198:201], v[36:39]
	v_mfma_f32_16x16x32_bf16 v[32:35], v[178:181], v[198:201], v[32:35]
	v_mfma_f32_16x16x32_bf16 v[20:23], v[170:173], v[206:209], v[20:23]
	v_mfma_f32_16x16x32_bf16 v[16:19], v[178:181], v[206:209], v[16:19]
	v_mfma_f32_16x16x32_bf16 v[4:7], v[170:173], v[214:217], v[4:7]
	v_mfma_f32_16x16x32_bf16 v[0:3], v[178:181], v[214:217], v[0:3]
	s_barrier
; #define PG8_STAGE(bufoff, gbase, voff) do { _Pragma("unroll") for (int _i = 0; _i < 2; ++_i) \
;         __builtin_amdgcn_global_load_lds((const unsigned*)((const char*)(gbase) + (voff)[_i]), (PG8_LAS unsigned*)(lds + (bufoff) + ldsw + _i * 8192), 16, 0, 0); } while (0)
; #define PG8_LDA(dst, b, h) do { _Pragma("unroll") for (int m = 0; m < 4; ++m) _Pragma("unroll") for (int k = 0; k < 2; ++k) dst[m][k] = *(const PG8_LAS bf16x8*)(lds + PG8_SA(b, h) + aoff + m * 2048 + k * 1024); } while (0)
; #define PG8_LDB(dst, b, h) do { _Pragma("unroll") for (int n = 0; n < 2; ++n) _Pragma("unroll") for (int k = 0; k < 2; ++k) dst[n][k] = *(const PG8_LAS bf16x8*)(lds + PG8_SB(b, h) + boff + n * 2048 + k * 1024); } while (0)
; #define PG8_MMA(ai, bj, At, Bt) do { __builtin_amdgcn_s_setprio(1); _Pragma("unroll") for (int m = 0; m < 4; ++m) _Pragma("unroll") for (int n = 0; n < 2; ++n) _Pragma("unroll") for (int k = 0; k < 2; ++k) \
;         acc[ai][bj][m][n] = __builtin_amdgcn_mfma_f32_16x16x32_bf16(Bt[n][k], At[m][k], acc[ai][bj][m][n], 0, 0, 0); __builtin_amdgcn_s_setprio(0); } while (0)
; #define PG8_WAIT_V(n) asm volatile("s_waitcnt vmcnt(" #n ")" ::: "memory")
; #define PG8_WAIT_L(n) asm volatile("s_waitcnt lgkmcnt(" #n ")" ::: "memory")
; #define PG8_BAR __builtin_amdgcn_s_barrier()
; #define PG8_SCHED __builtin_amdgcn_sched_barrier(0)
; template <class Epi, class Sched, bool ALIGN_EPI = false, bool SP2 = false>
; __device__ __forceinline__ void gemm_phase(PG8_LAS unsigned char* lds, const Gemm g, const Sched& S, const Epi& E) {
;     ...
;             PG8_LDB(B0, 1, 0); PG8_LDB(B1, 1, 1); PG8_SCHED; PG8_LDA(At, 1, 0); PG8_STAGE(PG8_SA(0, 1), a2 + hstep, voffA);
;             PG8_WAIT_V(8); PG8_WAIT_L(0); PG8_BAR; PG8_MMA(0, 0, At, B0); PG8_MMA(0, 1, At, B1); PG8_BAR; PG8_SCHED;
	s_add_i32 s51, 0, 0x18000
	s_add_i32 s52, 0, 0x1c000
	v_add_u32_e32 v162, s51, v149
	v_add_u32_e32 v178, s52, v149
	ds_read_b128 v[144:147], v162
	ds_read_b128 v[154:157], v162 offset:1024
	ds_read_b128 v[158:161], v162 offset:2048
	ds_read_b128 v[162:165], v162 offset:3072
	ds_read_b128 v[166:169], v178
	ds_read_b128 v[170:173], v178 offset:1024
	ds_read_b128 v[174:177], v178 offset:2048
	ds_read_b128 v[178:181], v178 offset:3072
	s_add_u32 s28, s28, 0x40000
	s_addc_u32 s29, s29, 0
	s_mov_b32 m0, s35
	v_lshl_add_u64 v[224:225], s[28:29], 0, v[128:129]
	ds_read_b128 v[182:185], v153 offset:32768
	ds_read_b128 v[186:189], v153 offset:33792
	ds_read_b128 v[190:193], v153 offset:34816
	ds_read_b128 v[198:201], v153 offset:35840
	ds_read_b128 v[202:205], v153 offset:36864
	ds_read_b128 v[206:209], v153 offset:37888
	ds_read_b128 v[210:213], v153 offset:38912
	ds_read_b128 v[214:217], v153 offset:39936
	global_load_lds_dwordx4 v[224:225], off
	v_lshl_add_u64 v[224:225], s[28:29], 0, v[132:133]
	s_mov_b32 m0, s36
	s_nop 0
	global_load_lds_dwordx4 v[224:225], off
	s_waitcnt vmcnt(8)
	s_waitcnt lgkmcnt(0)
	s_barrier
	s_waitcnt lgkmcnt(0)
	v_mfma_f32_16x16x32_bf16 v[124:127], v[144:147], v[182:185], v[124:127]
	v_mfma_f32_16x16x32_bf16 v[120:123], v[158:161], v[182:185], v[120:123]
	v_mfma_f32_16x16x32_bf16 v[108:111], v[144:147], v[190:193], v[108:111]
	v_mfma_f32_16x16x32_bf16 v[104:107], v[158:161], v[190:193], v[104:107]
	v_mfma_f32_16x16x32_bf16 v[92:95], v[144:147], v[202:205], v[92:95]
	v_mfma_f32_16x16x32_bf16 v[88:91], v[158:161], v[202:205], v[88:91]
	v_mfma_f32_16x16x32_bf16 v[76:79], v[144:147], v[210:213], v[76:79]
	v_mfma_f32_16x16x32_bf16 v[72:75], v[158:161], v[210:213], v[72:75]
	v_mfma_f32_16x16x32_bf16 v[124:127], v[154:157], v[186:189], v[124:127]
	v_mfma_f32_16x16x32_bf16 v[120:123], v[162:165], v[186:189], v[120:123]
	v_mfma_f32_16x16x32_bf16 v[108:111], v[154:157], v[198:201], v[108:111]
	v_mfma_f32_16x16x32_bf16 v[104:107], v[162:165], v[198:201], v[104:107]
	v_mfma_f32_16x16x32_bf16 v[92:95], v[154:157], v[206:209], v[92:95]
	v_mfma_f32_16x16x32_bf16 v[88:91], v[162:165], v[206:209], v[88:91]
	v_mfma_f32_16x16x32_bf16 v[76:79], v[154:157], v[214:217], v[76:79]
	v_mfma_f32_16x16x32_bf16 v[72:75], v[162:165], v[214:217], v[72:75]
	v_mfma_f32_16x16x32_bf16 v[116:119], v[166:169], v[182:185], v[116:119]
	v_mfma_f32_16x16x32_bf16 v[112:115], v[174:177], v[182:185], v[112:115]
	v_mfma_f32_16x16x32_bf16 v[100:103], v[166:169], v[190:193], v[100:103]
	v_mfma_f32_16x16x32_bf16 v[96:99], v[174:177], v[190:193], v[96:99]
	v_mfma_f32_16x16x32_bf16 v[84:87], v[166:169], v[202:205], v[84:87]
	v_mfma_f32_16x16x32_bf16 v[80:83], v[174:177], v[202:205], v[80:83]
	v_mfma_f32_16x16x32_bf16 v[68:71], v[166:169], v[210:213], v[68:71]
	v_mfma_f32_16x16x32_bf16 v[64:67], v[174:177], v[210:213], v[64:67]
	v_mfma_f32_16x16x32_bf16 v[116:119], v[170:173], v[186:189], v[116:119]
	v_mfma_f32_16x16x32_bf16 v[112:115], v[178:181], v[186:189], v[112:115]
	v_mfma_f32_16x16x32_bf16 v[100:103], v[170:173], v[198:201], v[100:103]
	v_mfma_f32_16x16x32_bf16 v[96:99], v[178:181], v[198:201], v[96:99]
	v_mfma_f32_16x16x32_bf16 v[84:87], v[170:173], v[206:209], v[84:87]
	v_mfma_f32_16x16x32_bf16 v[80:83], v[178:181], v[206:209], v[80:83]
	v_mfma_f32_16x16x32_bf16 v[68:71], v[170:173], v[214:217], v[68:71]
	v_mfma_f32_16x16x32_bf16 v[64:67], v[178:181], v[214:217], v[64:67]
	s_barrier
; #define PG8_STAGE(bufoff, gbase, voff) do { _Pragma("unroll") for (int _i = 0; _i < 2; ++_i) \
;         __builtin_amdgcn_global_load_lds((const unsigned*)((const char*)(gbase) + (voff)[_i]), (PG8_LAS unsigned*)(lds + (bufoff) + ldsw + _i * 8192), 16, 0, 0); } while (0)
; #define PG8_LDA(dst, b, h) do { _Pragma("unroll") for (int m = 0; m < 4; ++m) _Pragma("unroll") for (int k = 0; k < 2; ++k) dst[m][k] = *(const PG8_LAS bf16x8*)(lds + PG8_SA(b, h) + aoff + m * 2048 + k * 1024); } while (0)
; #define PG8_MMA(ai, bj, At, Bt) do { __builtin_amdgcn_s_setprio(1); _Pragma("unroll") for (int m = 0; m < 4; ++m) _Pragma("unroll") for (int n = 0; n < 2; ++n) _Pragma("unroll") for (int k = 0; k < 2; ++k) \
;         acc[ai][bj][m][n] = __builtin_amdgcn_mfma_f32_16x16x32_bf16(Bt[n][k], At[m][k], acc[ai][bj][m][n], 0, 0, 0); __builtin_amdgcn_s_setprio(0); } while (0)
; #define PG8_WAIT_V(n) asm volatile("s_waitcnt vmcnt(" #n ")" ::: "memory")
; #define PG8_WAIT_L(n) asm volatile("s_waitcnt lgkmcnt(" #n ")" ::: "memory")
; #define PG8_BAR __builtin_amdgcn_s_barrier()
; #define PG8_SCHED __builtin_amdgcn_sched_barrier(0)
; template <class Epi, class Sched, bool ALIGN_EPI = false, bool SP2 = false>
; __device__ __forceinline__ void gemm_phase(PG8_LAS unsigned char* lds, const Gemm g, const Sched& S, const Epi& E) {
;     ...
;         for (int t = 0; t < nt; t += 2) {
;     ...
;             PG8_LDA(At, 1, 1); PG8_STAGE(PG8_SB(1, 0), b3, voffB); PG8_STAGE(PG8_SB(1, 1), b3 + hstep, voffB); PG8_STAGE(PG8_SA(1, 0), a3, voffA);
;             PG8_WAIT_V(8); PG8_WAIT_L(0); PG8_BAR; PG8_MMA(1, 0, At, B0); PG8_MMA(1, 1, At, B1); PG8_BAR; PG8_SCHED;
	s_add_i32 s28, s51, s30
	v_lshl_add_u64 v[194:195], v[194:195], 0, s[10:11]
	s_mov_b32 m0, s28
	ds_read_b128 v[182:185], v153 offset:49152
	ds_read_b128 v[186:189], v153 offset:50176
	ds_read_b128 v[190:193], v153 offset:51200
	ds_read_b128 v[198:201], v153 offset:52224
	ds_read_b128 v[202:205], v153 offset:53248
	ds_read_b128 v[206:209], v153 offset:54272
	ds_read_b128 v[210:213], v153 offset:55296
	ds_read_b128 v[214:217], v153 offset:56320
	global_load_lds_dwordx4 v[194:195], off
	s_add_i32 m0, s28, 0x2000
	s_add_u32 s26, s26, 0x40080
	v_lshl_add_u64 v[194:195], v[218:219], 0, s[10:11]
	s_addc_u32 s27, s27, 0
	s_add_i32 s28, s52, s30
	global_load_lds_dwordx4 v[194:195], off
	v_lshl_add_u64 v[194:195], s[26:27], 0, v[130:131]
	s_mov_b32 m0, s28
	s_nop 0
	global_load_lds_dwordx4 v[194:195], off
	v_lshl_add_u64 v[194:195], s[26:27], 0, v[134:135]
	s_add_i32 m0, s28, 0x2000
	s_nop 0
	global_load_lds_dwordx4 v[194:195], off
	v_lshl_add_u64 v[194:195], v[220:221], 0, s[10:11]
	s_mov_b32 m0, s39
	s_nop 0
	global_load_lds_dwordx4 v[194:195], off
	v_lshl_add_u64 v[194:195], v[222:223], 0, s[10:11]
	s_mov_b32 m0, s40
	s_nop 0
	global_load_lds_dwordx4 v[194:195], off
	s_waitcnt vmcnt(8)
	s_waitcnt lgkmcnt(0)
	s_barrier
	s_waitcnt lgkmcnt(0)
	v_mfma_f32_16x16x32_bf16 v[60:63], v[144:147], v[182:185], v[60:63]
	v_mfma_f32_16x16x32_bf16 v[56:59], v[158:161], v[182:185], v[56:59]
	v_mfma_f32_16x16x32_bf16 v[44:47], v[144:147], v[190:193], v[44:47]
	v_mfma_f32_16x16x32_bf16 v[40:43], v[158:161], v[190:193], v[40:43]
	v_mfma_f32_16x16x32_bf16 v[28:31], v[144:147], v[202:205], v[28:31]
	v_mfma_f32_16x16x32_bf16 v[24:27], v[158:161], v[202:205], v[24:27]
	v_mfma_f32_16x16x32_bf16 v[12:15], v[144:147], v[210:213], v[12:15]
	v_mfma_f32_16x16x32_bf16 v[8:11], v[158:161], v[210:213], v[8:11]
	v_mfma_f32_16x16x32_bf16 v[60:63], v[154:157], v[186:189], v[60:63]
	v_mfma_f32_16x16x32_bf16 v[56:59], v[162:165], v[186:189], v[56:59]
	v_mfma_f32_16x16x32_bf16 v[44:47], v[154:157], v[198:201], v[44:47]
	v_mfma_f32_16x16x32_bf16 v[40:43], v[162:165], v[198:201], v[40:43]
	v_mfma_f32_16x16x32_bf16 v[28:31], v[154:157], v[206:209], v[28:31]
	v_mfma_f32_16x16x32_bf16 v[24:27], v[162:165], v[206:209], v[24:27]
	v_mfma_f32_16x16x32_bf16 v[12:15], v[154:157], v[214:217], v[12:15]
	v_mfma_f32_16x16x32_bf16 v[8:11], v[162:165], v[214:217], v[8:11]
	v_mfma_f32_16x16x32_bf16 v[52:55], v[166:169], v[182:185], v[52:55]
	v_mfma_f32_16x16x32_bf16 v[48:51], v[174:177], v[182:185], v[48:51]
	v_mfma_f32_16x16x32_bf16 v[36:39], v[166:169], v[190:193], v[36:39]
	v_mfma_f32_16x16x32_bf16 v[32:35], v[174:177], v[190:193], v[32:35]
	v_mfma_f32_16x16x32_bf16 v[20:23], v[166:169], v[202:205], v[20:23]
	v_mfma_f32_16x16x32_bf16 v[16:19], v[174:177], v[202:205], v[16:19]
	v_mfma_f32_16x16x32_bf16 v[4:7], v[166:169], v[210:213], v[4:7]
	v_mfma_f32_16x16x32_bf16 v[0:3], v[174:177], v[210:213], v[0:3]
	v_mfma_f32_16x16x32_bf16 v[52:55], v[170:173], v[186:189], v[52:55]
	v_mfma_f32_16x16x32_bf16 v[48:51], v[178:181], v[186:189], v[48:51]
	v_mfma_f32_16x16x32_bf16 v[36:39], v[170:173], v[198:201], v[36:39]
	v_mfma_f32_16x16x32_bf16 v[32:35], v[178:181], v[198:201], v[32:35]
	v_mfma_f32_16x16x32_bf16 v[20:23], v[170:173], v[206:209], v[20:23]
	v_mfma_f32_16x16x32_bf16 v[16:19], v[178:181], v[206:209], v[16:19]
	v_mfma_f32_16x16x32_bf16 v[4:7], v[170:173], v[214:217], v[4:7]
	v_mfma_f32_16x16x32_bf16 v[0:3], v[178:181], v[214:217], v[0:3]
	s_barrier
	s_add_i32 s50, s50, 2
	s_add_u32 s24, s24, 0x100
	s_addc_u32 s25, s25, 0
	s_add_u32 s48, s48, 0x100
	s_addc_u32 s49, s49, 0
	s_cmp_gt_u32 s50, 13
	s_cbranch_scc0 .LBB0_293
	s_setprio 0
	s_and_b64 vcc, exec, s[12:13]
	s_cbranch_vccz .LBB0_296
	s_barrier

; #define PG8_STAGE(bufoff, gbase, voff) do { _Pragma("unroll") for (int _i = 0; _i < 2; ++_i) \
;         __builtin_amdgcn_global_load_lds((const unsigned*)((const char*)(gbase) + (voff)[_i]), (PG8_LAS unsigned*)(lds + (bufoff) + ldsw + _i * 8192), 16, 0, 0); } while (0)
; #define PG8_LDA(dst, b, h) do { _Pragma("unroll") for (int m = 0; m < 4; ++m) _Pragma("unroll") for (int k = 0; k < 2; ++k) dst[m][k] = *(const PG8_LAS bf16x8*)(lds + PG8_SA(b, h) + aoff + m * 2048 + k * 1024); } while (0)
; #define PG8_LDB(dst, b, h) do { _Pragma("unroll") for (int n = 0; n < 2; ++n) _Pragma("unroll") for (int k = 0; k < 2; ++k) dst[n][k] = *(const PG8_LAS bf16x8*)(lds + PG8_SB(b, h) + boff + n * 2048 + k * 1024); } while (0)
; #define PG8_MMA(ai, bj, At, Bt) do { __builtin_amdgcn_s_setprio(1); _Pragma("unroll") for (int m = 0; m < 4; ++m) _Pragma("unroll") for (int n = 0; n < 2; ++n) _Pragma("unroll") for (int k = 0; k < 2; ++k) \
;         acc[ai][bj][m][n] = __builtin_amdgcn_mfma_f32_16x16x32_bf16(Bt[n][k], At[m][k], acc[ai][bj][m][n], 0, 0, 0); __builtin_amdgcn_s_setprio(0); } while (0)
; #define PG8_WAIT_V(n) asm volatile("s_waitcnt vmcnt(" #n ")" ::: "memory")
; #define PG8_WAIT_L(n) asm volatile("s_waitcnt lgkmcnt(" #n ")" ::: "memory")
; template <class Epi, class Sched, bool ALIGN_EPI = false, bool SP2 = false>
; __device__ __forceinline__ void gemm_phase(PG8_LAS unsigned char* lds, const Gemm g, const Sched& S, const Epi& E) {
;     ...
;             const char* a1 = cA + (size_t)(t + 1) * kstep;
;             const char* a2 = last ? nA : cA + (size_t)(t + 2) * kstep; const char* b2 = last ? nB : cB + (size_t)(t + 2) * kstep;
;             const char* a3 = a2 + kstep; const char* b3 = b2 + kstep;
;             if (last && has_next) S.a_ready(nxt);
;             if constexpr (SP2) {
;             PG8_LDB(B0, 0, 0); PG8_LDB(B1, 0, 1); PG8_SCHED; PG8_LDA(At, 0, 0); PG8_STAGE(PG8_SA(1, 1), a1 + hstep, voffA);
;             PG8_WAIT_V(8); PG8_WAIT_L(0); PG8_BAR; PG8_MMA(0, 0, At, B0); PG8_MMA(0, 1, At, B1); PG8_BAR; PG8_SCHED;
;     ...
; #pragma unroll
;         for (int a = 0; a < 2; ++a)
; #pragma unroll
;             for (int b = 0; b < 2; ++b)
; #pragma unroll
;                 for (int m = 0; m < 4; ++m)
; #pragma unroll
;                     for (int n = 0; n < 2; ++n) acc[a][b][m][n] = (f32x4){0.f, 0.f, 0.f, 0.f};
;         cur = nxt; cA = nA; cB = nB; ++ui;
.LBB0_369:
	s_add_u32 s22, s22, 0xb0080
	s_addc_u32 s23, s23, 0
	s_add_u32 s46, s24, 0x100
	v_mov_b32_e32 v0, 0
	s_addc_u32 s47, s25, 0
	s_mov_b32 s48, -2
	v_mov_b32_e32 v1, v0
	v_mov_b32_e32 v2, v0
	v_mov_b32_e32 v3, v0
	v_mov_b32_e32 v4, v0
	s_waitcnt lgkmcnt(0)
	v_mov_b32_e32 v5, v0
	v_mov_b32_e32 v6, v0
	v_mov_b32_e32 v7, v0
	v_mov_b32_e32 v16, v0
	v_mov_b32_e32 v17, v0
	v_mov_b32_e32 v18, v0
	v_mov_b32_e32 v19, v0
	v_mov_b32_e32 v20, v0
	v_mov_b32_e32 v21, v0
	v_mov_b32_e32 v22, v0
	v_mov_b32_e32 v23, v0
	v_mov_b32_e32 v32, v0
	v_mov_b32_e32 v33, v0
	v_mov_b32_e32 v34, v0
	v_mov_b32_e32 v35, v0
	v_mov_b32_e32 v36, v0
	v_mov_b32_e32 v37, v0
	v_mov_b32_e32 v38, v0
	v_mov_b32_e32 v39, v0
	v_mov_b32_e32 v48, v0
	v_mov_b32_e32 v49, v0
	v_mov_b32_e32 v50, v0
	v_mov_b32_e32 v51, v0
	v_mov_b32_e32 v52, v0
	v_mov_b32_e32 v53, v0
	v_mov_b32_e32 v54, v0
	v_mov_b32_e32 v55, v0
	v_mov_b32_e32 v8, v0
	v_mov_b32_e32 v9, v0
	v_mov_b32_e32 v10, v0
	v_mov_b32_e32 v11, v0
	v_mov_b32_e32 v12, v0
	v_mov_b32_e32 v13, v0
	v_mov_b32_e32 v14, v0
	v_mov_b32_e32 v15, v0
	v_mov_b32_e32 v24, v0
	v_mov_b32_e32 v25, v0
	v_mov_b32_e32 v26, v0
	v_mov_b32_e32 v27, v0
	v_mov_b32_e32 v28, v0
	v_mov_b32_e32 v29, v0
	v_mov_b32_e32 v30, v0
	v_mov_b32_e32 v31, v0
	v_mov_b32_e32 v40, v0
	v_mov_b32_e32 v41, v0
	v_mov_b32_e32 v42, v0
	v_mov_b32_e32 v43, v0
	v_mov_b32_e32 v44, v0
	v_mov_b32_e32 v45, v0
	v_mov_b32_e32 v46, v0
	v_mov_b32_e32 v47, v0
	v_mov_b32_e32 v56, v0
	v_mov_b32_e32 v57, v0
	v_mov_b32_e32 v58, v0
	v_mov_b32_e32 v59, v0
	v_mov_b32_e32 v60, v0
	v_mov_b32_e32 v61, v0
	v_mov_b32_e32 v62, v0
	v_mov_b32_e32 v63, v0
	v_mov_b32_e32 v64, v0
	v_mov_b32_e32 v65, v0
	v_mov_b32_e32 v66, v0
	v_mov_b32_e32 v67, v0
	v_mov_b32_e32 v68, v0
	v_mov_b32_e32 v69, v0
	v_mov_b32_e32 v70, v0
	v_mov_b32_e32 v71, v0
	v_mov_b32_e32 v80, v0
	v_mov_b32_e32 v81, v0
	v_mov_b32_e32 v82, v0
	v_mov_b32_e32 v83, v0
	v_mov_b32_e32 v84, v0
	v_mov_b32_e32 v85, v0
	v_mov_b32_e32 v86, v0
	v_mov_b32_e32 v87, v0
	v_mov_b32_e32 v96, v0
	v_mov_b32_e32 v97, v0
	v_mov_b32_e32 v98, v0
	v_mov_b32_e32 v99, v0
	v_mov_b32_e32 v100, v0
	v_mov_b32_e32 v101, v0
	v_mov_b32_e32 v102, v0
	v_mov_b32_e32 v103, v0
	v_mov_b32_e32 v112, v0
	v_mov_b32_e32 v113, v0
	v_mov_b32_e32 v114, v0
	v_mov_b32_e32 v115, v0
	v_mov_b32_e32 v116, v0
	v_mov_b32_e32 v117, v0
	v_mov_b32_e32 v118, v0
	v_mov_b32_e32 v119, v0
	v_mov_b32_e32 v72, v0
	v_mov_b32_e32 v73, v0
	v_mov_b32_e32 v74, v0
	v_mov_b32_e32 v75, v0
	v_mov_b32_e32 v76, v0
	v_mov_b32_e32 v77, v0
	v_mov_b32_e32 v78, v0
	v_mov_b32_e32 v79, v0
	v_mov_b32_e32 v88, v0
	v_mov_b32_e32 v89, v0
	v_mov_b32_e32 v90, v0
	v_mov_b32_e32 v91, v0
	v_mov_b32_e32 v92, v0
	v_mov_b32_e32 v93, v0
	v_mov_b32_e32 v94, v0
	v_mov_b32_e32 v95, v0
	v_mov_b32_e32 v104, v0
	v_mov_b32_e32 v105, v0
	v_mov_b32_e32 v106, v0
	v_mov_b32_e32 v107, v0
	v_mov_b32_e32 v108, v0
	v_mov_b32_e32 v109, v0
	v_mov_b32_e32 v110, v0
	v_mov_b32_e32 v111, v0
	v_mov_b32_e32 v120, v0
	v_mov_b32_e32 v121, v0
	v_mov_b32_e32 v122, v0
	v_mov_b32_e32 v123, v0
	v_mov_b32_e32 v124, v0
	v_mov_b32_e32 v125, v0
	v_mov_b32_e32 v126, v0
	v_mov_b32_e32 v127, v0
	v_readfirstlane_b32 s98, v197
	s_nop 3
	s_cmpk_gt_u32 s98, 0xff
	s_cbranch_scc0 .Lkp_7
	s_setprio 1
.Lkp_7:
.LBB0_370:
	ds_read_b128 v[144:147], v151
	ds_read_b128 v[156:159], v151 offset:1024
	ds_read_b128 v[160:163], v151 offset:2048
	ds_read_b128 v[164:167], v151 offset:3072
	ds_read_b128 v[168:171], v152
	ds_read_b128 v[172:175], v152 offset:1024
	ds_read_b128 v[176:179], v152 offset:2048
	ds_read_b128 v[180:183], v152 offset:3072
	s_add_u32 s24, s22, 0xfff50080
	s_addc_u32 s25, s23, -1
	s_cmp_eq_u32 s48, 40
	s_cselect_b32 s27, s5, s25
	s_cselect_b32 s26, s4, s24
	s_cselect_b32 s25, s21, s47
	s_cselect_b32 s24, s20, s46
	v_lshl_add_u64 v[218:219], s[22:23], 0, v[136:137]
	s_add_i32 m0, s29, 0xc000
	ds_read_b128 v[184:187], v153
	ds_read_b128 v[188:191], v153 offset:1024
	ds_read_b128 v[192:195], v153 offset:2048
	ds_read_b128 v[198:201], v153 offset:3072
	ds_read_b128 v[202:205], v153 offset:4096
	ds_read_b128 v[206:209], v153 offset:5120
	ds_read_b128 v[210:213], v153 offset:6144
	ds_read_b128 v[214:217], v153 offset:7168
	global_load_lds_dwordx4 v[218:219], off
	v_lshl_add_u64 v[218:219], s[22:23], 0, v[138:139]
	s_add_i32 m0, s29, 0xe000
	s_nop 0
	global_load_lds_dwordx4 v[218:219], off
	s_waitcnt vmcnt(8)
	s_waitcnt lgkmcnt(0)
	s_barrier
	s_waitcnt lgkmcnt(0)
	v_mfma_f32_16x16x32_bf16 v[124:127], v[144:147], v[184:187], v[124:127]
	v_mfma_f32_16x16x32_bf16 v[120:123], v[160:163], v[184:187], v[120:123]
	v_mfma_f32_16x16x32_bf16 v[108:111], v[144:147], v[192:195], v[108:111]
	v_mfma_f32_16x16x32_bf16 v[104:107], v[160:163], v[192:195], v[104:107]
	v_mfma_f32_16x16x32_bf16 v[92:95], v[144:147], v[202:205], v[92:95]
	v_mfma_f32_16x16x32_bf16 v[88:91], v[160:163], v[202:205], v[88:91]
	v_mfma_f32_16x16x32_bf16 v[76:79], v[144:147], v[210:213], v[76:79]
	v_mfma_f32_16x16x32_bf16 v[72:75], v[160:163], v[210:213], v[72:75]
	v_mfma_f32_16x16x32_bf16 v[124:127], v[156:159], v[188:191], v[124:127]
	v_mfma_f32_16x16x32_bf16 v[120:123], v[164:167], v[188:191], v[120:123]
	v_mfma_f32_16x16x32_bf16 v[108:111], v[156:159], v[198:201], v[108:111]
	v_mfma_f32_16x16x32_bf16 v[104:107], v[164:167], v[198:201], v[104:107]
	v_mfma_f32_16x16x32_bf16 v[92:95], v[156:159], v[206:209], v[92:95]
	v_mfma_f32_16x16x32_bf16 v[88:91], v[164:167], v[206:209], v[88:91]
	v_mfma_f32_16x16x32_bf16 v[76:79], v[156:159], v[214:217], v[76:79]
	v_mfma_f32_16x16x32_bf16 v[72:75], v[164:167], v[214:217], v[72:75]
	v_mfma_f32_16x16x32_bf16 v[116:119], v[168:171], v[184:187], v[116:119]
	v_mfma_f32_16x16x32_bf16 v[112:115], v[176:179], v[184:187], v[112:115]
	v_mfma_f32_16x16x32_bf16 v[100:103], v[168:171], v[192:195], v[100:103]
	v_mfma_f32_16x16x32_bf16 v[96:99], v[176:179], v[192:195], v[96:99]
	v_mfma_f32_16x16x32_bf16 v[84:87], v[168:171], v[202:205], v[84:87]
	v_mfma_f32_16x16x32_bf16 v[80:83], v[176:179], v[202:205], v[80:83]
	v_mfma_f32_16x16x32_bf16 v[68:71], v[168:171], v[210:213], v[68:71]
	v_mfma_f32_16x16x32_bf16 v[64:67], v[176:179], v[210:213], v[64:67]
	v_mfma_f32_16x16x32_bf16 v[116:119], v[172:175], v[188:191], v[116:119]
	v_mfma_f32_16x16x32_bf16 v[112:115], v[180:183], v[188:191], v[112:115]
	v_mfma_f32_16x16x32_bf16 v[100:103], v[172:175], v[198:201], v[100:103]
	v_mfma_f32_16x16x32_bf16 v[96:99], v[180:183], v[198:201], v[96:99]
	v_mfma_f32_16x16x32_bf16 v[84:87], v[172:175], v[206:209], v[84:87]
	v_mfma_f32_16x16x32_bf16 v[80:83], v[180:183], v[206:209], v[80:83]
	v_mfma_f32_16x16x32_bf16 v[68:71], v[172:175], v[214:217], v[68:71]
	v_mfma_f32_16x16x32_bf16 v[64:67], v[180:183], v[214:217], v[64:67]
	s_barrier
; #define PG8_STAGE(bufoff, gbase, voff) do { _Pragma("unroll") for (int _i = 0; _i < 2; ++_i) \
;         __builtin_amdgcn_global_load_lds((const unsigned*)((const char*)(gbase) + (voff)[_i]), (PG8_LAS unsigned*)(lds + (bufoff) + ldsw + _i * 8192), 16, 0, 0); } while (0)
; #define PG8_LDA(dst, b, h) do { _Pragma("unroll") for (int m = 0; m < 4; ++m) _Pragma("unroll") for (int k = 0; k < 2; ++k) dst[m][k] = *(const PG8_LAS bf16x8*)(lds + PG8_SA(b, h) + aoff + m * 2048 + k * 1024); } while (0)
; #define PG8_LDB(dst, b, h) do { _Pragma("unroll") for (int n = 0; n < 2; ++n) _Pragma("unroll") for (int k = 0; k < 2; ++k) dst[n][k] = *(const PG8_LAS bf16x8*)(lds + PG8_SB(b, h) + boff + n * 2048 + k * 1024); } while (0)
; #define PG8_MMA(ai, bj, At, Bt) do { __builtin_amdgcn_s_setprio(1); _Pragma("unroll") for (int m = 0; m < 4; ++m) _Pragma("unroll") for (int n = 0; n < 2; ++n) _Pragma("unroll") for (int k = 0; k < 2; ++k) \
;         acc[ai][bj][m][n] = __builtin_amdgcn_mfma_f32_16x16x32_bf16(Bt[n][k], At[m][k], acc[ai][bj][m][n], 0, 0, 0); __builtin_amdgcn_s_setprio(0); } while (0)
; #define PG8_WAIT_V(n) asm volatile("s_waitcnt vmcnt(" #n ")" ::: "memory")
; #define PG8_WAIT_L(n) asm volatile("s_waitcnt lgkmcnt(" #n ")" ::: "memory")
; #define PG8_BAR __builtin_amdgcn_s_barrier()
; #define PG8_SCHED __builtin_amdgcn_sched_barrier(0)
; template <class Epi, class Sched, bool ALIGN_EPI = false, bool SP2 = false>
; __device__ __forceinline__ void gemm_phase(PG8_LAS unsigned char* lds, const Gemm g, const Sched& S, const Epi& E) {
;     ...
;             PG8_LDA(At, 0, 1); PG8_STAGE(PG8_SB(0, 0), b2, voffB); PG8_STAGE(PG8_SB(0, 1), b2 + hstep, voffB); PG8_STAGE(PG8_SA(0, 0), a2, voffA);
;             PG8_WAIT_V(8); PG8_WAIT_L(0); PG8_BAR; PG8_MMA(1, 0, At, B0); PG8_MMA(1, 1, At, B1); PG8_BAR; PG8_SCHED;
;             PG8_LDB(B0, 1, 0); PG8_LDB(B1, 1, 1); PG8_SCHED; PG8_LDA(At, 1, 0); PG8_STAGE(PG8_SA(0, 1), a2 + hstep, voffA);
;             PG8_WAIT_V(8); PG8_WAIT_L(0); PG8_BAR; PG8_MMA(0, 0, At, B0); PG8_MMA(0, 1, At, B1); PG8_BAR; PG8_SCHED;
	s_add_i32 s49, s40, s28
	v_lshl_add_u64 v[218:219], s[24:25], 0, v[130:131]
	s_mov_b32 m0, s49
	ds_read_b128 v[184:187], v153 offset:16384
	ds_read_b128 v[188:191], v153 offset:17408
	ds_read_b128 v[192:195], v153 offset:18432
	ds_read_b128 v[198:201], v153 offset:19456
	ds_read_b128 v[202:205], v153 offset:20480
	ds_read_b128 v[206:209], v153 offset:21504
	ds_read_b128 v[210:213], v153 offset:22528
	ds_read_b128 v[214:217], v153 offset:23552
	global_load_lds_dwordx4 v[218:219], off
	s_add_i32 m0, s49, 0x2000
	s_add_u32 s50, s24, 0xb0000
	v_lshl_add_u64 v[220:221], s[24:25], 0, v[134:135]
	s_addc_u32 s51, s25, 0
	s_add_i32 s49, s41, s28
	global_load_lds_dwordx4 v[220:221], off
	v_lshl_add_u64 v[222:223], s[50:51], 0, v[130:131]
	s_mov_b32 m0, s49
	v_lshl_add_u64 v[224:225], s[26:27], 0, v[132:133]
	global_load_lds_dwordx4 v[222:223], off
	v_lshl_add_u64 v[222:223], s[50:51], 0, v[134:135]
	s_add_i32 m0, s49, 0x2000
	s_nop 0
	global_load_lds_dwordx4 v[222:223], off
	v_lshl_add_u64 v[222:223], s[26:27], 0, v[128:129]
	s_mov_b32 m0, s29
	s_nop 0
	global_load_lds_dwordx4 v[222:223], off
	s_mov_b32 m0, s30
	s_nop 0
	global_load_lds_dwordx4 v[224:225], off
	s_waitcnt vmcnt(8)
	s_waitcnt lgkmcnt(0)
	s_barrier
	s_waitcnt lgkmcnt(0)
	v_mfma_f32_16x16x32_bf16 v[60:63], v[144:147], v[184:187], v[60:63]
	v_mfma_f32_16x16x32_bf16 v[56:59], v[160:163], v[184:187], v[56:59]
	v_mfma_f32_16x16x32_bf16 v[44:47], v[144:147], v[192:195], v[44:47]
	v_mfma_f32_16x16x32_bf16 v[40:43], v[160:163], v[192:195], v[40:43]
	v_mfma_f32_16x16x32_bf16 v[28:31], v[144:147], v[202:205], v[28:31]
	v_mfma_f32_16x16x32_bf16 v[24:27], v[160:163], v[202:205], v[24:27]
	v_mfma_f32_16x16x32_bf16 v[12:15], v[144:147], v[210:213], v[12:15]
	v_mfma_f32_16x16x32_bf16 v[8:11], v[160:163], v[210:213], v[8:11]
	v_mfma_f32_16x16x32_bf16 v[60:63], v[156:159], v[188:191], v[60:63]
	v_mfma_f32_16x16x32_bf16 v[56:59], v[164:167], v[188:191], v[56:59]
	v_mfma_f32_16x16x32_bf16 v[44:47], v[156:159], v[198:201], v[44:47]
	v_mfma_f32_16x16x32_bf16 v[40:43], v[164:167], v[198:201], v[40:43]
	v_mfma_f32_16x16x32_bf16 v[28:31], v[156:159], v[206:209], v[28:31]
	v_mfma_f32_16x16x32_bf16 v[24:27], v[164:167], v[206:209], v[24:27]
	v_mfma_f32_16x16x32_bf16 v[12:15], v[156:159], v[214:217], v[12:15]
	v_mfma_f32_16x16x32_bf16 v[8:11], v[164:167], v[214:217], v[8:11]
	v_mfma_f32_16x16x32_bf16 v[52:55], v[168:171], v[184:187], v[52:55]
	v_mfma_f32_16x16x32_bf16 v[48:51], v[176:179], v[184:187], v[48:51]
	v_mfma_f32_16x16x32_bf16 v[36:39], v[168:171], v[192:195], v[36:39]
	v_mfma_f32_16x16x32_bf16 v[32:35], v[176:179], v[192:195], v[32:35]
	v_mfma_f32_16x16x32_bf16 v[20:23], v[168:171], v[202:205], v[20:23]
	v_mfma_f32_16x16x32_bf16 v[16:19], v[176:179], v[202:205], v[16:19]
	v_mfma_f32_16x16x32_bf16 v[4:7], v[168:171], v[210:213], v[4:7]
	v_mfma_f32_16x16x32_bf16 v[0:3], v[176:179], v[210:213], v[0:3]
	v_mfma_f32_16x16x32_bf16 v[52:55], v[172:175], v[188:191], v[52:55]
	v_mfma_f32_16x16x32_bf16 v[48:51], v[180:183], v[188:191], v[48:51]
	v_mfma_f32_16x16x32_bf16 v[36:39], v[172:175], v[198:201], v[36:39]
	v_mfma_f32_16x16x32_bf16 v[32:35], v[180:183], v[198:201], v[32:35]
	v_mfma_f32_16x16x32_bf16 v[20:23], v[172:175], v[206:209], v[20:23]
	v_mfma_f32_16x16x32_bf16 v[16:19], v[180:183], v[206:209], v[16:19]
	v_mfma_f32_16x16x32_bf16 v[4:7], v[172:175], v[214:217], v[4:7]
	v_mfma_f32_16x16x32_bf16 v[0:3], v[180:183], v[214:217], v[0:3]
	s_barrier
	s_add_i32 s49, 0, 0x18000
	v_add_u32_e32 v155, s49, v149
	s_add_i32 s50, 0, 0x1c000
	ds_read_b128 v[144:147], v155
	ds_read_b128 v[156:159], v155 offset:1024
	ds_read_b128 v[160:163], v155 offset:2048
	ds_read_b128 v[164:167], v155 offset:3072
	v_add_u32_e32 v155, s50, v149
	ds_read_b128 v[168:171], v155
	ds_read_b128 v[172:175], v155 offset:1024
	ds_read_b128 v[176:179], v155 offset:2048
	ds_read_b128 v[180:183], v155 offset:3072
	s_add_u32 s26, s26, 0xb0000
	s_addc_u32 s27, s27, 0
	s_mov_b32 m0, s31
	v_lshl_add_u64 v[226:227], s[26:27], 0, v[128:129]
	ds_read_b128 v[184:187], v153 offset:32768
	ds_read_b128 v[188:191], v153 offset:33792
	ds_read_b128 v[192:195], v153 offset:34816
	ds_read_b128 v[198:201], v153 offset:35840
	ds_read_b128 v[202:205], v153 offset:36864
	ds_read_b128 v[206:209], v153 offset:37888
	ds_read_b128 v[210:213], v153 offset:38912
	ds_read_b128 v[214:217], v153 offset:39936
	global_load_lds_dwordx4 v[226:227], off
	v_lshl_add_u64 v[226:227], s[26:27], 0, v[132:133]
	s_mov_b32 m0, s33
	s_nop 0
	global_load_lds_dwordx4 v[226:227], off
	s_waitcnt vmcnt(8)
	s_waitcnt lgkmcnt(0)
	s_barrier
; #define PG8_STAGE(bufoff, gbase, voff) do { _Pragma("unroll") for (int _i = 0; _i < 2; ++_i) \
;         __builtin_amdgcn_global_load_lds((const unsigned*)((const char*)(gbase) + (voff)[_i]), (PG8_LAS unsigned*)(lds + (bufoff) + ldsw + _i * 8192), 16, 0, 0); } while (0)
; #define PG8_LDA(dst, b, h) do { _Pragma("unroll") for (int m = 0; m < 4; ++m) _Pragma("unroll") for (int k = 0; k < 2; ++k) dst[m][k] = *(const PG8_LAS bf16x8*)(lds + PG8_SA(b, h) + aoff + m * 2048 + k * 1024); } while (0)
; #define PG8_LDB(dst, b, h) do { _Pragma("unroll") for (int n = 0; n < 2; ++n) _Pragma("unroll") for (int k = 0; k < 2; ++k) dst[n][k] = *(const PG8_LAS bf16x8*)(lds + PG8_SB(b, h) + boff + n * 2048 + k * 1024); } while (0)
; #define PG8_MMA(ai, bj, At, Bt) do { __builtin_amdgcn_s_setprio(1); _Pragma("unroll") for (int m = 0; m < 4; ++m) _Pragma("unroll") for (int n = 0; n < 2; ++n) _Pragma("unroll") for (int k = 0; k < 2; ++k) \
;         acc[ai][bj][m][n] = __builtin_amdgcn_mfma_f32_16x16x32_bf16(Bt[n][k], At[m][k], acc[ai][bj][m][n], 0, 0, 0); __builtin_amdgcn_s_setprio(0); } while (0)
; #define PG8_WAIT_V(n) asm volatile("s_waitcnt vmcnt(" #n ")" ::: "memory")
; #define PG8_WAIT_L(n) asm volatile("s_waitcnt lgkmcnt(" #n ")" ::: "memory")
; #define PG8_BAR __builtin_amdgcn_s_barrier()
; #define PG8_SCHED __builtin_amdgcn_sched_barrier(0)
; template <class Epi, class Sched, bool ALIGN_EPI = false, bool SP2 = false>
; __device__ __forceinline__ void gemm_phase(PG8_LAS unsigned char* lds, const Gemm g, const Sched& S, const Epi& E) {
;     ...
;         for (int t = 0; t < nt; t += 2) {
;     ...
;             PG8_LDB(B0, 1, 0); PG8_LDB(B1, 1, 1); PG8_SCHED; PG8_LDA(At, 1, 0); PG8_STAGE(PG8_SA(0, 1), a2 + hstep, voffA);
;             PG8_WAIT_V(8); PG8_WAIT_L(0); PG8_BAR; PG8_MMA(0, 0, At, B0); PG8_MMA(0, 1, At, B1); PG8_BAR; PG8_SCHED;
;             PG8_LDA(At, 1, 1); PG8_STAGE(PG8_SB(1, 0), b3, voffB); PG8_STAGE(PG8_SB(1, 1), b3 + hstep, voffB); PG8_STAGE(PG8_SA(1, 0), a3, voffA);
;             PG8_WAIT_V(8); PG8_WAIT_L(0); PG8_BAR; PG8_MMA(1, 0, At, B0); PG8_MMA(1, 1, At, B1); PG8_BAR; PG8_SCHED;
;     ...
;         if constexpr (ALIGN_EPI) { if (wr == 0) PG8_BAR; }
	s_waitcnt lgkmcnt(0)
	v_mfma_f32_16x16x32_bf16 v[124:127], v[144:147], v[184:187], v[124:127]
	v_mfma_f32_16x16x32_bf16 v[120:123], v[160:163], v[184:187], v[120:123]
	v_mfma_f32_16x16x32_bf16 v[108:111], v[144:147], v[192:195], v[108:111]
	v_mfma_f32_16x16x32_bf16 v[104:107], v[160:163], v[192:195], v[104:107]
	v_mfma_f32_16x16x32_bf16 v[92:95], v[144:147], v[202:205], v[92:95]
	v_mfma_f32_16x16x32_bf16 v[88:91], v[160:163], v[202:205], v[88:91]
	v_mfma_f32_16x16x32_bf16 v[76:79], v[144:147], v[210:213], v[76:79]
	v_mfma_f32_16x16x32_bf16 v[72:75], v[160:163], v[210:213], v[72:75]
	v_mfma_f32_16x16x32_bf16 v[124:127], v[156:159], v[188:191], v[124:127]
	v_mfma_f32_16x16x32_bf16 v[120:123], v[164:167], v[188:191], v[120:123]
	v_mfma_f32_16x16x32_bf16 v[108:111], v[156:159], v[198:201], v[108:111]
	v_mfma_f32_16x16x32_bf16 v[104:107], v[164:167], v[198:201], v[104:107]
	v_mfma_f32_16x16x32_bf16 v[92:95], v[156:159], v[206:209], v[92:95]
	v_mfma_f32_16x16x32_bf16 v[88:91], v[164:167], v[206:209], v[88:91]
	v_mfma_f32_16x16x32_bf16 v[76:79], v[156:159], v[214:217], v[76:79]
	v_mfma_f32_16x16x32_bf16 v[72:75], v[164:167], v[214:217], v[72:75]
	v_mfma_f32_16x16x32_bf16 v[116:119], v[168:171], v[184:187], v[116:119]
	v_mfma_f32_16x16x32_bf16 v[112:115], v[176:179], v[184:187], v[112:115]
	v_mfma_f32_16x16x32_bf16 v[100:103], v[168:171], v[192:195], v[100:103]
	v_mfma_f32_16x16x32_bf16 v[96:99], v[176:179], v[192:195], v[96:99]
	v_mfma_f32_16x16x32_bf16 v[84:87], v[168:171], v[202:205], v[84:87]
	v_mfma_f32_16x16x32_bf16 v[80:83], v[176:179], v[202:205], v[80:83]
	v_mfma_f32_16x16x32_bf16 v[68:71], v[168:171], v[210:213], v[68:71]
	v_mfma_f32_16x16x32_bf16 v[64:67], v[176:179], v[210:213], v[64:67]
	v_mfma_f32_16x16x32_bf16 v[116:119], v[172:175], v[188:191], v[116:119]
	v_mfma_f32_16x16x32_bf16 v[112:115], v[180:183], v[188:191], v[112:115]
	v_mfma_f32_16x16x32_bf16 v[100:103], v[172:175], v[198:201], v[100:103]
	v_mfma_f32_16x16x32_bf16 v[96:99], v[180:183], v[198:201], v[96:99]
	v_mfma_f32_16x16x32_bf16 v[84:87], v[172:175], v[206:209], v[84:87]
	v_mfma_f32_16x16x32_bf16 v[80:83], v[180:183], v[206:209], v[80:83]
	v_mfma_f32_16x16x32_bf16 v[68:71], v[172:175], v[214:217], v[68:71]
	v_mfma_f32_16x16x32_bf16 v[64:67], v[180:183], v[214:217], v[64:67]
	s_barrier
	s_add_i32 s26, s49, s28
	v_lshl_add_u64 v[218:219], v[218:219], 0, s[16:17]
	s_mov_b32 m0, s26
	ds_read_b128 v[184:187], v153 offset:49152
	ds_read_b128 v[188:191], v153 offset:50176
	ds_read_b128 v[192:195], v153 offset:51200
	ds_read_b128 v[198:201], v153 offset:52224
	ds_read_b128 v[202:205], v153 offset:53248
	ds_read_b128 v[206:209], v153 offset:54272
	ds_read_b128 v[210:213], v153 offset:55296
	ds_read_b128 v[214:217], v153 offset:56320
	global_load_lds_dwordx4 v[218:219], off
	s_add_i32 m0, s26, 0x2000
	s_add_u32 s24, s24, 0xb0080
	v_lshl_add_u64 v[218:219], v[220:221], 0, s[16:17]
	s_addc_u32 s25, s25, 0
	s_add_i32 s26, s50, s28
	global_load_lds_dwordx4 v[218:219], off
	v_lshl_add_u64 v[218:219], s[24:25], 0, v[130:131]
	s_mov_b32 m0, s26
	s_nop 0
	global_load_lds_dwordx4 v[218:219], off
	v_lshl_add_u64 v[218:219], s[24:25], 0, v[134:135]
	s_add_i32 m0, s26, 0x2000
	s_nop 0
	global_load_lds_dwordx4 v[218:219], off
	v_lshl_add_u64 v[218:219], v[222:223], 0, s[16:17]
	s_mov_b32 m0, s37
	s_nop 0
	global_load_lds_dwordx4 v[218:219], off
	v_lshl_add_u64 v[218:219], v[224:225], 0, s[16:17]
	s_mov_b32 m0, s38
	s_nop 0
	global_load_lds_dwordx4 v[218:219], off
	s_waitcnt vmcnt(8)
	s_waitcnt lgkmcnt(0)
	s_barrier
	s_waitcnt lgkmcnt(0)
	v_mfma_f32_16x16x32_bf16 v[60:63], v[144:147], v[184:187], v[60:63]
	v_mfma_f32_16x16x32_bf16 v[56:59], v[160:163], v[184:187], v[56:59]
	v_mfma_f32_16x16x32_bf16 v[44:47], v[144:147], v[192:195], v[44:47]
	v_mfma_f32_16x16x32_bf16 v[40:43], v[160:163], v[192:195], v[40:43]
	v_mfma_f32_16x16x32_bf16 v[28:31], v[144:147], v[202:205], v[28:31]
	v_mfma_f32_16x16x32_bf16 v[24:27], v[160:163], v[202:205], v[24:27]
	v_mfma_f32_16x16x32_bf16 v[12:15], v[144:147], v[210:213], v[12:15]
	v_mfma_f32_16x16x32_bf16 v[8:11], v[160:163], v[210:213], v[8:11]
	v_mfma_f32_16x16x32_bf16 v[60:63], v[156:159], v[188:191], v[60:63]
	v_mfma_f32_16x16x32_bf16 v[56:59], v[164:167], v[188:191], v[56:59]
	v_mfma_f32_16x16x32_bf16 v[44:47], v[156:159], v[198:201], v[44:47]
	v_mfma_f32_16x16x32_bf16 v[40:43], v[164:167], v[198:201], v[40:43]
	v_mfma_f32_16x16x32_bf16 v[28:31], v[156:159], v[206:209], v[28:31]
	v_mfma_f32_16x16x32_bf16 v[24:27], v[164:167], v[206:209], v[24:27]
	v_mfma_f32_16x16x32_bf16 v[12:15], v[156:159], v[214:217], v[12:15]
	v_mfma_f32_16x16x32_bf16 v[8:11], v[164:167], v[214:217], v[8:11]
	v_mfma_f32_16x16x32_bf16 v[52:55], v[168:171], v[184:187], v[52:55]
	v_mfma_f32_16x16x32_bf16 v[48:51], v[176:179], v[184:187], v[48:51]
	v_mfma_f32_16x16x32_bf16 v[36:39], v[168:171], v[192:195], v[36:39]
	v_mfma_f32_16x16x32_bf16 v[32:35], v[176:179], v[192:195], v[32:35]
	v_mfma_f32_16x16x32_bf16 v[20:23], v[168:171], v[202:205], v[20:23]
	v_mfma_f32_16x16x32_bf16 v[16:19], v[176:179], v[202:205], v[16:19]
	v_mfma_f32_16x16x32_bf16 v[4:7], v[168:171], v[210:213], v[4:7]
	v_mfma_f32_16x16x32_bf16 v[0:3], v[176:179], v[210:213], v[0:3]
	v_mfma_f32_16x16x32_bf16 v[52:55], v[172:175], v[188:191], v[52:55]
	v_mfma_f32_16x16x32_bf16 v[48:51], v[180:183], v[188:191], v[48:51]
	v_mfma_f32_16x16x32_bf16 v[36:39], v[172:175], v[198:201], v[36:39]
	v_mfma_f32_16x16x32_bf16 v[32:35], v[180:183], v[198:201], v[32:35]
	v_mfma_f32_16x16x32_bf16 v[20:23], v[172:175], v[206:209], v[20:23]
	v_mfma_f32_16x16x32_bf16 v[16:19], v[180:183], v[206:209], v[16:19]
	v_mfma_f32_16x16x32_bf16 v[4:7], v[172:175], v[214:217], v[4:7]
	v_mfma_f32_16x16x32_bf16 v[0:3], v[180:183], v[214:217], v[0:3]
	s_barrier
	s_add_i32 s48, s48, 2
	s_add_u32 s22, s22, 0x100
	s_addc_u32 s23, s23, 0
	s_add_u32 s46, s46, 0x100
	s_addc_u32 s47, s47, 0
	s_cmp_gt_u32 s48, 41
	s_cbranch_scc0 .LBB0_370
	s_setprio 0
	s_and_b64 vcc, exec, s[18:19]
	s_cbranch_vccz .LBB0_373
	s_barrier

; #define PG8_STAGE(bufoff, gbase, voff) do { _Pragma("unroll") for (int _i = 0; _i < 2; ++_i) \
;         __builtin_amdgcn_global_load_lds((const unsigned*)((const char*)(gbase) + (voff)[_i]), (PG8_LAS unsigned*)(lds + (bufoff) + ldsw + _i * 8192), 16, 0, 0); } while (0)
; #define PG8_LDA(dst, b, h) do { _Pragma("unroll") for (int m = 0; m < 4; ++m) _Pragma("unroll") for (int k = 0; k < 2; ++k) dst[m][k] = *(const PG8_LAS bf16x8*)(lds + PG8_SA(b, h) + aoff + m * 2048 + k * 1024); } while (0)
; #define PG8_LDB(dst, b, h) do { _Pragma("unroll") for (int n = 0; n < 2; ++n) _Pragma("unroll") for (int k = 0; k < 2; ++k) dst[n][k] = *(const PG8_LAS bf16x8*)(lds + PG8_SB(b, h) + boff + n * 2048 + k * 1024); } while (0)
; #define PG8_SCHED __builtin_amdgcn_sched_barrier(0)
; template <class Epi, class Sched, bool ALIGN_EPI = false, bool SP2 = false>
; __device__ __forceinline__ void gemm_phase(PG8_LAS unsigned char* lds, const Gemm g, const Sched& S, const Epi& E) {
;     ...
;         const bool has_next = S.next(ui + 1, nxt);
;         const char* nA = has_next ? (const char*)g.A + (size_t)nxt.pm * tstep : cA; const char* nB = has_next ? (const char*)g.Bt + (size_t)nxt.pn * tstep : cB;
;         for (int t = 0; t < nt; t += 2) {
;             const bool last = (t == nt - 2);
;             const char* a1 = cA + (size_t)(t + 1) * kstep;
;             const char* a2 = last ? nA : cA + (size_t)(t + 2) * kstep; const char* b2 = last ? nB : cB + (size_t)(t + 2) * kstep;
;             const char* a3 = a2 + kstep; const char* b3 = b2 + kstep;
;             if (last && has_next) S.a_ready(nxt);
;             if constexpr (SP2) {
;             PG8_LDB(B0, 0, 0); PG8_LDB(B1, 0, 1); PG8_SCHED; PG8_LDA(At, 0, 0); PG8_STAGE(PG8_SA(1, 1), a1 + hstep, voffA);
;     ...
; #pragma unroll
;         for (int a = 0; a < 2; ++a)
; #pragma unroll
;             for (int b = 0; b < 2; ++b)
; #pragma unroll
;                 for (int m = 0; m < 4; ++m)
; #pragma unroll
;                     for (int n = 0; n < 2; ++n) acc[a][b][m][n] = (f32x4){0.f, 0.f, 0.f, 0.f};
.LBB0_524:
	s_ashr_i32 s23, s22, 31
	s_lshl_b64 s[24:25], s[22:23], 19
	s_add_u32 s24, s62, s24
	s_addc_u32 s25, s63, s25
	s_and_b64 s[26:27], s[0:1], exec
	s_cselect_b32 s3, s25, s31
	s_cselect_b32 s23, s24, s30
	s_ashr_i32 s21, s20, 31
	s_lshl_b64 s[26:27], s[20:21], 19
	s_add_u32 s26, s6, s26
	s_addc_u32 s27, s7, s27
	s_and_b64 s[36:37], s[0:1], exec
	s_cselect_b32 s21, s27, s35
	s_cselect_b32 s50, s26, s34
	s_add_u32 s30, s30, 0x40080
	s_addc_u32 s31, s31, 0
	s_add_u32 s51, s34, 0x100
	v_mov_b32_e32 v0, 0
	s_addc_u32 s52, s35, 0
	s_mov_b32 s53, -2
	v_mov_b32_e32 v1, v0
	v_mov_b32_e32 v2, v0
	v_mov_b32_e32 v3, v0
	v_mov_b32_e32 v4, v0
	v_mov_b32_e32 v5, v0
	v_mov_b32_e32 v6, v0
	v_mov_b32_e32 v7, v0
	v_mov_b32_e32 v8, v0
	v_mov_b32_e32 v9, v0
	v_mov_b32_e32 v10, v0
	v_mov_b32_e32 v11, v0
	v_mov_b32_e32 v12, v0
	v_mov_b32_e32 v13, v0
	v_mov_b32_e32 v14, v0
	v_mov_b32_e32 v15, v0
	v_mov_b32_e32 v16, v0
	v_mov_b32_e32 v17, v0
	v_mov_b32_e32 v18, v0
	v_mov_b32_e32 v19, v0
	v_mov_b32_e32 v20, v0
	v_mov_b32_e32 v21, v0
	v_mov_b32_e32 v22, v0
	v_mov_b32_e32 v23, v0
	v_mov_b32_e32 v24, v0
	v_mov_b32_e32 v25, v0
	v_mov_b32_e32 v26, v0
	v_mov_b32_e32 v27, v0
	v_mov_b32_e32 v28, v0
	v_mov_b32_e32 v29, v0
	v_mov_b32_e32 v30, v0
	v_mov_b32_e32 v31, v0
	v_mov_b32_e32 v60, v0
	v_mov_b32_e32 v61, v0
	v_mov_b32_e32 v62, v0
	v_mov_b32_e32 v63, v0
	v_mov_b32_e32 v68, v0
	v_mov_b32_e32 v69, v0
	v_mov_b32_e32 v70, v0
	v_mov_b32_e32 v71, v0
	v_mov_b32_e32 v72, v0
	v_mov_b32_e32 v73, v0
	v_mov_b32_e32 v74, v0
	v_mov_b32_e32 v75, v0
	v_mov_b32_e32 v76, v0
	v_mov_b32_e32 v77, v0
	v_mov_b32_e32 v78, v0
	v_mov_b32_e32 v79, v0
	v_mov_b32_e32 v80, v0
	v_mov_b32_e32 v81, v0
	v_mov_b32_e32 v82, v0
	v_mov_b32_e32 v83, v0
	v_mov_b32_e32 v84, v0
	v_mov_b32_e32 v85, v0
	v_mov_b32_e32 v86, v0
	v_mov_b32_e32 v87, v0
	v_mov_b32_e32 v88, v0
	v_mov_b32_e32 v89, v0
	v_mov_b32_e32 v90, v0
	v_mov_b32_e32 v91, v0
	v_mov_b32_e32 v92, v0
	v_mov_b32_e32 v93, v0
	v_mov_b32_e32 v94, v0
	v_mov_b32_e32 v95, v0
	v_mov_b32_e32 v32, v0
	v_mov_b32_e32 v33, v0
	v_mov_b32_e32 v34, v0
	v_mov_b32_e32 v35, v0
	v_mov_b32_e32 v36, v0
	v_mov_b32_e32 v37, v0
	v_mov_b32_e32 v38, v0
	v_mov_b32_e32 v39, v0
	v_mov_b32_e32 v40, v0
	v_mov_b32_e32 v41, v0
	v_mov_b32_e32 v42, v0
	v_mov_b32_e32 v43, v0
	v_mov_b32_e32 v44, v0
	v_mov_b32_e32 v45, v0
	v_mov_b32_e32 v46, v0
	v_mov_b32_e32 v47, v0
	v_mov_b32_e32 v48, v0
	v_mov_b32_e32 v49, v0
	v_mov_b32_e32 v50, v0
	v_mov_b32_e32 v51, v0
	v_mov_b32_e32 v52, v0
	v_mov_b32_e32 v53, v0
	v_mov_b32_e32 v54, v0
	v_mov_b32_e32 v55, v0
	v_mov_b32_e32 v56, v0
	v_mov_b32_e32 v57, v0
	v_mov_b32_e32 v58, v0
	v_mov_b32_e32 v59, v0
	v_mov_b32_e32 v64, v0
	v_mov_b32_e32 v65, v0
	v_mov_b32_e32 v66, v0
	v_mov_b32_e32 v67, v0
	v_mov_b32_e32 v96, v0
	v_mov_b32_e32 v97, v0
	v_mov_b32_e32 v98, v0
	v_mov_b32_e32 v99, v0
	v_mov_b32_e32 v100, v0
	v_mov_b32_e32 v101, v0
	v_mov_b32_e32 v102, v0
	v_mov_b32_e32 v103, v0
	v_mov_b32_e32 v104, v0
	v_mov_b32_e32 v105, v0
	v_mov_b32_e32 v106, v0
	v_mov_b32_e32 v107, v0
	v_mov_b32_e32 v108, v0
	v_mov_b32_e32 v109, v0
	v_mov_b32_e32 v110, v0
	v_mov_b32_e32 v111, v0
	v_mov_b32_e32 v112, v0
	v_mov_b32_e32 v113, v0
	v_mov_b32_e32 v114, v0
	v_mov_b32_e32 v115, v0
	v_mov_b32_e32 v116, v0
	v_mov_b32_e32 v117, v0
	v_mov_b32_e32 v118, v0
	v_mov_b32_e32 v119, v0
	v_mov_b32_e32 v120, v0
	v_mov_b32_e32 v121, v0
	v_mov_b32_e32 v122, v0
	v_mov_b32_e32 v123, v0
	v_mov_b32_e32 v124, v0
	v_mov_b32_e32 v125, v0
	v_mov_b32_e32 v126, v0
	v_mov_b32_e32 v127, v0
	v_readfirstlane_b32 s98, v197
	s_nop 3
	s_cmpk_gt_u32 s98, 0xff
	s_cbranch_scc0 .Lkp_6
	s_setprio 1
.Lkp_6:
.LBB0_525:
	ds_read_b128 v[144:147], v157
	ds_read_b128 v[148:151], v157 offset:1024
	ds_read_b128 v[162:165], v157 offset:2048
	ds_read_b128 v[166:169], v157 offset:3072
	ds_read_b128 v[170:173], v158
	ds_read_b128 v[174:177], v158 offset:1024
	ds_read_b128 v[178:181], v158 offset:2048
	ds_read_b128 v[182:185], v158 offset:3072
	s_add_u32 s34, s30, 0xfffc0080
	s_addc_u32 s35, s31, -1
	s_cmp_eq_u32 s53, 12
	s_cselect_b32 s37, s3, s35
	s_cselect_b32 s36, s23, s34
	s_cselect_b32 s35, s21, s52
	s_cselect_b32 s34, s50, s51
	v_lshl_add_u64 v[194:195], s[30:31], 0, v[136:137]
	s_add_i32 m0, s29, 0xc000
	ds_read_b128 v[186:189], v159
	ds_read_b128 v[190:193], v159 offset:1024
	ds_read_b128 v[198:201], v159 offset:2048
	ds_read_b128 v[202:205], v159 offset:3072
	ds_read_b128 v[206:209], v159 offset:4096
	ds_read_b128 v[210:213], v159 offset:5120
	ds_read_b128 v[214:217], v159 offset:6144
	ds_read_b128 v[218:221], v159 offset:7168
	global_load_lds_dwordx4 v[194:195], off
	v_lshl_add_u64 v[194:195], s[30:31], 0, v[138:139]
	s_add_i32 m0, s29, 0xe000
	s_nop 0
	global_load_lds_dwordx4 v[194:195], off
	s_waitcnt vmcnt(8)
	s_waitcnt lgkmcnt(0)
	s_barrier
; #define PG8_STAGE(bufoff, gbase, voff) do { _Pragma("unroll") for (int _i = 0; _i < 2; ++_i) \
;         __builtin_amdgcn_global_load_lds((const unsigned*)((const char*)(gbase) + (voff)[_i]), (PG8_LAS unsigned*)(lds + (bufoff) + ldsw + _i * 8192), 16, 0, 0); } while (0)
; #define PG8_LDA(dst, b, h) do { _Pragma("unroll") for (int m = 0; m < 4; ++m) _Pragma("unroll") for (int k = 0; k < 2; ++k) dst[m][k] = *(const PG8_LAS bf16x8*)(lds + PG8_SA(b, h) + aoff + m * 2048 + k * 1024); } while (0)
; #define PG8_MMA(ai, bj, At, Bt) do { __builtin_amdgcn_s_setprio(1); _Pragma("unroll") for (int m = 0; m < 4; ++m) _Pragma("unroll") for (int n = 0; n < 2; ++n) _Pragma("unroll") for (int k = 0; k < 2; ++k) \
;         acc[ai][bj][m][n] = __builtin_amdgcn_mfma_f32_16x16x32_bf16(Bt[n][k], At[m][k], acc[ai][bj][m][n], 0, 0, 0); __builtin_amdgcn_s_setprio(0); } while (0)
; #define PG8_WAIT_V(n) asm volatile("s_waitcnt vmcnt(" #n ")" ::: "memory")
; #define PG8_WAIT_L(n) asm volatile("s_waitcnt lgkmcnt(" #n ")" ::: "memory")
; #define PG8_BAR __builtin_amdgcn_s_barrier()
; #define PG8_SCHED __builtin_amdgcn_sched_barrier(0)
; template <class Epi, class Sched, bool ALIGN_EPI = false, bool SP2 = false>
; __device__ __forceinline__ void gemm_phase(PG8_LAS unsigned char* lds, const Gemm g, const Sched& S, const Epi& E) {
;     ...
;             PG8_WAIT_V(8); PG8_WAIT_L(0); PG8_BAR; PG8_MMA(0, 0, At, B0); PG8_MMA(0, 1, At, B1); PG8_BAR; PG8_SCHED;
;             PG8_LDA(At, 0, 1); PG8_STAGE(PG8_SB(0, 0), b2, voffB); PG8_STAGE(PG8_SB(0, 1), b2 + hstep, voffB); PG8_STAGE(PG8_SA(0, 0), a2, voffA);
;             PG8_WAIT_V(8); PG8_WAIT_L(0); PG8_BAR; PG8_MMA(1, 0, At, B0); PG8_MMA(1, 1, At, B1); PG8_BAR; PG8_SCHED;
	s_waitcnt lgkmcnt(0)
	v_mfma_f32_16x16x32_bf16 v[124:127], v[144:147], v[186:189], v[124:127]
	v_mfma_f32_16x16x32_bf16 v[120:123], v[162:165], v[186:189], v[120:123]
	v_mfma_f32_16x16x32_bf16 v[116:119], v[144:147], v[198:201], v[116:119]
	v_mfma_f32_16x16x32_bf16 v[112:115], v[162:165], v[198:201], v[112:115]
	v_mfma_f32_16x16x32_bf16 v[108:111], v[144:147], v[206:209], v[108:111]
	v_mfma_f32_16x16x32_bf16 v[104:107], v[162:165], v[206:209], v[104:107]
	v_mfma_f32_16x16x32_bf16 v[100:103], v[144:147], v[214:217], v[100:103]
	v_mfma_f32_16x16x32_bf16 v[96:99], v[162:165], v[214:217], v[96:99]
	v_mfma_f32_16x16x32_bf16 v[124:127], v[148:151], v[190:193], v[124:127]
	v_mfma_f32_16x16x32_bf16 v[120:123], v[166:169], v[190:193], v[120:123]
	v_mfma_f32_16x16x32_bf16 v[116:119], v[148:151], v[202:205], v[116:119]
	v_mfma_f32_16x16x32_bf16 v[112:115], v[166:169], v[202:205], v[112:115]
	v_mfma_f32_16x16x32_bf16 v[108:111], v[148:151], v[210:213], v[108:111]
	v_mfma_f32_16x16x32_bf16 v[104:107], v[166:169], v[210:213], v[104:107]
	v_mfma_f32_16x16x32_bf16 v[100:103], v[148:151], v[218:221], v[100:103]
	v_mfma_f32_16x16x32_bf16 v[96:99], v[166:169], v[218:221], v[96:99]
	v_mfma_f32_16x16x32_bf16 v[64:67], v[170:173], v[186:189], v[64:67]
	v_mfma_f32_16x16x32_bf16 v[56:59], v[178:181], v[186:189], v[56:59]
	v_mfma_f32_16x16x32_bf16 v[52:55], v[170:173], v[198:201], v[52:55]
	v_mfma_f32_16x16x32_bf16 v[48:51], v[178:181], v[198:201], v[48:51]
	v_mfma_f32_16x16x32_bf16 v[44:47], v[170:173], v[206:209], v[44:47]
	v_mfma_f32_16x16x32_bf16 v[40:43], v[178:181], v[206:209], v[40:43]
	v_mfma_f32_16x16x32_bf16 v[36:39], v[170:173], v[214:217], v[36:39]
	v_mfma_f32_16x16x32_bf16 v[32:35], v[178:181], v[214:217], v[32:35]
	v_mfma_f32_16x16x32_bf16 v[64:67], v[174:177], v[190:193], v[64:67]
	v_mfma_f32_16x16x32_bf16 v[56:59], v[182:185], v[190:193], v[56:59]
	v_mfma_f32_16x16x32_bf16 v[52:55], v[174:177], v[202:205], v[52:55]
	v_mfma_f32_16x16x32_bf16 v[48:51], v[182:185], v[202:205], v[48:51]
	v_mfma_f32_16x16x32_bf16 v[44:47], v[174:177], v[210:213], v[44:47]
	v_mfma_f32_16x16x32_bf16 v[40:43], v[182:185], v[210:213], v[40:43]
	v_mfma_f32_16x16x32_bf16 v[36:39], v[174:177], v[218:221], v[36:39]
	v_mfma_f32_16x16x32_bf16 v[32:35], v[182:185], v[218:221], v[32:35]
	s_barrier
	s_add_i32 s54, s47, s33
	v_lshl_add_u64 v[194:195], s[34:35], 0, v[130:131]
	s_mov_b32 m0, s54
	ds_read_b128 v[186:189], v159 offset:16384
	ds_read_b128 v[190:193], v159 offset:17408
	ds_read_b128 v[198:201], v159 offset:18432
	ds_read_b128 v[202:205], v159 offset:19456
	ds_read_b128 v[206:209], v159 offset:20480
	ds_read_b128 v[210:213], v159 offset:21504
	ds_read_b128 v[214:217], v159 offset:22528
	ds_read_b128 v[218:221], v159 offset:23552
	global_load_lds_dwordx4 v[194:195], off
	s_add_i32 m0, s54, 0x2000
	s_add_u32 s54, s34, 0x40000
	v_lshl_add_u64 v[222:223], s[34:35], 0, v[134:135]
	s_addc_u32 s55, s35, 0
	s_add_i32 s56, s48, s33
	global_load_lds_dwordx4 v[222:223], off
	v_lshl_add_u64 v[224:225], s[54:55], 0, v[130:131]
	s_mov_b32 m0, s56
	v_lshl_add_u64 v[226:227], s[36:37], 0, v[132:133]
	global_load_lds_dwordx4 v[224:225], off
	v_lshl_add_u64 v[224:225], s[54:55], 0, v[134:135]
	s_add_i32 m0, s56, 0x2000
	s_nop 0
	global_load_lds_dwordx4 v[224:225], off
	v_lshl_add_u64 v[224:225], s[36:37], 0, v[128:129]
	s_mov_b32 m0, s29
	s_nop 0
	global_load_lds_dwordx4 v[224:225], off
	s_mov_b32 m0, s38
	s_nop 0
	global_load_lds_dwordx4 v[226:227], off
	s_waitcnt vmcnt(8)
	s_waitcnt lgkmcnt(0)
	s_barrier
	s_waitcnt lgkmcnt(0)
	v_mfma_f32_16x16x32_bf16 v[92:95], v[144:147], v[186:189], v[92:95]
	v_mfma_f32_16x16x32_bf16 v[88:91], v[162:165], v[186:189], v[88:91]
	v_mfma_f32_16x16x32_bf16 v[84:87], v[144:147], v[198:201], v[84:87]
	v_mfma_f32_16x16x32_bf16 v[80:83], v[162:165], v[198:201], v[80:83]
	v_mfma_f32_16x16x32_bf16 v[76:79], v[144:147], v[206:209], v[76:79]
	v_mfma_f32_16x16x32_bf16 v[72:75], v[162:165], v[206:209], v[72:75]
	v_mfma_f32_16x16x32_bf16 v[68:71], v[144:147], v[214:217], v[68:71]
	v_mfma_f32_16x16x32_bf16 v[60:63], v[162:165], v[214:217], v[60:63]
	v_mfma_f32_16x16x32_bf16 v[92:95], v[148:151], v[190:193], v[92:95]
	v_mfma_f32_16x16x32_bf16 v[88:91], v[166:169], v[190:193], v[88:91]
	v_mfma_f32_16x16x32_bf16 v[84:87], v[148:151], v[202:205], v[84:87]
	v_mfma_f32_16x16x32_bf16 v[80:83], v[166:169], v[202:205], v[80:83]
	v_mfma_f32_16x16x32_bf16 v[76:79], v[148:151], v[210:213], v[76:79]
	v_mfma_f32_16x16x32_bf16 v[72:75], v[166:169], v[210:213], v[72:75]
	v_mfma_f32_16x16x32_bf16 v[68:71], v[148:151], v[218:221], v[68:71]
	v_mfma_f32_16x16x32_bf16 v[60:63], v[166:169], v[218:221], v[60:63]
	v_mfma_f32_16x16x32_bf16 v[28:31], v[170:173], v[186:189], v[28:31]
	v_mfma_f32_16x16x32_bf16 v[24:27], v[178:181], v[186:189], v[24:27]
	v_mfma_f32_16x16x32_bf16 v[20:23], v[170:173], v[198:201], v[20:23]
	v_mfma_f32_16x16x32_bf16 v[16:19], v[178:181], v[198:201], v[16:19]
	v_mfma_f32_16x16x32_bf16 v[12:15], v[170:173], v[206:209], v[12:15]
	v_mfma_f32_16x16x32_bf16 v[8:11], v[178:181], v[206:209], v[8:11]
	v_mfma_f32_16x16x32_bf16 v[4:7], v[170:173], v[214:217], v[4:7]
	v_mfma_f32_16x16x32_bf16 v[0:3], v[178:181], v[214:217], v[0:3]
	v_mfma_f32_16x16x32_bf16 v[28:31], v[174:177], v[190:193], v[28:31]
	v_mfma_f32_16x16x32_bf16 v[24:27], v[182:185], v[190:193], v[24:27]
	v_mfma_f32_16x16x32_bf16 v[20:23], v[174:177], v[202:205], v[20:23]
	v_mfma_f32_16x16x32_bf16 v[16:19], v[182:185], v[202:205], v[16:19]
	v_mfma_f32_16x16x32_bf16 v[12:15], v[174:177], v[210:213], v[12:15]
	v_mfma_f32_16x16x32_bf16 v[8:11], v[182:185], v[210:213], v[8:11]
	v_mfma_f32_16x16x32_bf16 v[4:7], v[174:177], v[218:221], v[4:7]
	v_mfma_f32_16x16x32_bf16 v[0:3], v[182:185], v[218:221], v[0:3]
	s_barrier
; #define PG8_STAGE(bufoff, gbase, voff) do { _Pragma("unroll") for (int _i = 0; _i < 2; ++_i) \
;         __builtin_amdgcn_global_load_lds((const unsigned*)((const char*)(gbase) + (voff)[_i]), (PG8_LAS unsigned*)(lds + (bufoff) + ldsw + _i * 8192), 16, 0, 0); } while (0)
; #define PG8_LDA(dst, b, h) do { _Pragma("unroll") for (int m = 0; m < 4; ++m) _Pragma("unroll") for (int k = 0; k < 2; ++k) dst[m][k] = *(const PG8_LAS bf16x8*)(lds + PG8_SA(b, h) + aoff + m * 2048 + k * 1024); } while (0)
; #define PG8_LDB(dst, b, h) do { _Pragma("unroll") for (int n = 0; n < 2; ++n) _Pragma("unroll") for (int k = 0; k < 2; ++k) dst[n][k] = *(const PG8_LAS bf16x8*)(lds + PG8_SB(b, h) + boff + n * 2048 + k * 1024); } while (0)
; #define PG8_MMA(ai, bj, At, Bt) do { __builtin_amdgcn_s_setprio(1); _Pragma("unroll") for (int m = 0; m < 4; ++m) _Pragma("unroll") for (int n = 0; n < 2; ++n) _Pragma("unroll") for (int k = 0; k < 2; ++k) \
;         acc[ai][bj][m][n] = __builtin_amdgcn_mfma_f32_16x16x32_bf16(Bt[n][k], At[m][k], acc[ai][bj][m][n], 0, 0, 0); __builtin_amdgcn_s_setprio(0); } while (0)
; #define PG8_WAIT_V(n) asm volatile("s_waitcnt vmcnt(" #n ")" ::: "memory")
; #define PG8_WAIT_L(n) asm volatile("s_waitcnt lgkmcnt(" #n ")" ::: "memory")
; #define PG8_BAR __builtin_amdgcn_s_barrier()
; #define PG8_SCHED __builtin_amdgcn_sched_barrier(0)
; template <class Epi, class Sched, bool ALIGN_EPI = false, bool SP2 = false>
; __device__ __forceinline__ void gemm_phase(PG8_LAS unsigned char* lds, const Gemm g, const Sched& S, const Epi& E) {
;     ...
;             PG8_LDB(B0, 1, 0); PG8_LDB(B1, 1, 1); PG8_SCHED; PG8_LDA(At, 1, 0); PG8_STAGE(PG8_SA(0, 1), a2 + hstep, voffA);
;             PG8_WAIT_V(8); PG8_WAIT_L(0); PG8_BAR; PG8_MMA(0, 0, At, B0); PG8_MMA(0, 1, At, B1); PG8_BAR; PG8_SCHED;
	s_add_i32 s54, 0, 0x18000
	v_add_u32_e32 v152, s54, v155
	s_add_i32 s55, 0, 0x1c000
	ds_read_b128 v[144:147], v152
	ds_read_b128 v[148:151], v152 offset:1024
	ds_read_b128 v[162:165], v152 offset:2048
	ds_read_b128 v[166:169], v152 offset:3072
	v_add_u32_e32 v152, s55, v155
	ds_read_b128 v[170:173], v152
	ds_read_b128 v[174:177], v152 offset:1024
	ds_read_b128 v[178:181], v152 offset:2048
	ds_read_b128 v[182:185], v152 offset:3072
	s_add_u32 s36, s36, 0x40000
	s_addc_u32 s37, s37, 0
	s_mov_b32 m0, s39
	v_lshl_add_u64 v[228:229], s[36:37], 0, v[128:129]
	ds_read_b128 v[186:189], v159 offset:32768
	ds_read_b128 v[190:193], v159 offset:33792
	ds_read_b128 v[198:201], v159 offset:34816
	ds_read_b128 v[202:205], v159 offset:35840
	ds_read_b128 v[206:209], v159 offset:36864
	ds_read_b128 v[210:213], v159 offset:37888
	ds_read_b128 v[214:217], v159 offset:38912
	ds_read_b128 v[218:221], v159 offset:39936
	global_load_lds_dwordx4 v[228:229], off
	v_lshl_add_u64 v[228:229], s[36:37], 0, v[132:133]
	s_mov_b32 m0, s40
	s_nop 0
	global_load_lds_dwordx4 v[228:229], off
	s_waitcnt vmcnt(8)
	s_waitcnt lgkmcnt(0)
	s_barrier
	s_waitcnt lgkmcnt(0)
	v_mfma_f32_16x16x32_bf16 v[124:127], v[144:147], v[186:189], v[124:127]
	v_mfma_f32_16x16x32_bf16 v[120:123], v[162:165], v[186:189], v[120:123]
	v_mfma_f32_16x16x32_bf16 v[116:119], v[144:147], v[198:201], v[116:119]
	v_mfma_f32_16x16x32_bf16 v[112:115], v[162:165], v[198:201], v[112:115]
	v_mfma_f32_16x16x32_bf16 v[108:111], v[144:147], v[206:209], v[108:111]
	v_mfma_f32_16x16x32_bf16 v[104:107], v[162:165], v[206:209], v[104:107]
	v_mfma_f32_16x16x32_bf16 v[100:103], v[144:147], v[214:217], v[100:103]
	v_mfma_f32_16x16x32_bf16 v[96:99], v[162:165], v[214:217], v[96:99]
	v_mfma_f32_16x16x32_bf16 v[124:127], v[148:151], v[190:193], v[124:127]
	v_mfma_f32_16x16x32_bf16 v[120:123], v[166:169], v[190:193], v[120:123]
	v_mfma_f32_16x16x32_bf16 v[116:119], v[148:151], v[202:205], v[116:119]
	v_mfma_f32_16x16x32_bf16 v[112:115], v[166:169], v[202:205], v[112:115]
	v_mfma_f32_16x16x32_bf16 v[108:111], v[148:151], v[210:213], v[108:111]
	v_mfma_f32_16x16x32_bf16 v[104:107], v[166:169], v[210:213], v[104:107]
	v_mfma_f32_16x16x32_bf16 v[100:103], v[148:151], v[218:221], v[100:103]
	v_mfma_f32_16x16x32_bf16 v[96:99], v[166:169], v[218:221], v[96:99]
	v_mfma_f32_16x16x32_bf16 v[64:67], v[170:173], v[186:189], v[64:67]
	v_mfma_f32_16x16x32_bf16 v[56:59], v[178:181], v[186:189], v[56:59]
	v_mfma_f32_16x16x32_bf16 v[52:55], v[170:173], v[198:201], v[52:55]
	v_mfma_f32_16x16x32_bf16 v[48:51], v[178:181], v[198:201], v[48:51]
	v_mfma_f32_16x16x32_bf16 v[44:47], v[170:173], v[206:209], v[44:47]
	v_mfma_f32_16x16x32_bf16 v[40:43], v[178:181], v[206:209], v[40:43]
	v_mfma_f32_16x16x32_bf16 v[36:39], v[170:173], v[214:217], v[36:39]
	v_mfma_f32_16x16x32_bf16 v[32:35], v[178:181], v[214:217], v[32:35]
	v_mfma_f32_16x16x32_bf16 v[64:67], v[174:177], v[190:193], v[64:67]
	v_mfma_f32_16x16x32_bf16 v[56:59], v[182:185], v[190:193], v[56:59]
	v_mfma_f32_16x16x32_bf16 v[52:55], v[174:177], v[202:205], v[52:55]
	v_mfma_f32_16x16x32_bf16 v[48:51], v[182:185], v[202:205], v[48:51]
	v_mfma_f32_16x16x32_bf16 v[44:47], v[174:177], v[210:213], v[44:47]
	v_mfma_f32_16x16x32_bf16 v[40:43], v[182:185], v[210:213], v[40:43]
	v_mfma_f32_16x16x32_bf16 v[36:39], v[174:177], v[218:221], v[36:39]
	v_mfma_f32_16x16x32_bf16 v[32:35], v[182:185], v[218:221], v[32:35]
	s_barrier
; #define PG8_STAGE(bufoff, gbase, voff) do { _Pragma("unroll") for (int _i = 0; _i < 2; ++_i) \
;         __builtin_amdgcn_global_load_lds((const unsigned*)((const char*)(gbase) + (voff)[_i]), (PG8_LAS unsigned*)(lds + (bufoff) + ldsw + _i * 8192), 16, 0, 0); } while (0)
; #define PG8_LDA(dst, b, h) do { _Pragma("unroll") for (int m = 0; m < 4; ++m) _Pragma("unroll") for (int k = 0; k < 2; ++k) dst[m][k] = *(const PG8_LAS bf16x8*)(lds + PG8_SA(b, h) + aoff + m * 2048 + k * 1024); } while (0)
; #define PG8_MMA(ai, bj, At, Bt) do { __builtin_amdgcn_s_setprio(1); _Pragma("unroll") for (int m = 0; m < 4; ++m) _Pragma("unroll") for (int n = 0; n < 2; ++n) _Pragma("unroll") for (int k = 0; k < 2; ++k) \
;         acc[ai][bj][m][n] = __builtin_amdgcn_mfma_f32_16x16x32_bf16(Bt[n][k], At[m][k], acc[ai][bj][m][n], 0, 0, 0); __builtin_amdgcn_s_setprio(0); } while (0)
; #define PG8_WAIT_V(n) asm volatile("s_waitcnt vmcnt(" #n ")" ::: "memory")
; #define PG8_WAIT_L(n) asm volatile("s_waitcnt lgkmcnt(" #n ")" ::: "memory")
; #define PG8_BAR __builtin_amdgcn_s_barrier()
; #define PG8_SCHED __builtin_amdgcn_sched_barrier(0)
; template <class Epi, class Sched, bool ALIGN_EPI = false, bool SP2 = false>
; __device__ __forceinline__ void gemm_phase(PG8_LAS unsigned char* lds, const Gemm g, const Sched& S, const Epi& E) {
;     ...
;         for (int t = 0; t < nt; t += 2) {
;     ...
;             PG8_LDA(At, 1, 1); PG8_STAGE(PG8_SB(1, 0), b3, voffB); PG8_STAGE(PG8_SB(1, 1), b3 + hstep, voffB); PG8_STAGE(PG8_SA(1, 0), a3, voffA);
;             PG8_WAIT_V(8); PG8_WAIT_L(0); PG8_BAR; PG8_MMA(1, 0, At, B0); PG8_MMA(1, 1, At, B1); PG8_BAR; PG8_SCHED;
;     ...
;         if constexpr (ALIGN_EPI) { if (wr == 0) PG8_BAR; }
	s_add_i32 s36, s54, s33
	v_lshl_add_u64 v[194:195], v[194:195], 0, s[14:15]
	s_mov_b32 m0, s36
	ds_read_b128 v[186:189], v159 offset:49152
	ds_read_b128 v[190:193], v159 offset:50176
	ds_read_b128 v[198:201], v159 offset:51200
	ds_read_b128 v[202:205], v159 offset:52224
	ds_read_b128 v[206:209], v159 offset:53248
	ds_read_b128 v[210:213], v159 offset:54272
	ds_read_b128 v[214:217], v159 offset:55296
	ds_read_b128 v[218:221], v159 offset:56320
	global_load_lds_dwordx4 v[194:195], off
	s_add_i32 m0, s36, 0x2000
	s_add_u32 s34, s34, 0x40080
	v_lshl_add_u64 v[194:195], v[222:223], 0, s[14:15]
	s_addc_u32 s35, s35, 0
	s_add_i32 s36, s55, s33
	global_load_lds_dwordx4 v[194:195], off
	v_lshl_add_u64 v[194:195], s[34:35], 0, v[130:131]
	s_mov_b32 m0, s36
	s_nop 0
	global_load_lds_dwordx4 v[194:195], off
	v_lshl_add_u64 v[194:195], s[34:35], 0, v[134:135]
	s_add_i32 m0, s36, 0x2000
	s_nop 0
	global_load_lds_dwordx4 v[194:195], off
	v_lshl_add_u64 v[194:195], v[224:225], 0, s[14:15]
	s_mov_b32 m0, s44
	s_nop 0
	global_load_lds_dwordx4 v[194:195], off
	v_lshl_add_u64 v[194:195], v[226:227], 0, s[14:15]
	s_mov_b32 m0, s45
	s_nop 0
	global_load_lds_dwordx4 v[194:195], off
	s_waitcnt vmcnt(8)
	s_waitcnt lgkmcnt(0)
	s_barrier
	s_waitcnt lgkmcnt(0)
	v_mfma_f32_16x16x32_bf16 v[92:95], v[144:147], v[186:189], v[92:95]
	v_mfma_f32_16x16x32_bf16 v[88:91], v[162:165], v[186:189], v[88:91]
	v_mfma_f32_16x16x32_bf16 v[84:87], v[144:147], v[198:201], v[84:87]
	v_mfma_f32_16x16x32_bf16 v[80:83], v[162:165], v[198:201], v[80:83]
	v_mfma_f32_16x16x32_bf16 v[76:79], v[144:147], v[206:209], v[76:79]
	v_mfma_f32_16x16x32_bf16 v[72:75], v[162:165], v[206:209], v[72:75]
	v_mfma_f32_16x16x32_bf16 v[68:71], v[144:147], v[214:217], v[68:71]
	v_mfma_f32_16x16x32_bf16 v[60:63], v[162:165], v[214:217], v[60:63]
	v_mfma_f32_16x16x32_bf16 v[92:95], v[148:151], v[190:193], v[92:95]
	v_mfma_f32_16x16x32_bf16 v[88:91], v[166:169], v[190:193], v[88:91]
	v_mfma_f32_16x16x32_bf16 v[84:87], v[148:151], v[202:205], v[84:87]
	v_mfma_f32_16x16x32_bf16 v[80:83], v[166:169], v[202:205], v[80:83]
	v_mfma_f32_16x16x32_bf16 v[76:79], v[148:151], v[210:213], v[76:79]
	v_mfma_f32_16x16x32_bf16 v[72:75], v[166:169], v[210:213], v[72:75]
	v_mfma_f32_16x16x32_bf16 v[68:71], v[148:151], v[218:221], v[68:71]
	v_mfma_f32_16x16x32_bf16 v[60:63], v[166:169], v[218:221], v[60:63]
	v_mfma_f32_16x16x32_bf16 v[28:31], v[170:173], v[186:189], v[28:31]
	v_mfma_f32_16x16x32_bf16 v[24:27], v[178:181], v[186:189], v[24:27]
	v_mfma_f32_16x16x32_bf16 v[20:23], v[170:173], v[198:201], v[20:23]
	v_mfma_f32_16x16x32_bf16 v[16:19], v[178:181], v[198:201], v[16:19]
	v_mfma_f32_16x16x32_bf16 v[12:15], v[170:173], v[206:209], v[12:15]
	v_mfma_f32_16x16x32_bf16 v[8:11], v[178:181], v[206:209], v[8:11]
	v_mfma_f32_16x16x32_bf16 v[4:7], v[170:173], v[214:217], v[4:7]
	v_mfma_f32_16x16x32_bf16 v[0:3], v[178:181], v[214:217], v[0:3]
	v_mfma_f32_16x16x32_bf16 v[28:31], v[174:177], v[190:193], v[28:31]
	v_mfma_f32_16x16x32_bf16 v[24:27], v[182:185], v[190:193], v[24:27]
	v_mfma_f32_16x16x32_bf16 v[20:23], v[174:177], v[202:205], v[20:23]
	v_mfma_f32_16x16x32_bf16 v[16:19], v[182:185], v[202:205], v[16:19]
	v_mfma_f32_16x16x32_bf16 v[12:15], v[174:177], v[210:213], v[12:15]
	v_mfma_f32_16x16x32_bf16 v[8:11], v[182:185], v[210:213], v[8:11]
	v_mfma_f32_16x16x32_bf16 v[4:7], v[174:177], v[218:221], v[4:7]
	v_mfma_f32_16x16x32_bf16 v[0:3], v[182:185], v[218:221], v[0:3]
	s_barrier
	s_add_i32 s53, s53, 2
	s_add_u32 s30, s30, 0x100
	s_addc_u32 s31, s31, 0
	s_add_u32 s51, s51, 0x100
	s_addc_u32 s52, s52, 0
	s_cmp_gt_u32 s53, 13
	s_cbranch_scc0 .LBB0_525
	s_setprio 0
	s_and_b64 vcc, exec, s[16:17]
	s_cbranch_vccz .LBB0_528
	s_barrier

; template <class Epi, class Sched, bool ALIGN_EPI = false, bool SP2 = false>
; __device__ __forceinline__ void gemm_phase(PG8_LAS unsigned char* lds, const Gemm g, const Sched& S, const Epi& E) {
;     ...
;     f32x4 acc[2][2][4][2];
; #pragma unroll
;     for (int a = 0; a < 2; ++a)
; #pragma unroll
;         for (int b = 0; b < 2; ++b)
; #pragma unroll
;             for (int m = 0; m < 4; ++m)
; #pragma unroll
;                 for (int n = 0; n < 2; ++n) acc[a][b][m][n] = (f32x4){0.f, 0.f, 0.f, 0.f};
;     ...
;         for (int t = 0; t < nt; t += 2) {
;             const bool last = (t == nt - 2);
;             const char* a1 = cA + (size_t)(t + 1) * kstep;
;             const char* a2 = last ? nA : cA + (size_t)(t + 2) * kstep; const char* b2 = last ? nB : cB + (size_t)(t + 2) * kstep;
;             const char* a3 = a2 + kstep; const char* b3 = b2 + kstep;
;             if (last && has_next) S.a_ready(nxt);
.LBB0_704:
	v_mov_b32_e32 v127, 0
	s_and_b64 vcc, exec, s[0:1]
	v_mov_b32_e32 v126, v127
	v_mov_b32_e32 v125, v127
	v_mov_b32_e32 v124, v127
	v_mov_b32_e32 v123, v127
	v_mov_b32_e32 v122, v127
	v_mov_b32_e32 v121, v127
	v_mov_b32_e32 v120, v127
	v_mov_b32_e32 v119, v127
	v_mov_b32_e32 v118, v127
	v_mov_b32_e32 v117, v127
	v_mov_b32_e32 v116, v127
	v_mov_b32_e32 v115, v127
	v_mov_b32_e32 v114, v127
	v_mov_b32_e32 v113, v127
	v_mov_b32_e32 v112, v127
	v_mov_b32_e32 v111, v127
	v_mov_b32_e32 v110, v127
	v_mov_b32_e32 v109, v127
	v_mov_b32_e32 v108, v127
	v_mov_b32_e32 v107, v127
	v_mov_b32_e32 v106, v127
	v_mov_b32_e32 v105, v127
	v_mov_b32_e32 v104, v127
	v_mov_b32_e32 v103, v127
	v_mov_b32_e32 v102, v127
	v_mov_b32_e32 v101, v127
	v_mov_b32_e32 v100, v127
	v_mov_b32_e32 v99, v127
	v_mov_b32_e32 v98, v127
	v_mov_b32_e32 v97, v127
	v_mov_b32_e32 v96, v127
	v_mov_b32_e32 v63, v127
	v_mov_b32_e32 v62, v127
	v_mov_b32_e32 v61, v127
	v_mov_b32_e32 v60, v127
	v_mov_b32_e32 v59, v127
	v_mov_b32_e32 v58, v127
	v_mov_b32_e32 v57, v127
	v_mov_b32_e32 v56, v127
	v_mov_b32_e32 v55, v127
	v_mov_b32_e32 v54, v127
	v_mov_b32_e32 v53, v127
	v_mov_b32_e32 v52, v127
	v_mov_b32_e32 v51, v127
	v_mov_b32_e32 v50, v127
	v_mov_b32_e32 v49, v127
	v_mov_b32_e32 v48, v127
	v_mov_b32_e32 v47, v127
	v_mov_b32_e32 v46, v127
	v_mov_b32_e32 v45, v127
	v_mov_b32_e32 v44, v127
	v_mov_b32_e32 v43, v127
	v_mov_b32_e32 v42, v127
	v_mov_b32_e32 v41, v127
	v_mov_b32_e32 v40, v127
	v_mov_b32_e32 v39, v127
	v_mov_b32_e32 v38, v127
	v_mov_b32_e32 v37, v127
	v_mov_b32_e32 v36, v127
	v_mov_b32_e32 v35, v127
	v_mov_b32_e32 v34, v127
	v_mov_b32_e32 v33, v127
	v_mov_b32_e32 v32, v127
	v_mov_b32_e32 v95, v127
	v_mov_b32_e32 v94, v127
	v_mov_b32_e32 v93, v127
	v_mov_b32_e32 v92, v127
	v_mov_b32_e32 v91, v127
	v_mov_b32_e32 v90, v127
	v_mov_b32_e32 v89, v127
	v_mov_b32_e32 v88, v127
	v_mov_b32_e32 v87, v127
	v_mov_b32_e32 v86, v127
	v_mov_b32_e32 v85, v127
	v_mov_b32_e32 v84, v127
	v_mov_b32_e32 v83, v127
	v_mov_b32_e32 v82, v127
	v_mov_b32_e32 v81, v127
	v_mov_b32_e32 v80, v127
	v_mov_b32_e32 v79, v127
	v_mov_b32_e32 v78, v127
	v_mov_b32_e32 v77, v127
	v_mov_b32_e32 v76, v127
	v_mov_b32_e32 v75, v127
	v_mov_b32_e32 v74, v127
	v_mov_b32_e32 v73, v127
	v_mov_b32_e32 v72, v127
	v_mov_b32_e32 v71, v127
	v_mov_b32_e32 v70, v127
	v_mov_b32_e32 v69, v127
	v_mov_b32_e32 v68, v127
	v_mov_b32_e32 v67, v127
	v_mov_b32_e32 v66, v127
	v_mov_b32_e32 v65, v127
	v_mov_b32_e32 v64, v127
	v_mov_b32_e32 v31, v127
	v_mov_b32_e32 v30, v127
	v_mov_b32_e32 v29, v127
	v_mov_b32_e32 v28, v127
	v_mov_b32_e32 v27, v127
	v_mov_b32_e32 v26, v127
	v_mov_b32_e32 v25, v127
	v_mov_b32_e32 v24, v127
	v_mov_b32_e32 v23, v127
	v_mov_b32_e32 v22, v127
	v_mov_b32_e32 v21, v127
	v_mov_b32_e32 v20, v127
	v_mov_b32_e32 v19, v127
	v_mov_b32_e32 v18, v127
	v_mov_b32_e32 v17, v127
	v_mov_b32_e32 v16, v127
	v_mov_b32_e32 v15, v127
	v_mov_b32_e32 v14, v127
	v_mov_b32_e32 v13, v127
	v_mov_b32_e32 v12, v127
	v_mov_b32_e32 v11, v127
	v_mov_b32_e32 v10, v127
	v_mov_b32_e32 v9, v127
	v_mov_b32_e32 v8, v127
	v_mov_b32_e32 v7, v127
	v_mov_b32_e32 v6, v127
	v_mov_b32_e32 v5, v127
	v_mov_b32_e32 v4, v127
	v_mov_b32_e32 v3, v127
	v_mov_b32_e32 v2, v127
	v_mov_b32_e32 v1, v127
	v_mov_b32_e32 v0, v127
	s_cbranch_vccnz .LBB0_707
	s_add_u32 s24, s24, 0x80
	s_addc_u32 s25, s25, 0
	s_add_u32 s52, s26, 0x100
	v_mov_b32_e32 v0, 0
	s_addc_u32 s53, s27, 0
	s_mov_b32 s26, 0
	v_mov_b32_e32 v1, v0
	v_mov_b32_e32 v2, v0
	v_mov_b32_e32 v3, v0
	v_mov_b32_e32 v4, v0
	v_mov_b32_e32 v5, v0
	v_mov_b32_e32 v6, v0
	v_mov_b32_e32 v7, v0
	v_mov_b32_e32 v8, v0
	v_mov_b32_e32 v9, v0
	v_mov_b32_e32 v10, v0
	v_mov_b32_e32 v11, v0
	v_mov_b32_e32 v12, v0
	v_mov_b32_e32 v13, v0
	v_mov_b32_e32 v14, v0
	v_mov_b32_e32 v15, v0
	v_mov_b32_e32 v16, v0
	v_mov_b32_e32 v17, v0
	v_mov_b32_e32 v18, v0
	v_mov_b32_e32 v19, v0
	v_mov_b32_e32 v20, v0
	v_mov_b32_e32 v21, v0
	v_mov_b32_e32 v22, v0
	v_mov_b32_e32 v23, v0
	v_mov_b32_e32 v24, v0
	v_mov_b32_e32 v25, v0
	v_mov_b32_e32 v26, v0
	v_mov_b32_e32 v27, v0
	v_mov_b32_e32 v28, v0
	v_mov_b32_e32 v29, v0
	v_mov_b32_e32 v30, v0
	v_mov_b32_e32 v31, v0
	v_mov_b32_e32 v64, v0
	v_mov_b32_e32 v65, v0
	v_mov_b32_e32 v66, v0
	v_mov_b32_e32 v67, v0
	v_mov_b32_e32 v68, v0
	v_mov_b32_e32 v69, v0
	v_mov_b32_e32 v70, v0
	v_mov_b32_e32 v71, v0
	v_mov_b32_e32 v72, v0
	v_mov_b32_e32 v73, v0
	v_mov_b32_e32 v74, v0
	v_mov_b32_e32 v75, v0
	v_mov_b32_e32 v76, v0
	v_mov_b32_e32 v77, v0
	v_mov_b32_e32 v78, v0
	v_mov_b32_e32 v79, v0
	v_mov_b32_e32 v80, v0
	v_mov_b32_e32 v81, v0
	v_mov_b32_e32 v82, v0
	v_mov_b32_e32 v83, v0
	v_mov_b32_e32 v84, v0
	v_mov_b32_e32 v85, v0
	v_mov_b32_e32 v86, v0
	v_mov_b32_e32 v87, v0
	v_mov_b32_e32 v88, v0
	v_mov_b32_e32 v89, v0
	v_mov_b32_e32 v90, v0
	v_mov_b32_e32 v91, v0
	v_mov_b32_e32 v92, v0
	v_mov_b32_e32 v93, v0
	v_mov_b32_e32 v94, v0
	v_mov_b32_e32 v95, v0
	v_mov_b32_e32 v32, v0
	v_mov_b32_e32 v33, v0
	v_mov_b32_e32 v34, v0
	v_mov_b32_e32 v35, v0
	v_mov_b32_e32 v36, v0
	v_mov_b32_e32 v37, v0
	v_mov_b32_e32 v38, v0
	v_mov_b32_e32 v39, v0
	v_mov_b32_e32 v40, v0
	v_mov_b32_e32 v41, v0
	v_mov_b32_e32 v42, v0
	v_mov_b32_e32 v43, v0
	v_mov_b32_e32 v44, v0
	v_mov_b32_e32 v45, v0
	v_mov_b32_e32 v46, v0
	v_mov_b32_e32 v47, v0
	v_mov_b32_e32 v48, v0
	v_mov_b32_e32 v49, v0
	v_mov_b32_e32 v50, v0
	v_mov_b32_e32 v51, v0
	v_mov_b32_e32 v52, v0
	v_mov_b32_e32 v53, v0
	v_mov_b32_e32 v54, v0
	v_mov_b32_e32 v55, v0
	v_mov_b32_e32 v56, v0
	v_mov_b32_e32 v57, v0
	v_mov_b32_e32 v58, v0
	v_mov_b32_e32 v59, v0
	v_mov_b32_e32 v60, v0
	v_mov_b32_e32 v61, v0
	v_mov_b32_e32 v62, v0
	v_mov_b32_e32 v63, v0
	v_mov_b32_e32 v96, v0
	v_mov_b32_e32 v97, v0
	v_mov_b32_e32 v98, v0
	v_mov_b32_e32 v99, v0
	v_mov_b32_e32 v100, v0
	v_mov_b32_e32 v101, v0
	v_mov_b32_e32 v102, v0
	v_mov_b32_e32 v103, v0
	v_mov_b32_e32 v104, v0
	v_mov_b32_e32 v105, v0
	v_mov_b32_e32 v106, v0
	v_mov_b32_e32 v107, v0
	v_mov_b32_e32 v108, v0
	v_mov_b32_e32 v109, v0
	v_mov_b32_e32 v110, v0
	v_mov_b32_e32 v111, v0
	v_mov_b32_e32 v112, v0
	v_mov_b32_e32 v113, v0
	v_mov_b32_e32 v114, v0
	v_mov_b32_e32 v115, v0
	v_mov_b32_e32 v116, v0
	v_mov_b32_e32 v117, v0
	v_mov_b32_e32 v118, v0
	v_mov_b32_e32 v119, v0
	v_mov_b32_e32 v120, v0
	v_mov_b32_e32 v121, v0
	v_mov_b32_e32 v122, v0
	v_mov_b32_e32 v123, v0
	v_mov_b32_e32 v124, v0
	v_mov_b32_e32 v125, v0
	v_mov_b32_e32 v126, v0
	v_mov_b32_e32 v127, v0
	v_readfirstlane_b32 s98, v197
	s_nop 3
	s_cmpk_gt_u32 s98, 0xff
	s_cbranch_scc0 .Lkp_5
	s_setprio 1
; #define PG8_STAGE(bufoff, gbase, voff) do { _Pragma("unroll") for (int _i = 0; _i < 2; ++_i) \
;         __builtin_amdgcn_global_load_lds((const unsigned*)((const char*)(gbase) + (voff)[_i]), (PG8_LAS unsigned*)(lds + (bufoff) + ldsw + _i * 8192), 16, 0, 0); } while (0)
; #define PG8_LDA(dst, b, h) do { _Pragma("unroll") for (int m = 0; m < 4; ++m) _Pragma("unroll") for (int k = 0; k < 2; ++k) dst[m][k] = *(const PG8_LAS bf16x8*)(lds + PG8_SA(b, h) + aoff + m * 2048 + k * 1024); } while (0)
; #define PG8_LDB(dst, b, h) do { _Pragma("unroll") for (int n = 0; n < 2; ++n) _Pragma("unroll") for (int k = 0; k < 2; ++k) dst[n][k] = *(const PG8_LAS bf16x8*)(lds + PG8_SB(b, h) + boff + n * 2048 + k * 1024); } while (0)
; #define PG8_MMA(ai, bj, At, Bt) do { __builtin_amdgcn_s_setprio(1); _Pragma("unroll") for (int m = 0; m < 4; ++m) _Pragma("unroll") for (int n = 0; n < 2; ++n) _Pragma("unroll") for (int k = 0; k < 2; ++k) \
;         acc[ai][bj][m][n] = __builtin_amdgcn_mfma_f32_16x16x32_bf16(Bt[n][k], At[m][k], acc[ai][bj][m][n], 0, 0, 0); __builtin_amdgcn_s_setprio(0); } while (0)
; #define PG8_WAIT_V(n) asm volatile("s_waitcnt vmcnt(" #n ")" ::: "memory")
; #define PG8_WAIT_L(n) asm volatile("s_waitcnt lgkmcnt(" #n ")" ::: "memory")
; #define PG8_BAR __builtin_amdgcn_s_barrier()
; #define PG8_SCHED __builtin_amdgcn_sched_barrier(0)
; template <class Epi, class Sched, bool ALIGN_EPI = false, bool SP2 = false>
; __device__ __forceinline__ void gemm_phase(PG8_LAS unsigned char* lds, const Gemm g, const Sched& S, const Epi& E) {
;     ...
;             PG8_LDB(B0, 0, 0); PG8_LDB(B1, 0, 1); PG8_SCHED; PG8_LDA(At, 0, 0); PG8_STAGE(PG8_SA(1, 1), a1 + hstep, voffA);
;             PG8_WAIT_V(8); PG8_WAIT_L(0); PG8_BAR; PG8_MMA(0, 0, At, B0); PG8_MMA(0, 1, At, B1); PG8_BAR; PG8_SCHED;
;             PG8_LDA(At, 0, 1); PG8_STAGE(PG8_SB(0, 0), b2, voffB); PG8_STAGE(PG8_SB(0, 1), b2 + hstep, voffB); PG8_STAGE(PG8_SA(0, 0), a2, voffA);
;             PG8_WAIT_V(8); PG8_WAIT_L(0); PG8_BAR; PG8_MMA(1, 0, At, B0); PG8_MMA(1, 1, At, B1); PG8_BAR; PG8_SCHED;
.Lkp_5:
.LBB0_706:
	ds_read_b128 v[164:167], v161
	ds_read_b128 v[168:171], v161 offset:1024
	ds_read_b128 v[172:175], v161 offset:2048
	ds_read_b128 v[176:179], v161 offset:3072
	ds_read_b128 v[180:183], v162
	ds_read_b128 v[184:187], v162 offset:1024
	ds_read_b128 v[188:191], v162 offset:2048
	ds_read_b128 v[192:195], v162 offset:3072
	s_add_i32 s54, s26, 2
	s_add_u32 s55, s24, 0x80
	s_addc_u32 s27, s25, 0
	s_cmp_eq_u32 s43, s26
	s_cselect_b32 s26, s4, s55
	s_cselect_b32 s27, s5, s27
	s_cselect_b32 s57, s23, s53
	s_cselect_b32 s56, s22, s52
	s_mov_b32 m0, s47
	v_lshl_add_u64 v[230:231], s[24:25], 0, v[136:137]
	ds_read_b128 v[198:201], v163
	ds_read_b128 v[202:205], v163 offset:1024
	ds_read_b128 v[206:209], v163 offset:2048
	ds_read_b128 v[210:213], v163 offset:3072
	ds_read_b128 v[214:217], v163 offset:4096
	ds_read_b128 v[218:221], v163 offset:5120
	ds_read_b128 v[222:225], v163 offset:6144
	ds_read_b128 v[226:229], v163 offset:7168
	global_load_lds_dwordx4 v[230:231], off
	v_lshl_add_u64 v[230:231], s[24:25], 0, v[138:139]
	s_add_i32 m0, s35, 0xe000
	s_nop 0
	global_load_lds_dwordx4 v[230:231], off
	s_waitcnt vmcnt(8)
	s_waitcnt lgkmcnt(0)
	s_barrier
	s_waitcnt lgkmcnt(0)
	v_mfma_f32_16x16x32_bf16 v[124:127], v[164:167], v[198:201], v[124:127]
	v_mfma_f32_16x16x32_bf16 v[120:123], v[172:175], v[198:201], v[120:123]
	v_mfma_f32_16x16x32_bf16 v[116:119], v[164:167], v[206:209], v[116:119]
	v_mfma_f32_16x16x32_bf16 v[112:115], v[172:175], v[206:209], v[112:115]
	v_mfma_f32_16x16x32_bf16 v[108:111], v[164:167], v[214:217], v[108:111]
	v_mfma_f32_16x16x32_bf16 v[104:107], v[172:175], v[214:217], v[104:107]
	v_mfma_f32_16x16x32_bf16 v[100:103], v[164:167], v[222:225], v[100:103]
	v_mfma_f32_16x16x32_bf16 v[96:99], v[172:175], v[222:225], v[96:99]
	v_mfma_f32_16x16x32_bf16 v[124:127], v[168:171], v[202:205], v[124:127]
	v_mfma_f32_16x16x32_bf16 v[120:123], v[176:179], v[202:205], v[120:123]
	v_mfma_f32_16x16x32_bf16 v[116:119], v[168:171], v[210:213], v[116:119]
	v_mfma_f32_16x16x32_bf16 v[112:115], v[176:179], v[210:213], v[112:115]
	v_mfma_f32_16x16x32_bf16 v[108:111], v[168:171], v[218:221], v[108:111]
	v_mfma_f32_16x16x32_bf16 v[104:107], v[176:179], v[218:221], v[104:107]
	v_mfma_f32_16x16x32_bf16 v[100:103], v[168:171], v[226:229], v[100:103]
	v_mfma_f32_16x16x32_bf16 v[96:99], v[176:179], v[226:229], v[96:99]
	v_mfma_f32_16x16x32_bf16 v[60:63], v[180:183], v[198:201], v[60:63]
	v_mfma_f32_16x16x32_bf16 v[56:59], v[188:191], v[198:201], v[56:59]
	v_mfma_f32_16x16x32_bf16 v[52:55], v[180:183], v[206:209], v[52:55]
	v_mfma_f32_16x16x32_bf16 v[48:51], v[188:191], v[206:209], v[48:51]
	v_mfma_f32_16x16x32_bf16 v[44:47], v[180:183], v[214:217], v[44:47]
	v_mfma_f32_16x16x32_bf16 v[40:43], v[188:191], v[214:217], v[40:43]
	v_mfma_f32_16x16x32_bf16 v[36:39], v[180:183], v[222:225], v[36:39]
	v_mfma_f32_16x16x32_bf16 v[32:35], v[188:191], v[222:225], v[32:35]
	v_mfma_f32_16x16x32_bf16 v[60:63], v[184:187], v[202:205], v[60:63]
	v_mfma_f32_16x16x32_bf16 v[56:59], v[192:195], v[202:205], v[56:59]
	v_mfma_f32_16x16x32_bf16 v[52:55], v[184:187], v[210:213], v[52:55]
	v_mfma_f32_16x16x32_bf16 v[48:51], v[192:195], v[210:213], v[48:51]
	v_mfma_f32_16x16x32_bf16 v[44:47], v[184:187], v[218:221], v[44:47]
	v_mfma_f32_16x16x32_bf16 v[40:43], v[192:195], v[218:221], v[40:43]
	v_mfma_f32_16x16x32_bf16 v[36:39], v[184:187], v[226:229], v[36:39]
	v_mfma_f32_16x16x32_bf16 v[32:35], v[192:195], v[226:229], v[32:35]
	s_barrier
	s_add_i32 s55, s44, s34
	v_lshl_add_u64 v[230:231], s[56:57], 0, v[132:133]
	s_mov_b32 m0, s55
	ds_read_b128 v[198:201], v163 offset:16384
	ds_read_b128 v[202:205], v163 offset:17408
	ds_read_b128 v[206:209], v163 offset:18432
	ds_read_b128 v[210:213], v163 offset:19456
	ds_read_b128 v[214:217], v163 offset:20480
	ds_read_b128 v[218:221], v163 offset:21504
	ds_read_b128 v[222:225], v163 offset:22528
	ds_read_b128 v[226:229], v163 offset:23552
	global_load_lds_dwordx4 v[230:231], off
	s_add_i32 m0, s55, 0x2000
	v_lshl_add_u64 v[232:233], s[56:57], 0, v[128:129]
	s_add_u32 s56, s56, s10
	s_addc_u32 s57, s57, s11
	s_add_i32 s55, s45, s34
	global_load_lds_dwordx4 v[232:233], off
	v_lshl_add_u64 v[234:235], s[56:57], 0, v[132:133]
	s_mov_b32 m0, s55
	v_lshl_add_u64 v[236:237], s[56:57], 0, v[128:129]
	global_load_lds_dwordx4 v[234:235], off
	s_add_i32 m0, s55, 0x2000
	v_lshl_add_u64 v[238:239], s[26:27], 0, v[134:135]
	global_load_lds_dwordx4 v[236:237], off
	s_mov_b32 m0, s35
	v_lshl_add_u64 v[240:241], s[26:27], 0, v[130:131]
	global_load_lds_dwordx4 v[238:239], off
	s_mov_b32 m0, s36
	s_nop 0
	global_load_lds_dwordx4 v[240:241], off
	s_waitcnt vmcnt(8)
	s_waitcnt lgkmcnt(0)
	s_barrier
; #define PG8_STAGE(bufoff, gbase, voff) do { _Pragma("unroll") for (int _i = 0; _i < 2; ++_i) \
;         __builtin_amdgcn_global_load_lds((const unsigned*)((const char*)(gbase) + (voff)[_i]), (PG8_LAS unsigned*)(lds + (bufoff) + ldsw + _i * 8192), 16, 0, 0); } while (0)
; #define PG8_LDA(dst, b, h) do { _Pragma("unroll") for (int m = 0; m < 4; ++m) _Pragma("unroll") for (int k = 0; k < 2; ++k) dst[m][k] = *(const PG8_LAS bf16x8*)(lds + PG8_SA(b, h) + aoff + m * 2048 + k * 1024); } while (0)
; #define PG8_LDB(dst, b, h) do { _Pragma("unroll") for (int n = 0; n < 2; ++n) _Pragma("unroll") for (int k = 0; k < 2; ++k) dst[n][k] = *(const PG8_LAS bf16x8*)(lds + PG8_SB(b, h) + boff + n * 2048 + k * 1024); } while (0)
; #define PG8_MMA(ai, bj, At, Bt) do { __builtin_amdgcn_s_setprio(1); _Pragma("unroll") for (int m = 0; m < 4; ++m) _Pragma("unroll") for (int n = 0; n < 2; ++n) _Pragma("unroll") for (int k = 0; k < 2; ++k) \
;         acc[ai][bj][m][n] = __builtin_amdgcn_mfma_f32_16x16x32_bf16(Bt[n][k], At[m][k], acc[ai][bj][m][n], 0, 0, 0); __builtin_amdgcn_s_setprio(0); } while (0)
; #define PG8_WAIT_V(n) asm volatile("s_waitcnt vmcnt(" #n ")" ::: "memory")
; #define PG8_WAIT_L(n) asm volatile("s_waitcnt lgkmcnt(" #n ")" ::: "memory")
; #define PG8_BAR __builtin_amdgcn_s_barrier()
; #define PG8_SCHED __builtin_amdgcn_sched_barrier(0)
; template <class Epi, class Sched, bool ALIGN_EPI = false, bool SP2 = false>
; __device__ __forceinline__ void gemm_phase(PG8_LAS unsigned char* lds, const Gemm g, const Sched& S, const Epi& E) {
;     ...
;             PG8_WAIT_V(8); PG8_WAIT_L(0); PG8_BAR; PG8_MMA(1, 0, At, B0); PG8_MMA(1, 1, At, B1); PG8_BAR; PG8_SCHED;
;             PG8_LDB(B0, 1, 0); PG8_LDB(B1, 1, 1); PG8_SCHED; PG8_LDA(At, 1, 0); PG8_STAGE(PG8_SA(0, 1), a2 + hstep, voffA);
;             PG8_WAIT_V(8); PG8_WAIT_L(0); PG8_BAR; PG8_MMA(0, 0, At, B0); PG8_MMA(0, 1, At, B1); PG8_BAR; PG8_SCHED;
	s_waitcnt lgkmcnt(0)
	v_mfma_f32_16x16x32_bf16 v[92:95], v[164:167], v[198:201], v[92:95]
	v_mfma_f32_16x16x32_bf16 v[88:91], v[172:175], v[198:201], v[88:91]
	v_mfma_f32_16x16x32_bf16 v[84:87], v[164:167], v[206:209], v[84:87]
	v_mfma_f32_16x16x32_bf16 v[80:83], v[172:175], v[206:209], v[80:83]
	v_mfma_f32_16x16x32_bf16 v[76:79], v[164:167], v[214:217], v[76:79]
	v_mfma_f32_16x16x32_bf16 v[72:75], v[172:175], v[214:217], v[72:75]
	v_mfma_f32_16x16x32_bf16 v[68:71], v[164:167], v[222:225], v[68:71]
	v_mfma_f32_16x16x32_bf16 v[64:67], v[172:175], v[222:225], v[64:67]
	v_mfma_f32_16x16x32_bf16 v[92:95], v[168:171], v[202:205], v[92:95]
	v_mfma_f32_16x16x32_bf16 v[88:91], v[176:179], v[202:205], v[88:91]
	v_mfma_f32_16x16x32_bf16 v[84:87], v[168:171], v[210:213], v[84:87]
	v_mfma_f32_16x16x32_bf16 v[80:83], v[176:179], v[210:213], v[80:83]
	v_mfma_f32_16x16x32_bf16 v[76:79], v[168:171], v[218:221], v[76:79]
	v_mfma_f32_16x16x32_bf16 v[72:75], v[176:179], v[218:221], v[72:75]
	v_mfma_f32_16x16x32_bf16 v[68:71], v[168:171], v[226:229], v[68:71]
	v_mfma_f32_16x16x32_bf16 v[64:67], v[176:179], v[226:229], v[64:67]
	v_mfma_f32_16x16x32_bf16 v[28:31], v[180:183], v[198:201], v[28:31]
	v_mfma_f32_16x16x32_bf16 v[24:27], v[188:191], v[198:201], v[24:27]
	v_mfma_f32_16x16x32_bf16 v[20:23], v[180:183], v[206:209], v[20:23]
	v_mfma_f32_16x16x32_bf16 v[16:19], v[188:191], v[206:209], v[16:19]
	v_mfma_f32_16x16x32_bf16 v[12:15], v[180:183], v[214:217], v[12:15]
	v_mfma_f32_16x16x32_bf16 v[8:11], v[188:191], v[214:217], v[8:11]
	v_mfma_f32_16x16x32_bf16 v[4:7], v[180:183], v[222:225], v[4:7]
	v_mfma_f32_16x16x32_bf16 v[0:3], v[188:191], v[222:225], v[0:3]
	v_mfma_f32_16x16x32_bf16 v[28:31], v[184:187], v[202:205], v[28:31]
	v_mfma_f32_16x16x32_bf16 v[24:27], v[192:195], v[202:205], v[24:27]
	v_mfma_f32_16x16x32_bf16 v[20:23], v[184:187], v[210:213], v[20:23]
	v_mfma_f32_16x16x32_bf16 v[16:19], v[192:195], v[210:213], v[16:19]
	v_mfma_f32_16x16x32_bf16 v[12:15], v[184:187], v[218:221], v[12:15]
	v_mfma_f32_16x16x32_bf16 v[8:11], v[192:195], v[218:221], v[8:11]
	v_mfma_f32_16x16x32_bf16 v[4:7], v[184:187], v[226:229], v[4:7]
	v_mfma_f32_16x16x32_bf16 v[0:3], v[192:195], v[226:229], v[0:3]
	s_barrier
	s_add_i32 s55, 0, 0x18000
	s_add_i32 s56, 0, 0x1c000
	v_add_u32_e32 v176, s55, v145
	v_add_u32_e32 v192, s56, v145
	ds_read_b128 v[164:167], v176
	ds_read_b128 v[168:171], v176 offset:1024
	ds_read_b128 v[172:175], v176 offset:2048
	ds_read_b128 v[176:179], v176 offset:3072
	ds_read_b128 v[180:183], v192
	ds_read_b128 v[184:187], v192 offset:1024
	ds_read_b128 v[188:191], v192 offset:2048
	ds_read_b128 v[192:195], v192 offset:3072
	s_add_u32 s26, s26, s10
	s_addc_u32 s27, s27, s11
	s_mov_b32 m0, s37
	v_lshl_add_u64 v[242:243], s[26:27], 0, v[134:135]
	ds_read_b128 v[198:201], v163 offset:32768
	ds_read_b128 v[202:205], v163 offset:33792
	ds_read_b128 v[206:209], v163 offset:34816
	ds_read_b128 v[210:213], v163 offset:35840
	ds_read_b128 v[214:217], v163 offset:36864
	ds_read_b128 v[218:221], v163 offset:37888
	ds_read_b128 v[222:225], v163 offset:38912
	ds_read_b128 v[226:229], v163 offset:39936
	global_load_lds_dwordx4 v[242:243], off
	v_lshl_add_u64 v[242:243], s[26:27], 0, v[130:131]
	s_mov_b32 m0, s38
	s_nop 0
	global_load_lds_dwordx4 v[242:243], off
	s_waitcnt vmcnt(8)
	s_waitcnt lgkmcnt(0)
	s_barrier
	s_waitcnt lgkmcnt(0)
	v_mfma_f32_16x16x32_bf16 v[124:127], v[164:167], v[198:201], v[124:127]
	v_mfma_f32_16x16x32_bf16 v[120:123], v[172:175], v[198:201], v[120:123]
	v_mfma_f32_16x16x32_bf16 v[116:119], v[164:167], v[206:209], v[116:119]
	v_mfma_f32_16x16x32_bf16 v[112:115], v[172:175], v[206:209], v[112:115]
	v_mfma_f32_16x16x32_bf16 v[108:111], v[164:167], v[214:217], v[108:111]
	v_mfma_f32_16x16x32_bf16 v[104:107], v[172:175], v[214:217], v[104:107]
	v_mfma_f32_16x16x32_bf16 v[100:103], v[164:167], v[222:225], v[100:103]
	v_mfma_f32_16x16x32_bf16 v[96:99], v[172:175], v[222:225], v[96:99]
	v_mfma_f32_16x16x32_bf16 v[124:127], v[168:171], v[202:205], v[124:127]
	v_mfma_f32_16x16x32_bf16 v[120:123], v[176:179], v[202:205], v[120:123]
	v_mfma_f32_16x16x32_bf16 v[116:119], v[168:171], v[210:213], v[116:119]
	v_mfma_f32_16x16x32_bf16 v[112:115], v[176:179], v[210:213], v[112:115]
	v_mfma_f32_16x16x32_bf16 v[108:111], v[168:171], v[218:221], v[108:111]
	v_mfma_f32_16x16x32_bf16 v[104:107], v[176:179], v[218:221], v[104:107]
	v_mfma_f32_16x16x32_bf16 v[100:103], v[168:171], v[226:229], v[100:103]
	v_mfma_f32_16x16x32_bf16 v[96:99], v[176:179], v[226:229], v[96:99]
	v_mfma_f32_16x16x32_bf16 v[60:63], v[180:183], v[198:201], v[60:63]
	v_mfma_f32_16x16x32_bf16 v[56:59], v[188:191], v[198:201], v[56:59]
	v_mfma_f32_16x16x32_bf16 v[52:55], v[180:183], v[206:209], v[52:55]
	v_mfma_f32_16x16x32_bf16 v[48:51], v[188:191], v[206:209], v[48:51]
	v_mfma_f32_16x16x32_bf16 v[44:47], v[180:183], v[214:217], v[44:47]
	v_mfma_f32_16x16x32_bf16 v[40:43], v[188:191], v[214:217], v[40:43]
	v_mfma_f32_16x16x32_bf16 v[36:39], v[180:183], v[222:225], v[36:39]
	v_mfma_f32_16x16x32_bf16 v[32:35], v[188:191], v[222:225], v[32:35]
	v_mfma_f32_16x16x32_bf16 v[60:63], v[184:187], v[202:205], v[60:63]
	v_mfma_f32_16x16x32_bf16 v[56:59], v[192:195], v[202:205], v[56:59]
	v_mfma_f32_16x16x32_bf16 v[52:55], v[184:187], v[210:213], v[52:55]
	v_mfma_f32_16x16x32_bf16 v[48:51], v[192:195], v[210:213], v[48:51]
	v_mfma_f32_16x16x32_bf16 v[44:47], v[184:187], v[218:221], v[44:47]
	v_mfma_f32_16x16x32_bf16 v[40:43], v[192:195], v[218:221], v[40:43]
	v_mfma_f32_16x16x32_bf16 v[36:39], v[184:187], v[226:229], v[36:39]
	v_mfma_f32_16x16x32_bf16 v[32:35], v[192:195], v[226:229], v[32:35]
	s_barrier
; #define PG8_STAGE(bufoff, gbase, voff) do { _Pragma("unroll") for (int _i = 0; _i < 2; ++_i) \
;         __builtin_amdgcn_global_load_lds((const unsigned*)((const char*)(gbase) + (voff)[_i]), (PG8_LAS unsigned*)(lds + (bufoff) + ldsw + _i * 8192), 16, 0, 0); } while (0)
; #define PG8_LDA(dst, b, h) do { _Pragma("unroll") for (int m = 0; m < 4; ++m) _Pragma("unroll") for (int k = 0; k < 2; ++k) dst[m][k] = *(const PG8_LAS bf16x8*)(lds + PG8_SA(b, h) + aoff + m * 2048 + k * 1024); } while (0)
; #define PG8_MMA(ai, bj, At, Bt) do { __builtin_amdgcn_s_setprio(1); _Pragma("unroll") for (int m = 0; m < 4; ++m) _Pragma("unroll") for (int n = 0; n < 2; ++n) _Pragma("unroll") for (int k = 0; k < 2; ++k) \
;         acc[ai][bj][m][n] = __builtin_amdgcn_mfma_f32_16x16x32_bf16(Bt[n][k], At[m][k], acc[ai][bj][m][n], 0, 0, 0); __builtin_amdgcn_s_setprio(0); } while (0)
; #define PG8_WAIT_V(n) asm volatile("s_waitcnt vmcnt(" #n ")" ::: "memory")
; #define PG8_WAIT_L(n) asm volatile("s_waitcnt lgkmcnt(" #n ")" ::: "memory")
; #define PG8_BAR __builtin_amdgcn_s_barrier()
; #define PG8_SCHED __builtin_amdgcn_sched_barrier(0)
; template <class Epi, class Sched, bool ALIGN_EPI = false, bool SP2 = false>
; __device__ __forceinline__ void gemm_phase(PG8_LAS unsigned char* lds, const Gemm g, const Sched& S, const Epi& E) {
;     ...
;         for (int t = 0; t < nt; t += 2) {
;     ...
;             PG8_LDA(At, 1, 1); PG8_STAGE(PG8_SB(1, 0), b3, voffB); PG8_STAGE(PG8_SB(1, 1), b3 + hstep, voffB); PG8_STAGE(PG8_SA(1, 0), a3, voffA);
;             PG8_WAIT_V(8); PG8_WAIT_L(0); PG8_BAR; PG8_MMA(1, 0, At, B0); PG8_MMA(1, 1, At, B1); PG8_BAR; PG8_SCHED;
	s_add_i32 s26, s55, s34
	v_lshl_add_u64 v[230:231], v[230:231], 0, s[18:19]
	s_mov_b32 m0, s26
	ds_read_b128 v[198:201], v163 offset:49152
	ds_read_b128 v[202:205], v163 offset:50176
	ds_read_b128 v[206:209], v163 offset:51200
	ds_read_b128 v[210:213], v163 offset:52224
	ds_read_b128 v[214:217], v163 offset:53248
	ds_read_b128 v[218:221], v163 offset:54272
	ds_read_b128 v[222:225], v163 offset:55296
	ds_read_b128 v[226:229], v163 offset:56320
	global_load_lds_dwordx4 v[230:231], off
	v_lshl_add_u64 v[230:231], v[232:233], 0, s[18:19]
	s_add_i32 m0, s26, 0x2000
	s_add_i32 s26, s56, s34
	global_load_lds_dwordx4 v[230:231], off
	v_lshl_add_u64 v[230:231], v[234:235], 0, s[18:19]
	s_mov_b32 m0, s26
	s_nop 0
	global_load_lds_dwordx4 v[230:231], off
	v_lshl_add_u64 v[230:231], v[236:237], 0, s[18:19]
	s_add_i32 m0, s26, 0x2000
	s_nop 0
	global_load_lds_dwordx4 v[230:231], off
	v_lshl_add_u64 v[230:231], v[238:239], 0, s[18:19]
	s_mov_b32 m0, s39
	s_nop 0
	global_load_lds_dwordx4 v[230:231], off
	v_lshl_add_u64 v[230:231], v[240:241], 0, s[18:19]
	s_mov_b32 m0, s40
	s_nop 0
	global_load_lds_dwordx4 v[230:231], off
	s_waitcnt vmcnt(8)
	s_waitcnt lgkmcnt(0)
	s_barrier
	s_waitcnt lgkmcnt(0)
	v_mfma_f32_16x16x32_bf16 v[92:95], v[164:167], v[198:201], v[92:95]
	v_mfma_f32_16x16x32_bf16 v[88:91], v[172:175], v[198:201], v[88:91]
	v_mfma_f32_16x16x32_bf16 v[84:87], v[164:167], v[206:209], v[84:87]
	v_mfma_f32_16x16x32_bf16 v[80:83], v[172:175], v[206:209], v[80:83]
	v_mfma_f32_16x16x32_bf16 v[76:79], v[164:167], v[214:217], v[76:79]
	v_mfma_f32_16x16x32_bf16 v[72:75], v[172:175], v[214:217], v[72:75]
	v_mfma_f32_16x16x32_bf16 v[68:71], v[164:167], v[222:225], v[68:71]
	v_mfma_f32_16x16x32_bf16 v[64:67], v[172:175], v[222:225], v[64:67]
	v_mfma_f32_16x16x32_bf16 v[92:95], v[168:171], v[202:205], v[92:95]
	v_mfma_f32_16x16x32_bf16 v[88:91], v[176:179], v[202:205], v[88:91]
	v_mfma_f32_16x16x32_bf16 v[84:87], v[168:171], v[210:213], v[84:87]
	v_mfma_f32_16x16x32_bf16 v[80:83], v[176:179], v[210:213], v[80:83]
	v_mfma_f32_16x16x32_bf16 v[76:79], v[168:171], v[218:221], v[76:79]
	v_mfma_f32_16x16x32_bf16 v[72:75], v[176:179], v[218:221], v[72:75]
	v_mfma_f32_16x16x32_bf16 v[68:71], v[168:171], v[226:229], v[68:71]
	v_mfma_f32_16x16x32_bf16 v[64:67], v[176:179], v[226:229], v[64:67]
	v_mfma_f32_16x16x32_bf16 v[28:31], v[180:183], v[198:201], v[28:31]
	v_mfma_f32_16x16x32_bf16 v[24:27], v[188:191], v[198:201], v[24:27]
	v_mfma_f32_16x16x32_bf16 v[20:23], v[180:183], v[206:209], v[20:23]
	v_mfma_f32_16x16x32_bf16 v[16:19], v[188:191], v[206:209], v[16:19]
	v_mfma_f32_16x16x32_bf16 v[12:15], v[180:183], v[214:217], v[12:15]
	v_mfma_f32_16x16x32_bf16 v[8:11], v[188:191], v[214:217], v[8:11]
	v_mfma_f32_16x16x32_bf16 v[4:7], v[180:183], v[222:225], v[4:7]
	v_mfma_f32_16x16x32_bf16 v[0:3], v[188:191], v[222:225], v[0:3]
	v_mfma_f32_16x16x32_bf16 v[28:31], v[184:187], v[202:205], v[28:31]
	v_mfma_f32_16x16x32_bf16 v[24:27], v[192:195], v[202:205], v[24:27]
	v_mfma_f32_16x16x32_bf16 v[20:23], v[184:187], v[210:213], v[20:23]
	v_mfma_f32_16x16x32_bf16 v[16:19], v[192:195], v[210:213], v[16:19]
	v_mfma_f32_16x16x32_bf16 v[12:15], v[184:187], v[218:221], v[12:15]
	v_mfma_f32_16x16x32_bf16 v[8:11], v[192:195], v[218:221], v[8:11]
	v_mfma_f32_16x16x32_bf16 v[4:7], v[184:187], v[226:229], v[4:7]
	v_mfma_f32_16x16x32_bf16 v[0:3], v[192:195], v[226:229], v[0:3]
	s_barrier
	s_add_u32 s24, s24, 0x100
	s_addc_u32 s25, s25, 0
	s_add_u32 s52, s52, 0x100
	s_addc_u32 s53, s53, 0
	s_cmp_ge_i32 s54, s41
	s_mov_b32 s26, s54
	s_cbranch_scc0 .LBB0_706
	s_setprio 0

; template <class Epi, class Sched, bool ALIGN_EPI = false, bool SP2 = false>
; __device__ __forceinline__ void gemm_phase(PG8_LAS unsigned char* lds, const Gemm g, const Sched& S, const Epi& E) {
;     ...
;     f32x4 acc[2][2][4][2];
; #pragma unroll
;     for (int a = 0; a < 2; ++a)
; #pragma unroll
;         for (int b = 0; b < 2; ++b)
; #pragma unroll
;             for (int m = 0; m < 4; ++m)
; #pragma unroll
;                 for (int n = 0; n < 2; ++n) acc[a][b][m][n] = (f32x4){0.f, 0.f, 0.f, 0.f};
;     ...
;         for (int t = 0; t < nt; t += 2) {
;             const bool last = (t == nt - 2);
;             const char* a1 = cA + (size_t)(t + 1) * kstep;
;             const char* a2 = last ? nA : cA + (size_t)(t + 2) * kstep; const char* b2 = last ? nB : cB + (size_t)(t + 2) * kstep;
;             const char* a3 = a2 + kstep; const char* b3 = b2 + kstep;
;             if (last && has_next) S.a_ready(nxt);
.LBB0_729:
	v_mov_b32_e32 v127, 0
	s_and_b64 vcc, exec, s[0:1]
	v_mov_b32_e32 v126, v127
	v_mov_b32_e32 v125, v127
	v_mov_b32_e32 v124, v127
	v_mov_b32_e32 v123, v127
	v_mov_b32_e32 v122, v127
	v_mov_b32_e32 v121, v127
	v_mov_b32_e32 v120, v127
	v_mov_b32_e32 v119, v127
	v_mov_b32_e32 v118, v127
	v_mov_b32_e32 v117, v127
	v_mov_b32_e32 v116, v127
	v_mov_b32_e32 v115, v127
	v_mov_b32_e32 v114, v127
	v_mov_b32_e32 v113, v127
	v_mov_b32_e32 v112, v127
	v_mov_b32_e32 v111, v127
	v_mov_b32_e32 v110, v127
	v_mov_b32_e32 v109, v127
	v_mov_b32_e32 v108, v127
	v_mov_b32_e32 v107, v127
	v_mov_b32_e32 v106, v127
	v_mov_b32_e32 v105, v127
	v_mov_b32_e32 v104, v127
	v_mov_b32_e32 v103, v127
	v_mov_b32_e32 v102, v127
	v_mov_b32_e32 v101, v127
	v_mov_b32_e32 v100, v127
	v_mov_b32_e32 v99, v127
	v_mov_b32_e32 v98, v127
	v_mov_b32_e32 v97, v127
	v_mov_b32_e32 v96, v127
	v_mov_b32_e32 v63, v127
	v_mov_b32_e32 v62, v127
	v_mov_b32_e32 v61, v127
	v_mov_b32_e32 v60, v127
	v_mov_b32_e32 v59, v127
	v_mov_b32_e32 v58, v127
	v_mov_b32_e32 v57, v127
	v_mov_b32_e32 v56, v127
	v_mov_b32_e32 v55, v127
	v_mov_b32_e32 v54, v127
	v_mov_b32_e32 v53, v127
	v_mov_b32_e32 v52, v127
	v_mov_b32_e32 v51, v127
	v_mov_b32_e32 v50, v127
	v_mov_b32_e32 v49, v127
	v_mov_b32_e32 v48, v127
	v_mov_b32_e32 v47, v127
	v_mov_b32_e32 v46, v127
	v_mov_b32_e32 v45, v127
	v_mov_b32_e32 v44, v127
	v_mov_b32_e32 v43, v127
	v_mov_b32_e32 v42, v127
	v_mov_b32_e32 v41, v127
	v_mov_b32_e32 v40, v127
	v_mov_b32_e32 v39, v127
	v_mov_b32_e32 v38, v127
	v_mov_b32_e32 v37, v127
	v_mov_b32_e32 v36, v127
	v_mov_b32_e32 v35, v127
	v_mov_b32_e32 v34, v127
	v_mov_b32_e32 v33, v127
	v_mov_b32_e32 v32, v127
	v_mov_b32_e32 v95, v127
	v_mov_b32_e32 v94, v127
	v_mov_b32_e32 v93, v127
	v_mov_b32_e32 v92, v127
	v_mov_b32_e32 v91, v127
	v_mov_b32_e32 v90, v127
	v_mov_b32_e32 v89, v127
	v_mov_b32_e32 v88, v127
	v_mov_b32_e32 v87, v127
	v_mov_b32_e32 v86, v127
	v_mov_b32_e32 v85, v127
	v_mov_b32_e32 v84, v127
	v_mov_b32_e32 v83, v127
	v_mov_b32_e32 v82, v127
	v_mov_b32_e32 v81, v127
	v_mov_b32_e32 v80, v127
	v_mov_b32_e32 v79, v127
	v_mov_b32_e32 v78, v127
	v_mov_b32_e32 v77, v127
	v_mov_b32_e32 v76, v127
	v_mov_b32_e32 v75, v127
	v_mov_b32_e32 v74, v127
	v_mov_b32_e32 v73, v127
	v_mov_b32_e32 v72, v127
	v_mov_b32_e32 v71, v127
	v_mov_b32_e32 v70, v127
	v_mov_b32_e32 v69, v127
	v_mov_b32_e32 v68, v127
	v_mov_b32_e32 v67, v127
	v_mov_b32_e32 v66, v127
	v_mov_b32_e32 v65, v127
	v_mov_b32_e32 v64, v127
	v_mov_b32_e32 v31, v127
	v_mov_b32_e32 v30, v127
	v_mov_b32_e32 v29, v127
	v_mov_b32_e32 v28, v127
	v_mov_b32_e32 v27, v127
	v_mov_b32_e32 v26, v127
	v_mov_b32_e32 v25, v127
	v_mov_b32_e32 v24, v127
	v_mov_b32_e32 v23, v127
	v_mov_b32_e32 v22, v127
	v_mov_b32_e32 v21, v127
	v_mov_b32_e32 v20, v127
	v_mov_b32_e32 v19, v127
	v_mov_b32_e32 v18, v127
	v_mov_b32_e32 v17, v127
	v_mov_b32_e32 v16, v127
	v_mov_b32_e32 v15, v127
	v_mov_b32_e32 v14, v127
	v_mov_b32_e32 v13, v127
	v_mov_b32_e32 v12, v127
	v_mov_b32_e32 v11, v127
	v_mov_b32_e32 v10, v127
	v_mov_b32_e32 v9, v127
	v_mov_b32_e32 v8, v127
	v_mov_b32_e32 v7, v127
	v_mov_b32_e32 v6, v127
	v_mov_b32_e32 v5, v127
	v_mov_b32_e32 v4, v127
	v_mov_b32_e32 v3, v127
	v_mov_b32_e32 v2, v127
	v_mov_b32_e32 v1, v127
	v_mov_b32_e32 v0, v127
	s_cbranch_vccnz .LBB0_732
	s_add_u32 s22, s22, 0x80
	s_addc_u32 s23, s23, 0
	s_add_u32 s48, s24, 0x100
	v_mov_b32_e32 v0, 0
	s_addc_u32 s49, s25, 0
	s_mov_b32 s24, 0
	v_mov_b32_e32 v1, v0
	v_mov_b32_e32 v2, v0
	v_mov_b32_e32 v3, v0
	v_mov_b32_e32 v4, v0
	v_mov_b32_e32 v5, v0
	v_mov_b32_e32 v6, v0
	v_mov_b32_e32 v7, v0
	v_mov_b32_e32 v8, v0
	v_mov_b32_e32 v9, v0
	v_mov_b32_e32 v10, v0
	v_mov_b32_e32 v11, v0
	v_mov_b32_e32 v12, v0
	v_mov_b32_e32 v13, v0
	v_mov_b32_e32 v14, v0
	v_mov_b32_e32 v15, v0
	v_mov_b32_e32 v16, v0
	v_mov_b32_e32 v17, v0
	v_mov_b32_e32 v18, v0
	v_mov_b32_e32 v19, v0
	v_mov_b32_e32 v20, v0
	v_mov_b32_e32 v21, v0
	v_mov_b32_e32 v22, v0
	v_mov_b32_e32 v23, v0
	v_mov_b32_e32 v24, v0
	v_mov_b32_e32 v25, v0
	v_mov_b32_e32 v26, v0
	v_mov_b32_e32 v27, v0
	v_mov_b32_e32 v28, v0
	v_mov_b32_e32 v29, v0
	v_mov_b32_e32 v30, v0
	v_mov_b32_e32 v31, v0
	v_mov_b32_e32 v64, v0
	v_mov_b32_e32 v65, v0
	v_mov_b32_e32 v66, v0
	v_mov_b32_e32 v67, v0
	v_mov_b32_e32 v68, v0
	v_mov_b32_e32 v69, v0
	v_mov_b32_e32 v70, v0
	v_mov_b32_e32 v71, v0
	v_mov_b32_e32 v72, v0
	v_mov_b32_e32 v73, v0
	v_mov_b32_e32 v74, v0
	v_mov_b32_e32 v75, v0
	v_mov_b32_e32 v76, v0
	v_mov_b32_e32 v77, v0
	v_mov_b32_e32 v78, v0
	v_mov_b32_e32 v79, v0
	v_mov_b32_e32 v80, v0
	v_mov_b32_e32 v81, v0
	v_mov_b32_e32 v82, v0
	v_mov_b32_e32 v83, v0
	v_mov_b32_e32 v84, v0
	v_mov_b32_e32 v85, v0
	v_mov_b32_e32 v86, v0
	v_mov_b32_e32 v87, v0
	v_mov_b32_e32 v88, v0
	v_mov_b32_e32 v89, v0
	v_mov_b32_e32 v90, v0
	v_mov_b32_e32 v91, v0
	v_mov_b32_e32 v92, v0
	v_mov_b32_e32 v93, v0
	v_mov_b32_e32 v94, v0
	v_mov_b32_e32 v95, v0
	v_mov_b32_e32 v32, v0
	v_mov_b32_e32 v33, v0
	v_mov_b32_e32 v34, v0
	v_mov_b32_e32 v35, v0
	v_mov_b32_e32 v36, v0
	v_mov_b32_e32 v37, v0
	v_mov_b32_e32 v38, v0
	v_mov_b32_e32 v39, v0
	v_mov_b32_e32 v40, v0
	v_mov_b32_e32 v41, v0
	v_mov_b32_e32 v42, v0
	v_mov_b32_e32 v43, v0
	v_mov_b32_e32 v44, v0
	v_mov_b32_e32 v45, v0
	v_mov_b32_e32 v46, v0
	v_mov_b32_e32 v47, v0
	v_mov_b32_e32 v48, v0
	v_mov_b32_e32 v49, v0
	v_mov_b32_e32 v50, v0
	v_mov_b32_e32 v51, v0
	v_mov_b32_e32 v52, v0
	v_mov_b32_e32 v53, v0
	v_mov_b32_e32 v54, v0
	v_mov_b32_e32 v55, v0
	v_mov_b32_e32 v56, v0
	v_mov_b32_e32 v57, v0
	v_mov_b32_e32 v58, v0
	v_mov_b32_e32 v59, v0
	v_mov_b32_e32 v60, v0
	v_mov_b32_e32 v61, v0
	v_mov_b32_e32 v62, v0
	v_mov_b32_e32 v63, v0
	v_mov_b32_e32 v96, v0
	v_mov_b32_e32 v97, v0
	v_mov_b32_e32 v98, v0
	v_mov_b32_e32 v99, v0
	v_mov_b32_e32 v100, v0
	v_mov_b32_e32 v101, v0
	v_mov_b32_e32 v102, v0
	v_mov_b32_e32 v103, v0
	v_mov_b32_e32 v104, v0
	v_mov_b32_e32 v105, v0
	v_mov_b32_e32 v106, v0
	v_mov_b32_e32 v107, v0
	v_mov_b32_e32 v108, v0
	v_mov_b32_e32 v109, v0
	v_mov_b32_e32 v110, v0
	v_mov_b32_e32 v111, v0
	v_mov_b32_e32 v112, v0
	v_mov_b32_e32 v113, v0
	v_mov_b32_e32 v114, v0
	v_mov_b32_e32 v115, v0
	v_mov_b32_e32 v116, v0
	v_mov_b32_e32 v117, v0
	v_mov_b32_e32 v118, v0
	v_mov_b32_e32 v119, v0
	v_mov_b32_e32 v120, v0
	v_mov_b32_e32 v121, v0
	v_mov_b32_e32 v122, v0
	v_mov_b32_e32 v123, v0
	v_mov_b32_e32 v124, v0
	v_mov_b32_e32 v125, v0
	v_mov_b32_e32 v126, v0
	v_mov_b32_e32 v127, v0
	v_readfirstlane_b32 s98, v197
	s_nop 3
	s_cmpk_gt_u32 s98, 0xff
	s_cbranch_scc0 .Lkp_4
	s_setprio 1
; #define PG8_STAGE(bufoff, gbase, voff) do { _Pragma("unroll") for (int _i = 0; _i < 2; ++_i) \
;         __builtin_amdgcn_global_load_lds((const unsigned*)((const char*)(gbase) + (voff)[_i]), (PG8_LAS unsigned*)(lds + (bufoff) + ldsw + _i * 8192), 16, 0, 0); } while (0)
; #define PG8_LDA(dst, b, h) do { _Pragma("unroll") for (int m = 0; m < 4; ++m) _Pragma("unroll") for (int k = 0; k < 2; ++k) dst[m][k] = *(const PG8_LAS bf16x8*)(lds + PG8_SA(b, h) + aoff + m * 2048 + k * 1024); } while (0)
; #define PG8_LDB(dst, b, h) do { _Pragma("unroll") for (int n = 0; n < 2; ++n) _Pragma("unroll") for (int k = 0; k < 2; ++k) dst[n][k] = *(const PG8_LAS bf16x8*)(lds + PG8_SB(b, h) + boff + n * 2048 + k * 1024); } while (0)
; #define PG8_MMA(ai, bj, At, Bt) do { __builtin_amdgcn_s_setprio(1); _Pragma("unroll") for (int m = 0; m < 4; ++m) _Pragma("unroll") for (int n = 0; n < 2; ++n) _Pragma("unroll") for (int k = 0; k < 2; ++k) \
;         acc[ai][bj][m][n] = __builtin_amdgcn_mfma_f32_16x16x32_bf16(Bt[n][k], At[m][k], acc[ai][bj][m][n], 0, 0, 0); __builtin_amdgcn_s_setprio(0); } while (0)
; #define PG8_WAIT_V(n) asm volatile("s_waitcnt vmcnt(" #n ")" ::: "memory")
; #define PG8_WAIT_L(n) asm volatile("s_waitcnt lgkmcnt(" #n ")" ::: "memory")
; #define PG8_BAR __builtin_amdgcn_s_barrier()
; #define PG8_SCHED __builtin_amdgcn_sched_barrier(0)
; template <class Epi, class Sched, bool ALIGN_EPI = false, bool SP2 = false>
; __device__ __forceinline__ void gemm_phase(PG8_LAS unsigned char* lds, const Gemm g, const Sched& S, const Epi& E) {
;     ...
;             PG8_LDB(B0, 0, 0); PG8_LDB(B1, 0, 1); PG8_SCHED; PG8_LDA(At, 0, 0); PG8_STAGE(PG8_SA(1, 1), a1 + hstep, voffA);
;             PG8_WAIT_V(8); PG8_WAIT_L(0); PG8_BAR; PG8_MMA(0, 0, At, B0); PG8_MMA(0, 1, At, B1); PG8_BAR; PG8_SCHED;
;             PG8_LDA(At, 0, 1); PG8_STAGE(PG8_SB(0, 0), b2, voffB); PG8_STAGE(PG8_SB(0, 1), b2 + hstep, voffB); PG8_STAGE(PG8_SA(0, 0), a2, voffA);
;             PG8_WAIT_V(8); PG8_WAIT_L(0); PG8_BAR; PG8_MMA(1, 0, At, B0); PG8_MMA(1, 1, At, B1); PG8_BAR; PG8_SCHED;
.Lkp_4:
.LBB0_731:
	ds_read_b128 v[166:169], v162
	ds_read_b128 v[170:173], v162 offset:1024
	ds_read_b128 v[174:177], v162 offset:2048
	ds_read_b128 v[178:181], v162 offset:3072
	ds_read_b128 v[182:185], v163
	ds_read_b128 v[186:189], v163 offset:1024
	ds_read_b128 v[190:193], v163 offset:2048
	ds_read_b128 v[198:201], v163 offset:3072
	s_add_i32 s50, s24, 2
	s_add_u32 s51, s22, 0x80
	s_addc_u32 s25, s23, 0
	s_cmp_eq_u32 s40, s24
	s_cselect_b32 s24, s4, s51
	s_cselect_b32 s25, s5, s25
	s_cselect_b32 s53, s21, s49
	s_cselect_b32 s52, s20, s48
	v_lshl_add_u64 v[194:195], s[22:23], 0, v[138:139]
	s_add_i32 m0, s27, 0xc000
	ds_read_b128 v[202:205], v164
	ds_read_b128 v[206:209], v164 offset:1024
	ds_read_b128 v[210:213], v164 offset:2048
	ds_read_b128 v[214:217], v164 offset:3072
	ds_read_b128 v[218:221], v164 offset:4096
	ds_read_b128 v[222:225], v164 offset:5120
	ds_read_b128 v[226:229], v164 offset:6144
	ds_read_b128 v[230:233], v164 offset:7168
	global_load_lds_dwordx4 v[194:195], off
	v_lshl_add_u64 v[194:195], s[22:23], 0, v[140:141]
	s_add_i32 m0, s27, 0xe000
	s_nop 0
	global_load_lds_dwordx4 v[194:195], off
	s_waitcnt vmcnt(8)
	s_waitcnt lgkmcnt(0)
	s_barrier
	s_waitcnt lgkmcnt(0)
	v_mfma_f32_16x16x32_bf16 v[124:127], v[166:169], v[202:205], v[124:127]
	v_mfma_f32_16x16x32_bf16 v[120:123], v[174:177], v[202:205], v[120:123]
	v_mfma_f32_16x16x32_bf16 v[116:119], v[166:169], v[210:213], v[116:119]
	v_mfma_f32_16x16x32_bf16 v[112:115], v[174:177], v[210:213], v[112:115]
	v_mfma_f32_16x16x32_bf16 v[108:111], v[166:169], v[218:221], v[108:111]
	v_mfma_f32_16x16x32_bf16 v[104:107], v[174:177], v[218:221], v[104:107]
	v_mfma_f32_16x16x32_bf16 v[100:103], v[166:169], v[226:229], v[100:103]
	v_mfma_f32_16x16x32_bf16 v[96:99], v[174:177], v[226:229], v[96:99]
	v_mfma_f32_16x16x32_bf16 v[124:127], v[170:173], v[206:209], v[124:127]
	v_mfma_f32_16x16x32_bf16 v[120:123], v[178:181], v[206:209], v[120:123]
	v_mfma_f32_16x16x32_bf16 v[116:119], v[170:173], v[214:217], v[116:119]
	v_mfma_f32_16x16x32_bf16 v[112:115], v[178:181], v[214:217], v[112:115]
	v_mfma_f32_16x16x32_bf16 v[108:111], v[170:173], v[222:225], v[108:111]
	v_mfma_f32_16x16x32_bf16 v[104:107], v[178:181], v[222:225], v[104:107]
	v_mfma_f32_16x16x32_bf16 v[100:103], v[170:173], v[230:233], v[100:103]
	v_mfma_f32_16x16x32_bf16 v[96:99], v[178:181], v[230:233], v[96:99]
	v_mfma_f32_16x16x32_bf16 v[60:63], v[182:185], v[202:205], v[60:63]
	v_mfma_f32_16x16x32_bf16 v[56:59], v[190:193], v[202:205], v[56:59]
	v_mfma_f32_16x16x32_bf16 v[52:55], v[182:185], v[210:213], v[52:55]
	v_mfma_f32_16x16x32_bf16 v[48:51], v[190:193], v[210:213], v[48:51]
	v_mfma_f32_16x16x32_bf16 v[44:47], v[182:185], v[218:221], v[44:47]
	v_mfma_f32_16x16x32_bf16 v[40:43], v[190:193], v[218:221], v[40:43]
	v_mfma_f32_16x16x32_bf16 v[36:39], v[182:185], v[226:229], v[36:39]
	v_mfma_f32_16x16x32_bf16 v[32:35], v[190:193], v[226:229], v[32:35]
	v_mfma_f32_16x16x32_bf16 v[60:63], v[186:189], v[206:209], v[60:63]
	v_mfma_f32_16x16x32_bf16 v[56:59], v[198:201], v[206:209], v[56:59]
	v_mfma_f32_16x16x32_bf16 v[52:55], v[186:189], v[214:217], v[52:55]
	v_mfma_f32_16x16x32_bf16 v[48:51], v[198:201], v[214:217], v[48:51]
	v_mfma_f32_16x16x32_bf16 v[44:47], v[186:189], v[222:225], v[44:47]
	v_mfma_f32_16x16x32_bf16 v[40:43], v[198:201], v[222:225], v[40:43]
	v_mfma_f32_16x16x32_bf16 v[36:39], v[186:189], v[230:233], v[36:39]
	v_mfma_f32_16x16x32_bf16 v[32:35], v[198:201], v[230:233], v[32:35]
	s_barrier
	s_add_i32 s51, s41, s26
	v_lshl_add_u64 v[194:195], s[52:53], 0, v[132:133]
	s_mov_b32 m0, s51
	ds_read_b128 v[202:205], v164 offset:16384
	ds_read_b128 v[206:209], v164 offset:17408
	ds_read_b128 v[210:213], v164 offset:18432
	ds_read_b128 v[214:217], v164 offset:19456
	ds_read_b128 v[218:221], v164 offset:20480
	ds_read_b128 v[222:225], v164 offset:21504
	ds_read_b128 v[226:229], v164 offset:22528
	ds_read_b128 v[230:233], v164 offset:23552
	global_load_lds_dwordx4 v[194:195], off
	s_add_i32 m0, s51, 0x2000
	v_lshl_add_u64 v[234:235], s[52:53], 0, v[128:129]
	s_add_u32 s52, s52, s10
	s_addc_u32 s53, s53, s11
	s_add_i32 s51, s42, s26
	global_load_lds_dwordx4 v[234:235], off
	v_lshl_add_u64 v[236:237], s[52:53], 0, v[132:133]
	s_mov_b32 m0, s51
	v_lshl_add_u64 v[238:239], s[52:53], 0, v[128:129]
	global_load_lds_dwordx4 v[236:237], off
	s_add_i32 m0, s51, 0x2000
	v_lshl_add_u64 v[240:241], s[24:25], 0, v[134:135]
	global_load_lds_dwordx4 v[238:239], off
	s_mov_b32 m0, s27
	v_lshl_add_u64 v[242:243], s[24:25], 0, v[130:131]
	global_load_lds_dwordx4 v[240:241], off
	s_mov_b32 m0, s30
	s_nop 0
	global_load_lds_dwordx4 v[242:243], off
	s_waitcnt vmcnt(8)
	s_waitcnt lgkmcnt(0)
	s_barrier
; #define PG8_STAGE(bufoff, gbase, voff) do { _Pragma("unroll") for (int _i = 0; _i < 2; ++_i) \
;         __builtin_amdgcn_global_load_lds((const unsigned*)((const char*)(gbase) + (voff)[_i]), (PG8_LAS unsigned*)(lds + (bufoff) + ldsw + _i * 8192), 16, 0, 0); } while (0)
; #define PG8_LDA(dst, b, h) do { _Pragma("unroll") for (int m = 0; m < 4; ++m) _Pragma("unroll") for (int k = 0; k < 2; ++k) dst[m][k] = *(const PG8_LAS bf16x8*)(lds + PG8_SA(b, h) + aoff + m * 2048 + k * 1024); } while (0)
; #define PG8_LDB(dst, b, h) do { _Pragma("unroll") for (int n = 0; n < 2; ++n) _Pragma("unroll") for (int k = 0; k < 2; ++k) dst[n][k] = *(const PG8_LAS bf16x8*)(lds + PG8_SB(b, h) + boff + n * 2048 + k * 1024); } while (0)
; #define PG8_MMA(ai, bj, At, Bt) do { __builtin_amdgcn_s_setprio(1); _Pragma("unroll") for (int m = 0; m < 4; ++m) _Pragma("unroll") for (int n = 0; n < 2; ++n) _Pragma("unroll") for (int k = 0; k < 2; ++k) \
;         acc[ai][bj][m][n] = __builtin_amdgcn_mfma_f32_16x16x32_bf16(Bt[n][k], At[m][k], acc[ai][bj][m][n], 0, 0, 0); __builtin_amdgcn_s_setprio(0); } while (0)
; #define PG8_WAIT_V(n) asm volatile("s_waitcnt vmcnt(" #n ")" ::: "memory")
; #define PG8_WAIT_L(n) asm volatile("s_waitcnt lgkmcnt(" #n ")" ::: "memory")
; #define PG8_BAR __builtin_amdgcn_s_barrier()
; #define PG8_SCHED __builtin_amdgcn_sched_barrier(0)
; template <class Epi, class Sched, bool ALIGN_EPI = false, bool SP2 = false>
; __device__ __forceinline__ void gemm_phase(PG8_LAS unsigned char* lds, const Gemm g, const Sched& S, const Epi& E) {
;     ...
;             PG8_WAIT_V(8); PG8_WAIT_L(0); PG8_BAR; PG8_MMA(1, 0, At, B0); PG8_MMA(1, 1, At, B1); PG8_BAR; PG8_SCHED;
;             PG8_LDB(B0, 1, 0); PG8_LDB(B1, 1, 1); PG8_SCHED; PG8_LDA(At, 1, 0); PG8_STAGE(PG8_SA(0, 1), a2 + hstep, voffA);
;             PG8_WAIT_V(8); PG8_WAIT_L(0); PG8_BAR; PG8_MMA(0, 0, At, B0); PG8_MMA(0, 1, At, B1); PG8_BAR; PG8_SCHED;
	s_waitcnt lgkmcnt(0)
	v_mfma_f32_16x16x32_bf16 v[92:95], v[166:169], v[202:205], v[92:95]
	v_mfma_f32_16x16x32_bf16 v[88:91], v[174:177], v[202:205], v[88:91]
	v_mfma_f32_16x16x32_bf16 v[84:87], v[166:169], v[210:213], v[84:87]
	v_mfma_f32_16x16x32_bf16 v[80:83], v[174:177], v[210:213], v[80:83]
	v_mfma_f32_16x16x32_bf16 v[76:79], v[166:169], v[218:221], v[76:79]
	v_mfma_f32_16x16x32_bf16 v[72:75], v[174:177], v[218:221], v[72:75]
	v_mfma_f32_16x16x32_bf16 v[68:71], v[166:169], v[226:229], v[68:71]
	v_mfma_f32_16x16x32_bf16 v[64:67], v[174:177], v[226:229], v[64:67]
	v_mfma_f32_16x16x32_bf16 v[92:95], v[170:173], v[206:209], v[92:95]
	v_mfma_f32_16x16x32_bf16 v[88:91], v[178:181], v[206:209], v[88:91]
	v_mfma_f32_16x16x32_bf16 v[84:87], v[170:173], v[214:217], v[84:87]
	v_mfma_f32_16x16x32_bf16 v[80:83], v[178:181], v[214:217], v[80:83]
	v_mfma_f32_16x16x32_bf16 v[76:79], v[170:173], v[222:225], v[76:79]
	v_mfma_f32_16x16x32_bf16 v[72:75], v[178:181], v[222:225], v[72:75]
	v_mfma_f32_16x16x32_bf16 v[68:71], v[170:173], v[230:233], v[68:71]
	v_mfma_f32_16x16x32_bf16 v[64:67], v[178:181], v[230:233], v[64:67]
	v_mfma_f32_16x16x32_bf16 v[28:31], v[182:185], v[202:205], v[28:31]
	v_mfma_f32_16x16x32_bf16 v[24:27], v[190:193], v[202:205], v[24:27]
	v_mfma_f32_16x16x32_bf16 v[20:23], v[182:185], v[210:213], v[20:23]
	v_mfma_f32_16x16x32_bf16 v[16:19], v[190:193], v[210:213], v[16:19]
	v_mfma_f32_16x16x32_bf16 v[12:15], v[182:185], v[218:221], v[12:15]
	v_mfma_f32_16x16x32_bf16 v[8:11], v[190:193], v[218:221], v[8:11]
	v_mfma_f32_16x16x32_bf16 v[4:7], v[182:185], v[226:229], v[4:7]
	v_mfma_f32_16x16x32_bf16 v[0:3], v[190:193], v[226:229], v[0:3]
	v_mfma_f32_16x16x32_bf16 v[28:31], v[186:189], v[206:209], v[28:31]
	v_mfma_f32_16x16x32_bf16 v[24:27], v[198:201], v[206:209], v[24:27]
	v_mfma_f32_16x16x32_bf16 v[20:23], v[186:189], v[214:217], v[20:23]
	v_mfma_f32_16x16x32_bf16 v[16:19], v[198:201], v[214:217], v[16:19]
	v_mfma_f32_16x16x32_bf16 v[12:15], v[186:189], v[222:225], v[12:15]
	v_mfma_f32_16x16x32_bf16 v[8:11], v[198:201], v[222:225], v[8:11]
	v_mfma_f32_16x16x32_bf16 v[4:7], v[186:189], v[230:233], v[4:7]
	v_mfma_f32_16x16x32_bf16 v[0:3], v[198:201], v[230:233], v[0:3]
	s_barrier
	s_add_i32 s51, 0, 0x18000
	v_add_u32_e32 v165, s51, v161
	s_add_i32 s52, 0, 0x1c000
	ds_read_b128 v[166:169], v165
	ds_read_b128 v[170:173], v165 offset:1024
	ds_read_b128 v[174:177], v165 offset:2048
	ds_read_b128 v[178:181], v165 offset:3072
	v_add_u32_e32 v165, s52, v161
	ds_read_b128 v[182:185], v165
	ds_read_b128 v[186:189], v165 offset:1024
	ds_read_b128 v[190:193], v165 offset:2048
	ds_read_b128 v[198:201], v165 offset:3072
	s_add_u32 s24, s24, s10
	s_addc_u32 s25, s25, s11
	s_mov_b32 m0, s31
	v_lshl_add_u64 v[244:245], s[24:25], 0, v[134:135]
	ds_read_b128 v[202:205], v164 offset:32768
	ds_read_b128 v[206:209], v164 offset:33792
	ds_read_b128 v[210:213], v164 offset:34816
	ds_read_b128 v[214:217], v164 offset:35840
	ds_read_b128 v[218:221], v164 offset:36864
	ds_read_b128 v[222:225], v164 offset:37888
	ds_read_b128 v[226:229], v164 offset:38912
	ds_read_b128 v[230:233], v164 offset:39936
	global_load_lds_dwordx4 v[244:245], off
	v_lshl_add_u64 v[244:245], s[24:25], 0, v[130:131]
	s_mov_b32 m0, s34
	s_nop 0
	global_load_lds_dwordx4 v[244:245], off
	s_waitcnt vmcnt(8)
	s_waitcnt lgkmcnt(0)
	s_barrier
	s_waitcnt lgkmcnt(0)
	v_mfma_f32_16x16x32_bf16 v[124:127], v[166:169], v[202:205], v[124:127]
	v_mfma_f32_16x16x32_bf16 v[120:123], v[174:177], v[202:205], v[120:123]
	v_mfma_f32_16x16x32_bf16 v[116:119], v[166:169], v[210:213], v[116:119]
	v_mfma_f32_16x16x32_bf16 v[112:115], v[174:177], v[210:213], v[112:115]
	v_mfma_f32_16x16x32_bf16 v[108:111], v[166:169], v[218:221], v[108:111]
	v_mfma_f32_16x16x32_bf16 v[104:107], v[174:177], v[218:221], v[104:107]
	v_mfma_f32_16x16x32_bf16 v[100:103], v[166:169], v[226:229], v[100:103]
	v_mfma_f32_16x16x32_bf16 v[96:99], v[174:177], v[226:229], v[96:99]
	v_mfma_f32_16x16x32_bf16 v[124:127], v[170:173], v[206:209], v[124:127]
	v_mfma_f32_16x16x32_bf16 v[120:123], v[178:181], v[206:209], v[120:123]
	v_mfma_f32_16x16x32_bf16 v[116:119], v[170:173], v[214:217], v[116:119]
	v_mfma_f32_16x16x32_bf16 v[112:115], v[178:181], v[214:217], v[112:115]
	v_mfma_f32_16x16x32_bf16 v[108:111], v[170:173], v[222:225], v[108:111]
	v_mfma_f32_16x16x32_bf16 v[104:107], v[178:181], v[222:225], v[104:107]
	v_mfma_f32_16x16x32_bf16 v[100:103], v[170:173], v[230:233], v[100:103]
	v_mfma_f32_16x16x32_bf16 v[96:99], v[178:181], v[230:233], v[96:99]
	v_mfma_f32_16x16x32_bf16 v[60:63], v[182:185], v[202:205], v[60:63]
	v_mfma_f32_16x16x32_bf16 v[56:59], v[190:193], v[202:205], v[56:59]
	v_mfma_f32_16x16x32_bf16 v[52:55], v[182:185], v[210:213], v[52:55]
	v_mfma_f32_16x16x32_bf16 v[48:51], v[190:193], v[210:213], v[48:51]
	v_mfma_f32_16x16x32_bf16 v[44:47], v[182:185], v[218:221], v[44:47]
	v_mfma_f32_16x16x32_bf16 v[40:43], v[190:193], v[218:221], v[40:43]
	v_mfma_f32_16x16x32_bf16 v[36:39], v[182:185], v[226:229], v[36:39]
	v_mfma_f32_16x16x32_bf16 v[32:35], v[190:193], v[226:229], v[32:35]
	v_mfma_f32_16x16x32_bf16 v[60:63], v[186:189], v[206:209], v[60:63]
	v_mfma_f32_16x16x32_bf16 v[56:59], v[198:201], v[206:209], v[56:59]
	v_mfma_f32_16x16x32_bf16 v[52:55], v[186:189], v[214:217], v[52:55]
	v_mfma_f32_16x16x32_bf16 v[48:51], v[198:201], v[214:217], v[48:51]
	v_mfma_f32_16x16x32_bf16 v[44:47], v[186:189], v[222:225], v[44:47]
	v_mfma_f32_16x16x32_bf16 v[40:43], v[198:201], v[222:225], v[40:43]
	v_mfma_f32_16x16x32_bf16 v[36:39], v[186:189], v[230:233], v[36:39]
	v_mfma_f32_16x16x32_bf16 v[32:35], v[198:201], v[230:233], v[32:35]
	s_barrier
; #define PG8_STAGE(bufoff, gbase, voff) do { _Pragma("unroll") for (int _i = 0; _i < 2; ++_i) \
;         __builtin_amdgcn_global_load_lds((const unsigned*)((const char*)(gbase) + (voff)[_i]), (PG8_LAS unsigned*)(lds + (bufoff) + ldsw + _i * 8192), 16, 0, 0); } while (0)
; #define PG8_LDA(dst, b, h) do { _Pragma("unroll") for (int m = 0; m < 4; ++m) _Pragma("unroll") for (int k = 0; k < 2; ++k) dst[m][k] = *(const PG8_LAS bf16x8*)(lds + PG8_SA(b, h) + aoff + m * 2048 + k * 1024); } while (0)
; #define PG8_MMA(ai, bj, At, Bt) do { __builtin_amdgcn_s_setprio(1); _Pragma("unroll") for (int m = 0; m < 4; ++m) _Pragma("unroll") for (int n = 0; n < 2; ++n) _Pragma("unroll") for (int k = 0; k < 2; ++k) \
;         acc[ai][bj][m][n] = __builtin_amdgcn_mfma_f32_16x16x32_bf16(Bt[n][k], At[m][k], acc[ai][bj][m][n], 0, 0, 0); __builtin_amdgcn_s_setprio(0); } while (0)
; #define PG8_WAIT_V(n) asm volatile("s_waitcnt vmcnt(" #n ")" ::: "memory")
; #define PG8_WAIT_L(n) asm volatile("s_waitcnt lgkmcnt(" #n ")" ::: "memory")
; #define PG8_BAR __builtin_amdgcn_s_barrier()
; #define PG8_SCHED __builtin_amdgcn_sched_barrier(0)
; template <class Epi, class Sched, bool ALIGN_EPI = false, bool SP2 = false>
; __device__ __forceinline__ void gemm_phase(PG8_LAS unsigned char* lds, const Gemm g, const Sched& S, const Epi& E) {
;     ...
;         for (int t = 0; t < nt; t += 2) {
;     ...
;             PG8_LDA(At, 1, 1); PG8_STAGE(PG8_SB(1, 0), b3, voffB); PG8_STAGE(PG8_SB(1, 1), b3 + hstep, voffB); PG8_STAGE(PG8_SA(1, 0), a3, voffA);
;             PG8_WAIT_V(8); PG8_WAIT_L(0); PG8_BAR; PG8_MMA(1, 0, At, B0); PG8_MMA(1, 1, At, B1); PG8_BAR; PG8_SCHED;
	s_add_i32 s24, s51, s26
	v_lshl_add_u64 v[194:195], v[194:195], 0, s[16:17]
	s_mov_b32 m0, s24
	ds_read_b128 v[202:205], v164 offset:49152
	ds_read_b128 v[206:209], v164 offset:50176
	ds_read_b128 v[210:213], v164 offset:51200
	ds_read_b128 v[214:217], v164 offset:52224
	ds_read_b128 v[218:221], v164 offset:53248
	ds_read_b128 v[222:225], v164 offset:54272
	ds_read_b128 v[226:229], v164 offset:55296
	ds_read_b128 v[230:233], v164 offset:56320
	global_load_lds_dwordx4 v[194:195], off
	v_lshl_add_u64 v[194:195], v[234:235], 0, s[16:17]
	s_add_i32 m0, s24, 0x2000
	s_add_i32 s24, s52, s26
	global_load_lds_dwordx4 v[194:195], off
	v_lshl_add_u64 v[194:195], v[236:237], 0, s[16:17]
	s_mov_b32 m0, s24
	s_nop 0
	global_load_lds_dwordx4 v[194:195], off
	v_lshl_add_u64 v[194:195], v[238:239], 0, s[16:17]
	s_add_i32 m0, s24, 0x2000
	s_nop 0
	global_load_lds_dwordx4 v[194:195], off
	v_lshl_add_u64 v[194:195], v[240:241], 0, s[16:17]
	s_mov_b32 m0, s36
	s_nop 0
	global_load_lds_dwordx4 v[194:195], off
	v_lshl_add_u64 v[194:195], v[242:243], 0, s[16:17]
	s_mov_b32 m0, s37
	s_nop 0
	global_load_lds_dwordx4 v[194:195], off
	s_waitcnt vmcnt(8)
	s_waitcnt lgkmcnt(0)
	s_barrier
	s_waitcnt lgkmcnt(0)
	v_mfma_f32_16x16x32_bf16 v[92:95], v[166:169], v[202:205], v[92:95]
	v_mfma_f32_16x16x32_bf16 v[88:91], v[174:177], v[202:205], v[88:91]
	v_mfma_f32_16x16x32_bf16 v[84:87], v[166:169], v[210:213], v[84:87]
	v_mfma_f32_16x16x32_bf16 v[80:83], v[174:177], v[210:213], v[80:83]
	v_mfma_f32_16x16x32_bf16 v[76:79], v[166:169], v[218:221], v[76:79]
	v_mfma_f32_16x16x32_bf16 v[72:75], v[174:177], v[218:221], v[72:75]
	v_mfma_f32_16x16x32_bf16 v[68:71], v[166:169], v[226:229], v[68:71]
	v_mfma_f32_16x16x32_bf16 v[64:67], v[174:177], v[226:229], v[64:67]
	v_mfma_f32_16x16x32_bf16 v[92:95], v[170:173], v[206:209], v[92:95]
	v_mfma_f32_16x16x32_bf16 v[88:91], v[178:181], v[206:209], v[88:91]
	v_mfma_f32_16x16x32_bf16 v[84:87], v[170:173], v[214:217], v[84:87]
	v_mfma_f32_16x16x32_bf16 v[80:83], v[178:181], v[214:217], v[80:83]
	v_mfma_f32_16x16x32_bf16 v[76:79], v[170:173], v[222:225], v[76:79]
	v_mfma_f32_16x16x32_bf16 v[72:75], v[178:181], v[222:225], v[72:75]
	v_mfma_f32_16x16x32_bf16 v[68:71], v[170:173], v[230:233], v[68:71]
	v_mfma_f32_16x16x32_bf16 v[64:67], v[178:181], v[230:233], v[64:67]
	v_mfma_f32_16x16x32_bf16 v[28:31], v[182:185], v[202:205], v[28:31]
	v_mfma_f32_16x16x32_bf16 v[24:27], v[190:193], v[202:205], v[24:27]
	v_mfma_f32_16x16x32_bf16 v[20:23], v[182:185], v[210:213], v[20:23]
	v_mfma_f32_16x16x32_bf16 v[16:19], v[190:193], v[210:213], v[16:19]
	v_mfma_f32_16x16x32_bf16 v[12:15], v[182:185], v[218:221], v[12:15]
	v_mfma_f32_16x16x32_bf16 v[8:11], v[190:193], v[218:221], v[8:11]
	v_mfma_f32_16x16x32_bf16 v[4:7], v[182:185], v[226:229], v[4:7]
	v_mfma_f32_16x16x32_bf16 v[0:3], v[190:193], v[226:229], v[0:3]
	v_mfma_f32_16x16x32_bf16 v[28:31], v[186:189], v[206:209], v[28:31]
	v_mfma_f32_16x16x32_bf16 v[24:27], v[198:201], v[206:209], v[24:27]
	v_mfma_f32_16x16x32_bf16 v[20:23], v[186:189], v[214:217], v[20:23]
	v_mfma_f32_16x16x32_bf16 v[16:19], v[198:201], v[214:217], v[16:19]
	v_mfma_f32_16x16x32_bf16 v[12:15], v[186:189], v[222:225], v[12:15]
	v_mfma_f32_16x16x32_bf16 v[8:11], v[198:201], v[222:225], v[8:11]
	v_mfma_f32_16x16x32_bf16 v[4:7], v[186:189], v[230:233], v[4:7]
	v_mfma_f32_16x16x32_bf16 v[0:3], v[198:201], v[230:233], v[0:3]
	s_barrier
	s_add_u32 s22, s22, 0x100
	s_addc_u32 s23, s23, 0
	s_add_u32 s48, s48, 0x100
	s_addc_u32 s49, s49, 0
	s_cmp_ge_i32 s50, s38
	s_mov_b32 s24, s50
	s_cbranch_scc0 .LBB0_731
	s_setprio 0

; template <class Epi, class Sched, bool ALIGN_EPI = false, bool SP2 = false>
; __device__ __forceinline__ void gemm_phase(PG8_LAS unsigned char* lds, const Gemm g, const Sched& S, const Epi& E) {
;     ...
;     f32x4 acc[2][2][4][2];
; #pragma unroll
;     for (int a = 0; a < 2; ++a)
; #pragma unroll
;         for (int b = 0; b < 2; ++b)
; #pragma unroll
;             for (int m = 0; m < 4; ++m)
; #pragma unroll
;                 for (int n = 0; n < 2; ++n) acc[a][b][m][n] = (f32x4){0.f, 0.f, 0.f, 0.f};
;     ...
;         for (int t = 0; t < nt; t += 2) {
;             const bool last = (t == nt - 2);
;             const char* a1 = cA + (size_t)(t + 1) * kstep;
;             const char* a2 = last ? nA : cA + (size_t)(t + 2) * kstep; const char* b2 = last ? nB : cB + (size_t)(t + 2) * kstep;
;             const char* a3 = a2 + kstep; const char* b3 = b2 + kstep;
;             if (last && has_next) S.a_ready(nxt);
.LBB0_755:
	v_mov_b32_e32 v123, 0
	s_andn2_b64 vcc, exec, s[16:17]
	v_mov_b32_e32 v122, v123
	v_mov_b32_e32 v121, v123
	v_mov_b32_e32 v120, v123
	v_mov_b32_e32 v127, v123
	v_mov_b32_e32 v126, v123
	v_mov_b32_e32 v125, v123
	v_mov_b32_e32 v124, v123
	v_mov_b32_e32 v119, v123
	v_mov_b32_e32 v118, v123
	v_mov_b32_e32 v117, v123
	v_mov_b32_e32 v116, v123
	v_mov_b32_e32 v115, v123
	v_mov_b32_e32 v114, v123
	v_mov_b32_e32 v113, v123
	v_mov_b32_e32 v112, v123
	v_mov_b32_e32 v111, v123
	v_mov_b32_e32 v110, v123
	v_mov_b32_e32 v109, v123
	v_mov_b32_e32 v108, v123
	v_mov_b32_e32 v107, v123
	v_mov_b32_e32 v106, v123
	v_mov_b32_e32 v105, v123
	v_mov_b32_e32 v104, v123
	v_mov_b32_e32 v103, v123
	v_mov_b32_e32 v102, v123
	v_mov_b32_e32 v101, v123
	v_mov_b32_e32 v100, v123
	v_mov_b32_e32 v99, v123
	v_mov_b32_e32 v98, v123
	v_mov_b32_e32 v97, v123
	v_mov_b32_e32 v96, v123
	v_mov_b32_e32 v63, v123
	v_mov_b32_e32 v62, v123
	v_mov_b32_e32 v61, v123
	v_mov_b32_e32 v60, v123
	v_mov_b32_e32 v59, v123
	v_mov_b32_e32 v58, v123
	v_mov_b32_e32 v57, v123
	v_mov_b32_e32 v56, v123
	v_mov_b32_e32 v55, v123
	v_mov_b32_e32 v54, v123
	v_mov_b32_e32 v53, v123
	v_mov_b32_e32 v52, v123
	v_mov_b32_e32 v51, v123
	v_mov_b32_e32 v50, v123
	v_mov_b32_e32 v49, v123
	v_mov_b32_e32 v48, v123
	v_mov_b32_e32 v47, v123
	v_mov_b32_e32 v46, v123
	v_mov_b32_e32 v45, v123
	v_mov_b32_e32 v44, v123
	v_mov_b32_e32 v43, v123
	v_mov_b32_e32 v42, v123
	v_mov_b32_e32 v41, v123
	v_mov_b32_e32 v40, v123
	v_mov_b32_e32 v39, v123
	v_mov_b32_e32 v38, v123
	v_mov_b32_e32 v37, v123
	v_mov_b32_e32 v36, v123
	v_mov_b32_e32 v35, v123
	v_mov_b32_e32 v34, v123
	v_mov_b32_e32 v33, v123
	v_mov_b32_e32 v32, v123
	v_mov_b32_e32 v95, v123
	v_mov_b32_e32 v94, v123
	v_mov_b32_e32 v93, v123
	v_mov_b32_e32 v92, v123
	v_mov_b32_e32 v91, v123
	v_mov_b32_e32 v90, v123
	v_mov_b32_e32 v89, v123
	v_mov_b32_e32 v88, v123
	v_mov_b32_e32 v87, v123
	v_mov_b32_e32 v86, v123
	v_mov_b32_e32 v85, v123
	v_mov_b32_e32 v84, v123
	v_mov_b32_e32 v83, v123
	v_mov_b32_e32 v82, v123
	v_mov_b32_e32 v81, v123
	v_mov_b32_e32 v80, v123
	v_mov_b32_e32 v79, v123
	v_mov_b32_e32 v78, v123
	v_mov_b32_e32 v77, v123
	v_mov_b32_e32 v76, v123
	v_mov_b32_e32 v75, v123
	v_mov_b32_e32 v74, v123
	v_mov_b32_e32 v73, v123
	v_mov_b32_e32 v72, v123
	v_mov_b32_e32 v71, v123
	v_mov_b32_e32 v70, v123
	v_mov_b32_e32 v69, v123
	v_mov_b32_e32 v68, v123
	v_mov_b32_e32 v67, v123
	v_mov_b32_e32 v66, v123
	v_mov_b32_e32 v65, v123
	v_mov_b32_e32 v64, v123
	v_mov_b32_e32 v31, v123
	v_mov_b32_e32 v30, v123
	v_mov_b32_e32 v29, v123
	v_mov_b32_e32 v28, v123
	v_mov_b32_e32 v27, v123
	v_mov_b32_e32 v26, v123
	v_mov_b32_e32 v25, v123
	v_mov_b32_e32 v24, v123
	v_mov_b32_e32 v23, v123
	v_mov_b32_e32 v22, v123
	v_mov_b32_e32 v21, v123
	v_mov_b32_e32 v20, v123
	v_mov_b32_e32 v19, v123
	v_mov_b32_e32 v18, v123
	v_mov_b32_e32 v17, v123
	v_mov_b32_e32 v16, v123
	v_mov_b32_e32 v15, v123
	v_mov_b32_e32 v14, v123
	v_mov_b32_e32 v13, v123
	v_mov_b32_e32 v12, v123
	v_mov_b32_e32 v11, v123
	v_mov_b32_e32 v10, v123
	v_mov_b32_e32 v9, v123
	v_mov_b32_e32 v8, v123
	v_mov_b32_e32 v7, v123
	v_mov_b32_e32 v6, v123
	v_mov_b32_e32 v5, v123
	v_mov_b32_e32 v4, v123
	v_mov_b32_e32 v3, v123
	v_mov_b32_e32 v2, v123
	v_mov_b32_e32 v1, v123
	v_mov_b32_e32 v0, v123
	s_cbranch_vccnz .LBB0_758
	s_add_u32 s22, s22, 0x80
	s_addc_u32 s23, s23, 0
	s_add_u32 s51, s24, 0x100
	v_mov_b32_e32 v0, 0
	s_addc_u32 s52, s25, 0
	s_mov_b32 s24, 0
	v_mov_b32_e32 v1, v0
	v_mov_b32_e32 v2, v0
	v_mov_b32_e32 v3, v0
	v_mov_b32_e32 v4, v0
	v_mov_b32_e32 v5, v0
	v_mov_b32_e32 v6, v0
	v_mov_b32_e32 v7, v0
	v_mov_b32_e32 v8, v0
	v_mov_b32_e32 v9, v0
	v_mov_b32_e32 v10, v0
	v_mov_b32_e32 v11, v0
	v_mov_b32_e32 v12, v0
	v_mov_b32_e32 v13, v0
	v_mov_b32_e32 v14, v0
	v_mov_b32_e32 v15, v0
	v_mov_b32_e32 v16, v0
	v_mov_b32_e32 v17, v0
	v_mov_b32_e32 v18, v0
	v_mov_b32_e32 v19, v0
	v_mov_b32_e32 v20, v0
	v_mov_b32_e32 v21, v0
	v_mov_b32_e32 v22, v0
	v_mov_b32_e32 v23, v0
	v_mov_b32_e32 v24, v0
	v_mov_b32_e32 v25, v0
	v_mov_b32_e32 v26, v0
	v_mov_b32_e32 v27, v0
	v_mov_b32_e32 v28, v0
	v_mov_b32_e32 v29, v0
	v_mov_b32_e32 v30, v0
	v_mov_b32_e32 v31, v0
	v_mov_b32_e32 v64, v0
	v_mov_b32_e32 v65, v0
	v_mov_b32_e32 v66, v0
	v_mov_b32_e32 v67, v0
	v_mov_b32_e32 v68, v0
	v_mov_b32_e32 v69, v0
	v_mov_b32_e32 v70, v0
	v_mov_b32_e32 v71, v0
	v_mov_b32_e32 v72, v0
	v_mov_b32_e32 v73, v0
	v_mov_b32_e32 v74, v0
	v_mov_b32_e32 v75, v0
	v_mov_b32_e32 v76, v0
	v_mov_b32_e32 v77, v0
	v_mov_b32_e32 v78, v0
	v_mov_b32_e32 v79, v0
	v_mov_b32_e32 v80, v0
	v_mov_b32_e32 v81, v0
	v_mov_b32_e32 v82, v0
	v_mov_b32_e32 v83, v0
	v_mov_b32_e32 v84, v0
	v_mov_b32_e32 v85, v0
	v_mov_b32_e32 v86, v0
	v_mov_b32_e32 v87, v0
	v_mov_b32_e32 v88, v0
	v_mov_b32_e32 v89, v0
	v_mov_b32_e32 v90, v0
	v_mov_b32_e32 v91, v0
	v_mov_b32_e32 v92, v0
	v_mov_b32_e32 v93, v0
	v_mov_b32_e32 v94, v0
	v_mov_b32_e32 v95, v0
	v_mov_b32_e32 v32, v0
	v_mov_b32_e32 v33, v0
	v_mov_b32_e32 v34, v0
	v_mov_b32_e32 v35, v0
	v_mov_b32_e32 v36, v0
	v_mov_b32_e32 v37, v0
	v_mov_b32_e32 v38, v0
	v_mov_b32_e32 v39, v0
	v_mov_b32_e32 v40, v0
	v_mov_b32_e32 v41, v0
	v_mov_b32_e32 v42, v0
	v_mov_b32_e32 v43, v0
	v_mov_b32_e32 v44, v0
	v_mov_b32_e32 v45, v0
	v_mov_b32_e32 v46, v0
	v_mov_b32_e32 v47, v0
	v_mov_b32_e32 v48, v0
	v_mov_b32_e32 v49, v0
	v_mov_b32_e32 v50, v0
	v_mov_b32_e32 v51, v0
	v_mov_b32_e32 v52, v0
	v_mov_b32_e32 v53, v0
	v_mov_b32_e32 v54, v0
	v_mov_b32_e32 v55, v0
	v_mov_b32_e32 v56, v0
	v_mov_b32_e32 v57, v0
	v_mov_b32_e32 v58, v0
	v_mov_b32_e32 v59, v0
	v_mov_b32_e32 v60, v0
	v_mov_b32_e32 v61, v0
	v_mov_b32_e32 v62, v0
	v_mov_b32_e32 v63, v0
	v_mov_b32_e32 v96, v0
	v_mov_b32_e32 v97, v0
	v_mov_b32_e32 v98, v0
	v_mov_b32_e32 v99, v0
	v_mov_b32_e32 v100, v0
	v_mov_b32_e32 v101, v0
	v_mov_b32_e32 v102, v0
	v_mov_b32_e32 v103, v0
	v_mov_b32_e32 v104, v0
	v_mov_b32_e32 v105, v0
	v_mov_b32_e32 v106, v0
	v_mov_b32_e32 v107, v0
	v_mov_b32_e32 v108, v0
	v_mov_b32_e32 v109, v0
	v_mov_b32_e32 v110, v0
	v_mov_b32_e32 v111, v0
	v_mov_b32_e32 v112, v0
	v_mov_b32_e32 v113, v0
	v_mov_b32_e32 v114, v0
	v_mov_b32_e32 v115, v0
	v_mov_b32_e32 v116, v0
	v_mov_b32_e32 v117, v0
	v_mov_b32_e32 v118, v0
	v_mov_b32_e32 v119, v0
	v_mov_b32_e32 v124, v0
	v_mov_b32_e32 v125, v0
	v_mov_b32_e32 v126, v0
	v_mov_b32_e32 v127, v0
	v_mov_b32_e32 v120, v0
	v_mov_b32_e32 v121, v0
	v_mov_b32_e32 v122, v0
	v_mov_b32_e32 v123, v0
	v_readfirstlane_b32 s98, v197
	s_nop 3
	s_cmpk_gt_u32 s98, 0xff
	s_cbranch_scc0 .Lkp_3
	s_setprio 1
; #define PG8_STAGE(bufoff, gbase, voff) do { _Pragma("unroll") for (int _i = 0; _i < 2; ++_i) \
;         __builtin_amdgcn_global_load_lds((const unsigned*)((const char*)(gbase) + (voff)[_i]), (PG8_LAS unsigned*)(lds + (bufoff) + ldsw + _i * 8192), 16, 0, 0); } while (0)
; #define PG8_LDA(dst, b, h) do { _Pragma("unroll") for (int m = 0; m < 4; ++m) _Pragma("unroll") for (int k = 0; k < 2; ++k) dst[m][k] = *(const PG8_LAS bf16x8*)(lds + PG8_SA(b, h) + aoff + m * 2048 + k * 1024); } while (0)
; #define PG8_LDB(dst, b, h) do { _Pragma("unroll") for (int n = 0; n < 2; ++n) _Pragma("unroll") for (int k = 0; k < 2; ++k) dst[n][k] = *(const PG8_LAS bf16x8*)(lds + PG8_SB(b, h) + boff + n * 2048 + k * 1024); } while (0)
; #define PG8_MMA(ai, bj, At, Bt) do { __builtin_amdgcn_s_setprio(1); _Pragma("unroll") for (int m = 0; m < 4; ++m) _Pragma("unroll") for (int n = 0; n < 2; ++n) _Pragma("unroll") for (int k = 0; k < 2; ++k) \
;         acc[ai][bj][m][n] = __builtin_amdgcn_mfma_f32_16x16x32_bf16(Bt[n][k], At[m][k], acc[ai][bj][m][n], 0, 0, 0); __builtin_amdgcn_s_setprio(0); } while (0)
; #define PG8_WAIT_V(n) asm volatile("s_waitcnt vmcnt(" #n ")" ::: "memory")
; #define PG8_WAIT_L(n) asm volatile("s_waitcnt lgkmcnt(" #n ")" ::: "memory")
; #define PG8_BAR __builtin_amdgcn_s_barrier()
; #define PG8_SCHED __builtin_amdgcn_sched_barrier(0)
; template <class Epi, class Sched, bool ALIGN_EPI = false, bool SP2 = false>
; __device__ __forceinline__ void gemm_phase(PG8_LAS unsigned char* lds, const Gemm g, const Sched& S, const Epi& E) {
;     ...
;             PG8_LDB(B0, 0, 0); PG8_LDB(B1, 0, 1); PG8_SCHED; PG8_LDA(At, 0, 0); PG8_STAGE(PG8_SA(1, 1), a1 + hstep, voffA);
;             PG8_WAIT_V(8); PG8_WAIT_L(0); PG8_BAR; PG8_MMA(0, 0, At, B0); PG8_MMA(0, 1, At, B1); PG8_BAR; PG8_SCHED;
;             PG8_LDA(At, 0, 1); PG8_STAGE(PG8_SB(0, 0), b2, voffB); PG8_STAGE(PG8_SB(0, 1), b2 + hstep, voffB); PG8_STAGE(PG8_SA(0, 0), a2, voffA);
;             PG8_WAIT_V(8); PG8_WAIT_L(0); PG8_BAR; PG8_MMA(1, 0, At, B0); PG8_MMA(1, 1, At, B1); PG8_BAR; PG8_SCHED;
.Lkp_3:
.LBB0_757:
	ds_read_b128 v[150:153], v146
	ds_read_b128 v[154:157], v146 offset:1024
	ds_read_b128 v[158:161], v146 offset:2048
	ds_read_b128 v[162:165], v146 offset:3072
	ds_read_b128 v[166:169], v147
	ds_read_b128 v[170:173], v147 offset:1024
	ds_read_b128 v[174:177], v147 offset:2048
	ds_read_b128 v[178:181], v147 offset:3072
	s_add_i32 s53, s24, 2
	s_add_u32 s54, s22, 0x80
	s_addc_u32 s25, s23, 0
	s_cmp_eq_u32 s43, s24
	s_cselect_b32 s24, s2, s54
	s_cselect_b32 s25, s3, s25
	s_cselect_b32 s55, s21, s52
	s_cselect_b32 s54, s20, s51
	v_lshl_add_u64 v[194:195], s[22:23], 0, v[136:137]
	s_add_i32 m0, s31, 0xc000
	ds_read_b128 v[182:185], v148
	ds_read_b128 v[186:189], v148 offset:1024
	ds_read_b128 v[190:193], v148 offset:2048
	ds_read_b128 v[198:201], v148 offset:3072
	ds_read_b128 v[202:205], v148 offset:4096
	ds_read_b128 v[206:209], v148 offset:5120
	ds_read_b128 v[210:213], v148 offset:6144
	ds_read_b128 v[214:217], v148 offset:7168
	global_load_lds_dwordx4 v[194:195], off
	v_lshl_add_u64 v[194:195], s[22:23], 0, v[138:139]
	s_add_i32 m0, s31, 0xe000
	s_nop 0
	global_load_lds_dwordx4 v[194:195], off
	s_waitcnt vmcnt(8)
	s_waitcnt lgkmcnt(0)
	s_barrier
	s_waitcnt lgkmcnt(0)
	v_mfma_f32_16x16x32_bf16 v[120:123], v[150:153], v[182:185], v[120:123]
	v_mfma_f32_16x16x32_bf16 v[124:127], v[158:161], v[182:185], v[124:127]
	v_mfma_f32_16x16x32_bf16 v[116:119], v[150:153], v[190:193], v[116:119]
	v_mfma_f32_16x16x32_bf16 v[112:115], v[158:161], v[190:193], v[112:115]
	v_mfma_f32_16x16x32_bf16 v[108:111], v[150:153], v[202:205], v[108:111]
	v_mfma_f32_16x16x32_bf16 v[104:107], v[158:161], v[202:205], v[104:107]
	v_mfma_f32_16x16x32_bf16 v[100:103], v[150:153], v[210:213], v[100:103]
	v_mfma_f32_16x16x32_bf16 v[96:99], v[158:161], v[210:213], v[96:99]
	v_mfma_f32_16x16x32_bf16 v[120:123], v[154:157], v[186:189], v[120:123]
	v_mfma_f32_16x16x32_bf16 v[124:127], v[162:165], v[186:189], v[124:127]
	v_mfma_f32_16x16x32_bf16 v[116:119], v[154:157], v[198:201], v[116:119]
	v_mfma_f32_16x16x32_bf16 v[112:115], v[162:165], v[198:201], v[112:115]
	v_mfma_f32_16x16x32_bf16 v[108:111], v[154:157], v[206:209], v[108:111]
	v_mfma_f32_16x16x32_bf16 v[104:107], v[162:165], v[206:209], v[104:107]
	v_mfma_f32_16x16x32_bf16 v[100:103], v[154:157], v[214:217], v[100:103]
	v_mfma_f32_16x16x32_bf16 v[96:99], v[162:165], v[214:217], v[96:99]
	v_mfma_f32_16x16x32_bf16 v[60:63], v[166:169], v[182:185], v[60:63]
	v_mfma_f32_16x16x32_bf16 v[56:59], v[174:177], v[182:185], v[56:59]
	v_mfma_f32_16x16x32_bf16 v[52:55], v[166:169], v[190:193], v[52:55]
	v_mfma_f32_16x16x32_bf16 v[48:51], v[174:177], v[190:193], v[48:51]
	v_mfma_f32_16x16x32_bf16 v[44:47], v[166:169], v[202:205], v[44:47]
	v_mfma_f32_16x16x32_bf16 v[40:43], v[174:177], v[202:205], v[40:43]
	v_mfma_f32_16x16x32_bf16 v[36:39], v[166:169], v[210:213], v[36:39]
	v_mfma_f32_16x16x32_bf16 v[32:35], v[174:177], v[210:213], v[32:35]
	v_mfma_f32_16x16x32_bf16 v[60:63], v[170:173], v[186:189], v[60:63]
	v_mfma_f32_16x16x32_bf16 v[56:59], v[178:181], v[186:189], v[56:59]
	v_mfma_f32_16x16x32_bf16 v[52:55], v[170:173], v[198:201], v[52:55]
	v_mfma_f32_16x16x32_bf16 v[48:51], v[178:181], v[198:201], v[48:51]
	v_mfma_f32_16x16x32_bf16 v[44:47], v[170:173], v[206:209], v[44:47]
	v_mfma_f32_16x16x32_bf16 v[40:43], v[178:181], v[206:209], v[40:43]
	v_mfma_f32_16x16x32_bf16 v[36:39], v[170:173], v[214:217], v[36:39]
	v_mfma_f32_16x16x32_bf16 v[32:35], v[178:181], v[214:217], v[32:35]
	s_barrier
	s_add_i32 s56, s44, s27
	v_lshl_add_u64 v[194:195], s[54:55], 0, v[132:133]
	s_mov_b32 m0, s56
	ds_read_b128 v[182:185], v148 offset:16384
	ds_read_b128 v[186:189], v148 offset:17408
	ds_read_b128 v[190:193], v148 offset:18432
	ds_read_b128 v[198:201], v148 offset:19456
	ds_read_b128 v[202:205], v148 offset:20480
	ds_read_b128 v[206:209], v148 offset:21504
	ds_read_b128 v[210:213], v148 offset:22528
	ds_read_b128 v[214:217], v148 offset:23552
	global_load_lds_dwordx4 v[194:195], off
	s_add_i32 m0, s56, 0x2000
	v_lshl_add_u64 v[218:219], s[54:55], 0, v[128:129]
	s_add_u32 s54, s54, s4
	s_addc_u32 s55, s55, s5
	s_add_i32 s56, s45, s27
	global_load_lds_dwordx4 v[218:219], off
	v_lshl_add_u64 v[220:221], s[54:55], 0, v[132:133]
	s_mov_b32 m0, s56
	v_lshl_add_u64 v[222:223], s[54:55], 0, v[128:129]
	global_load_lds_dwordx4 v[220:221], off
	s_add_i32 m0, s56, 0x2000
	v_lshl_add_u64 v[224:225], s[24:25], 0, v[134:135]
	global_load_lds_dwordx4 v[222:223], off
	s_mov_b32 m0, s31
	v_lshl_add_u64 v[226:227], s[24:25], 0, v[130:131]
	global_load_lds_dwordx4 v[224:225], off
	s_mov_b32 m0, s34
	s_nop 0
	global_load_lds_dwordx4 v[226:227], off
	s_waitcnt vmcnt(8)
	s_waitcnt lgkmcnt(0)
	s_barrier
; #define PG8_STAGE(bufoff, gbase, voff) do { _Pragma("unroll") for (int _i = 0; _i < 2; ++_i) \
;         __builtin_amdgcn_global_load_lds((const unsigned*)((const char*)(gbase) + (voff)[_i]), (PG8_LAS unsigned*)(lds + (bufoff) + ldsw + _i * 8192), 16, 0, 0); } while (0)
; #define PG8_LDA(dst, b, h) do { _Pragma("unroll") for (int m = 0; m < 4; ++m) _Pragma("unroll") for (int k = 0; k < 2; ++k) dst[m][k] = *(const PG8_LAS bf16x8*)(lds + PG8_SA(b, h) + aoff + m * 2048 + k * 1024); } while (0)
; #define PG8_LDB(dst, b, h) do { _Pragma("unroll") for (int n = 0; n < 2; ++n) _Pragma("unroll") for (int k = 0; k < 2; ++k) dst[n][k] = *(const PG8_LAS bf16x8*)(lds + PG8_SB(b, h) + boff + n * 2048 + k * 1024); } while (0)
; #define PG8_MMA(ai, bj, At, Bt) do { __builtin_amdgcn_s_setprio(1); _Pragma("unroll") for (int m = 0; m < 4; ++m) _Pragma("unroll") for (int n = 0; n < 2; ++n) _Pragma("unroll") for (int k = 0; k < 2; ++k) \
;         acc[ai][bj][m][n] = __builtin_amdgcn_mfma_f32_16x16x32_bf16(Bt[n][k], At[m][k], acc[ai][bj][m][n], 0, 0, 0); __builtin_amdgcn_s_setprio(0); } while (0)
; #define PG8_WAIT_V(n) asm volatile("s_waitcnt vmcnt(" #n ")" ::: "memory")
; #define PG8_WAIT_L(n) asm volatile("s_waitcnt lgkmcnt(" #n ")" ::: "memory")
; #define PG8_BAR __builtin_amdgcn_s_barrier()
; #define PG8_SCHED __builtin_amdgcn_sched_barrier(0)
; template <class Epi, class Sched, bool ALIGN_EPI = false, bool SP2 = false>
; __device__ __forceinline__ void gemm_phase(PG8_LAS unsigned char* lds, const Gemm g, const Sched& S, const Epi& E) {
;     ...
;             PG8_WAIT_V(8); PG8_WAIT_L(0); PG8_BAR; PG8_MMA(1, 0, At, B0); PG8_MMA(1, 1, At, B1); PG8_BAR; PG8_SCHED;
;             PG8_LDB(B0, 1, 0); PG8_LDB(B1, 1, 1); PG8_SCHED; PG8_LDA(At, 1, 0); PG8_STAGE(PG8_SA(0, 1), a2 + hstep, voffA);
;             PG8_WAIT_V(8); PG8_WAIT_L(0); PG8_BAR; PG8_MMA(0, 0, At, B0); PG8_MMA(0, 1, At, B1); PG8_BAR; PG8_SCHED;
	s_waitcnt lgkmcnt(0)
	v_mfma_f32_16x16x32_bf16 v[92:95], v[150:153], v[182:185], v[92:95]
	v_mfma_f32_16x16x32_bf16 v[88:91], v[158:161], v[182:185], v[88:91]
	v_mfma_f32_16x16x32_bf16 v[84:87], v[150:153], v[190:193], v[84:87]
	v_mfma_f32_16x16x32_bf16 v[80:83], v[158:161], v[190:193], v[80:83]
	v_mfma_f32_16x16x32_bf16 v[76:79], v[150:153], v[202:205], v[76:79]
	v_mfma_f32_16x16x32_bf16 v[72:75], v[158:161], v[202:205], v[72:75]
	v_mfma_f32_16x16x32_bf16 v[68:71], v[150:153], v[210:213], v[68:71]
	v_mfma_f32_16x16x32_bf16 v[64:67], v[158:161], v[210:213], v[64:67]
	v_mfma_f32_16x16x32_bf16 v[92:95], v[154:157], v[186:189], v[92:95]
	v_mfma_f32_16x16x32_bf16 v[88:91], v[162:165], v[186:189], v[88:91]
	v_mfma_f32_16x16x32_bf16 v[84:87], v[154:157], v[198:201], v[84:87]
	v_mfma_f32_16x16x32_bf16 v[80:83], v[162:165], v[198:201], v[80:83]
	v_mfma_f32_16x16x32_bf16 v[76:79], v[154:157], v[206:209], v[76:79]
	v_mfma_f32_16x16x32_bf16 v[72:75], v[162:165], v[206:209], v[72:75]
	v_mfma_f32_16x16x32_bf16 v[68:71], v[154:157], v[214:217], v[68:71]
	v_mfma_f32_16x16x32_bf16 v[64:67], v[162:165], v[214:217], v[64:67]
	v_mfma_f32_16x16x32_bf16 v[28:31], v[166:169], v[182:185], v[28:31]
	v_mfma_f32_16x16x32_bf16 v[24:27], v[174:177], v[182:185], v[24:27]
	v_mfma_f32_16x16x32_bf16 v[20:23], v[166:169], v[190:193], v[20:23]
	v_mfma_f32_16x16x32_bf16 v[16:19], v[174:177], v[190:193], v[16:19]
	v_mfma_f32_16x16x32_bf16 v[12:15], v[166:169], v[202:205], v[12:15]
	v_mfma_f32_16x16x32_bf16 v[8:11], v[174:177], v[202:205], v[8:11]
	v_mfma_f32_16x16x32_bf16 v[4:7], v[166:169], v[210:213], v[4:7]
	v_mfma_f32_16x16x32_bf16 v[0:3], v[174:177], v[210:213], v[0:3]
	v_mfma_f32_16x16x32_bf16 v[28:31], v[170:173], v[186:189], v[28:31]
	v_mfma_f32_16x16x32_bf16 v[24:27], v[178:181], v[186:189], v[24:27]
	v_mfma_f32_16x16x32_bf16 v[20:23], v[170:173], v[198:201], v[20:23]
	v_mfma_f32_16x16x32_bf16 v[16:19], v[178:181], v[198:201], v[16:19]
	v_mfma_f32_16x16x32_bf16 v[12:15], v[170:173], v[206:209], v[12:15]
	v_mfma_f32_16x16x32_bf16 v[8:11], v[178:181], v[206:209], v[8:11]
	v_mfma_f32_16x16x32_bf16 v[4:7], v[170:173], v[214:217], v[4:7]
	v_mfma_f32_16x16x32_bf16 v[0:3], v[178:181], v[214:217], v[0:3]
	s_barrier
	s_add_i32 s54, 0, 0x18000
	s_add_i32 s55, 0, 0x1c000
	v_add_u32_e32 v162, s54, v145
	v_add_u32_e32 v178, s55, v145
	ds_read_b128 v[150:153], v162
	ds_read_b128 v[154:157], v162 offset:1024
	ds_read_b128 v[158:161], v162 offset:2048
	ds_read_b128 v[162:165], v162 offset:3072
	ds_read_b128 v[166:169], v178
	ds_read_b128 v[170:173], v178 offset:1024
	ds_read_b128 v[174:177], v178 offset:2048
	ds_read_b128 v[178:181], v178 offset:3072
	s_add_u32 s24, s24, s4
	s_addc_u32 s25, s25, s5
	s_mov_b32 m0, s35
	v_lshl_add_u64 v[228:229], s[24:25], 0, v[134:135]
	ds_read_b128 v[182:185], v148 offset:32768
	ds_read_b128 v[186:189], v148 offset:33792
	ds_read_b128 v[190:193], v148 offset:34816
	ds_read_b128 v[198:201], v148 offset:35840
	ds_read_b128 v[202:205], v148 offset:36864
	ds_read_b128 v[206:209], v148 offset:37888
	ds_read_b128 v[210:213], v148 offset:38912
	ds_read_b128 v[214:217], v148 offset:39936
	global_load_lds_dwordx4 v[228:229], off
	v_lshl_add_u64 v[228:229], s[24:25], 0, v[130:131]
	s_mov_b32 m0, s36
	s_nop 0
	global_load_lds_dwordx4 v[228:229], off
	s_waitcnt vmcnt(8)
	s_waitcnt lgkmcnt(0)
	s_barrier
	s_waitcnt lgkmcnt(0)
	v_mfma_f32_16x16x32_bf16 v[120:123], v[150:153], v[182:185], v[120:123]
	v_mfma_f32_16x16x32_bf16 v[124:127], v[158:161], v[182:185], v[124:127]
	v_mfma_f32_16x16x32_bf16 v[116:119], v[150:153], v[190:193], v[116:119]
	v_mfma_f32_16x16x32_bf16 v[112:115], v[158:161], v[190:193], v[112:115]
	v_mfma_f32_16x16x32_bf16 v[108:111], v[150:153], v[202:205], v[108:111]
	v_mfma_f32_16x16x32_bf16 v[104:107], v[158:161], v[202:205], v[104:107]
	v_mfma_f32_16x16x32_bf16 v[100:103], v[150:153], v[210:213], v[100:103]
	v_mfma_f32_16x16x32_bf16 v[96:99], v[158:161], v[210:213], v[96:99]
	v_mfma_f32_16x16x32_bf16 v[120:123], v[154:157], v[186:189], v[120:123]
	v_mfma_f32_16x16x32_bf16 v[124:127], v[162:165], v[186:189], v[124:127]
	v_mfma_f32_16x16x32_bf16 v[116:119], v[154:157], v[198:201], v[116:119]
	v_mfma_f32_16x16x32_bf16 v[112:115], v[162:165], v[198:201], v[112:115]
	v_mfma_f32_16x16x32_bf16 v[108:111], v[154:157], v[206:209], v[108:111]
	v_mfma_f32_16x16x32_bf16 v[104:107], v[162:165], v[206:209], v[104:107]
	v_mfma_f32_16x16x32_bf16 v[100:103], v[154:157], v[214:217], v[100:103]
	v_mfma_f32_16x16x32_bf16 v[96:99], v[162:165], v[214:217], v[96:99]
	v_mfma_f32_16x16x32_bf16 v[60:63], v[166:169], v[182:185], v[60:63]
	v_mfma_f32_16x16x32_bf16 v[56:59], v[174:177], v[182:185], v[56:59]
	v_mfma_f32_16x16x32_bf16 v[52:55], v[166:169], v[190:193], v[52:55]
	v_mfma_f32_16x16x32_bf16 v[48:51], v[174:177], v[190:193], v[48:51]
	v_mfma_f32_16x16x32_bf16 v[44:47], v[166:169], v[202:205], v[44:47]
	v_mfma_f32_16x16x32_bf16 v[40:43], v[174:177], v[202:205], v[40:43]
	v_mfma_f32_16x16x32_bf16 v[36:39], v[166:169], v[210:213], v[36:39]
	v_mfma_f32_16x16x32_bf16 v[32:35], v[174:177], v[210:213], v[32:35]
	v_mfma_f32_16x16x32_bf16 v[60:63], v[170:173], v[186:189], v[60:63]
	v_mfma_f32_16x16x32_bf16 v[56:59], v[178:181], v[186:189], v[56:59]
	v_mfma_f32_16x16x32_bf16 v[52:55], v[170:173], v[198:201], v[52:55]
	v_mfma_f32_16x16x32_bf16 v[48:51], v[178:181], v[198:201], v[48:51]
	v_mfma_f32_16x16x32_bf16 v[44:47], v[170:173], v[206:209], v[44:47]
	v_mfma_f32_16x16x32_bf16 v[40:43], v[178:181], v[206:209], v[40:43]
	v_mfma_f32_16x16x32_bf16 v[36:39], v[170:173], v[214:217], v[36:39]
	v_mfma_f32_16x16x32_bf16 v[32:35], v[178:181], v[214:217], v[32:35]
	s_barrier
; #define PG8_STAGE(bufoff, gbase, voff) do { _Pragma("unroll") for (int _i = 0; _i < 2; ++_i) \
;         __builtin_amdgcn_global_load_lds((const unsigned*)((const char*)(gbase) + (voff)[_i]), (PG8_LAS unsigned*)(lds + (bufoff) + ldsw + _i * 8192), 16, 0, 0); } while (0)
; #define PG8_LDA(dst, b, h) do { _Pragma("unroll") for (int m = 0; m < 4; ++m) _Pragma("unroll") for (int k = 0; k < 2; ++k) dst[m][k] = *(const PG8_LAS bf16x8*)(lds + PG8_SA(b, h) + aoff + m * 2048 + k * 1024); } while (0)
; #define PG8_MMA(ai, bj, At, Bt) do { __builtin_amdgcn_s_setprio(1); _Pragma("unroll") for (int m = 0; m < 4; ++m) _Pragma("unroll") for (int n = 0; n < 2; ++n) _Pragma("unroll") for (int k = 0; k < 2; ++k) \
;         acc[ai][bj][m][n] = __builtin_amdgcn_mfma_f32_16x16x32_bf16(Bt[n][k], At[m][k], acc[ai][bj][m][n], 0, 0, 0); __builtin_amdgcn_s_setprio(0); } while (0)
; #define PG8_WAIT_V(n) asm volatile("s_waitcnt vmcnt(" #n ")" ::: "memory")
; #define PG8_WAIT_L(n) asm volatile("s_waitcnt lgkmcnt(" #n ")" ::: "memory")
; #define PG8_BAR __builtin_amdgcn_s_barrier()
; #define PG8_SCHED __builtin_amdgcn_sched_barrier(0)
; template <class Epi, class Sched, bool ALIGN_EPI = false, bool SP2 = false>
; __device__ __forceinline__ void gemm_phase(PG8_LAS unsigned char* lds, const Gemm g, const Sched& S, const Epi& E) {
;     ...
;         for (int t = 0; t < nt; t += 2) {
;     ...
;             PG8_LDA(At, 1, 1); PG8_STAGE(PG8_SB(1, 0), b3, voffB); PG8_STAGE(PG8_SB(1, 1), b3 + hstep, voffB); PG8_STAGE(PG8_SA(1, 0), a3, voffA);
;             PG8_WAIT_V(8); PG8_WAIT_L(0); PG8_BAR; PG8_MMA(1, 0, At, B0); PG8_MMA(1, 1, At, B1); PG8_BAR; PG8_SCHED;
	s_add_i32 s24, s54, s27
	v_lshl_add_u64 v[194:195], v[194:195], 0, s[14:15]
	s_mov_b32 m0, s24
	ds_read_b128 v[182:185], v148 offset:49152
	ds_read_b128 v[186:189], v148 offset:50176
	ds_read_b128 v[190:193], v148 offset:51200
	ds_read_b128 v[198:201], v148 offset:52224
	ds_read_b128 v[202:205], v148 offset:53248
	ds_read_b128 v[206:209], v148 offset:54272
	ds_read_b128 v[210:213], v148 offset:55296
	ds_read_b128 v[214:217], v148 offset:56320
	global_load_lds_dwordx4 v[194:195], off
	v_lshl_add_u64 v[194:195], v[218:219], 0, s[14:15]
	s_add_i32 m0, s24, 0x2000
	s_add_i32 s24, s55, s27
	global_load_lds_dwordx4 v[194:195], off
	v_lshl_add_u64 v[194:195], v[220:221], 0, s[14:15]
	s_mov_b32 m0, s24
	s_nop 0
	global_load_lds_dwordx4 v[194:195], off
	v_lshl_add_u64 v[194:195], v[222:223], 0, s[14:15]
	s_add_i32 m0, s24, 0x2000
	s_nop 0
	global_load_lds_dwordx4 v[194:195], off
	v_lshl_add_u64 v[194:195], v[224:225], 0, s[14:15]
	s_mov_b32 m0, s40
	s_nop 0
	global_load_lds_dwordx4 v[194:195], off
	v_lshl_add_u64 v[194:195], v[226:227], 0, s[14:15]
	s_mov_b32 m0, s41
	s_nop 0
	global_load_lds_dwordx4 v[194:195], off
	s_waitcnt vmcnt(8)
	s_waitcnt lgkmcnt(0)
	s_barrier
	s_waitcnt lgkmcnt(0)
	v_mfma_f32_16x16x32_bf16 v[92:95], v[150:153], v[182:185], v[92:95]
	v_mfma_f32_16x16x32_bf16 v[88:91], v[158:161], v[182:185], v[88:91]
	v_mfma_f32_16x16x32_bf16 v[84:87], v[150:153], v[190:193], v[84:87]
	v_mfma_f32_16x16x32_bf16 v[80:83], v[158:161], v[190:193], v[80:83]
	v_mfma_f32_16x16x32_bf16 v[76:79], v[150:153], v[202:205], v[76:79]
	v_mfma_f32_16x16x32_bf16 v[72:75], v[158:161], v[202:205], v[72:75]
	v_mfma_f32_16x16x32_bf16 v[68:71], v[150:153], v[210:213], v[68:71]
	v_mfma_f32_16x16x32_bf16 v[64:67], v[158:161], v[210:213], v[64:67]
	v_mfma_f32_16x16x32_bf16 v[92:95], v[154:157], v[186:189], v[92:95]
	v_mfma_f32_16x16x32_bf16 v[88:91], v[162:165], v[186:189], v[88:91]
	v_mfma_f32_16x16x32_bf16 v[84:87], v[154:157], v[198:201], v[84:87]
	v_mfma_f32_16x16x32_bf16 v[80:83], v[162:165], v[198:201], v[80:83]
	v_mfma_f32_16x16x32_bf16 v[76:79], v[154:157], v[206:209], v[76:79]
	v_mfma_f32_16x16x32_bf16 v[72:75], v[162:165], v[206:209], v[72:75]
	v_mfma_f32_16x16x32_bf16 v[68:71], v[154:157], v[214:217], v[68:71]
	v_mfma_f32_16x16x32_bf16 v[64:67], v[162:165], v[214:217], v[64:67]
	v_mfma_f32_16x16x32_bf16 v[28:31], v[166:169], v[182:185], v[28:31]
	v_mfma_f32_16x16x32_bf16 v[24:27], v[174:177], v[182:185], v[24:27]
	v_mfma_f32_16x16x32_bf16 v[20:23], v[166:169], v[190:193], v[20:23]
	v_mfma_f32_16x16x32_bf16 v[16:19], v[174:177], v[190:193], v[16:19]
	v_mfma_f32_16x16x32_bf16 v[12:15], v[166:169], v[202:205], v[12:15]
	v_mfma_f32_16x16x32_bf16 v[8:11], v[174:177], v[202:205], v[8:11]
	v_mfma_f32_16x16x32_bf16 v[4:7], v[166:169], v[210:213], v[4:7]
	v_mfma_f32_16x16x32_bf16 v[0:3], v[174:177], v[210:213], v[0:3]
	v_mfma_f32_16x16x32_bf16 v[28:31], v[170:173], v[186:189], v[28:31]
	v_mfma_f32_16x16x32_bf16 v[24:27], v[178:181], v[186:189], v[24:27]
	v_mfma_f32_16x16x32_bf16 v[20:23], v[170:173], v[198:201], v[20:23]
	v_mfma_f32_16x16x32_bf16 v[16:19], v[178:181], v[198:201], v[16:19]
	v_mfma_f32_16x16x32_bf16 v[12:15], v[170:173], v[206:209], v[12:15]
	v_mfma_f32_16x16x32_bf16 v[8:11], v[178:181], v[206:209], v[8:11]
	v_mfma_f32_16x16x32_bf16 v[4:7], v[170:173], v[214:217], v[4:7]
	v_mfma_f32_16x16x32_bf16 v[0:3], v[178:181], v[214:217], v[0:3]
	s_barrier
	s_add_u32 s22, s22, 0x100
	s_addc_u32 s23, s23, 0
	s_add_u32 s51, s51, 0x100
	s_addc_u32 s52, s52, 0
	s_cmp_ge_i32 s53, s38
	s_mov_b32 s24, s53
	s_cbranch_scc0 .LBB0_757
	s_setprio 0

; template <class Epi, class Sched, bool ALIGN_EPI = false, bool SP2 = false>
; __device__ __forceinline__ void gemm_phase(PG8_LAS unsigned char* lds, const Gemm g, const Sched& S, const Epi& E) {
;     ...
;         const bool has_next = S.next(ui + 1, nxt);
;         const char* nA = has_next ? (const char*)g.A + (size_t)nxt.pm * tstep : cA; const char* nB = has_next ? (const char*)g.Bt + (size_t)nxt.pn * tstep : cB;
;     ...
; #pragma unroll
;         for (int a = 0; a < 2; ++a)
; #pragma unroll
;             for (int b = 0; b < 2; ++b)
; #pragma unroll
;                 for (int m = 0; m < 4; ++m)
; #pragma unroll
;                     for (int n = 0; n < 2; ++n) acc[a][b][m][n] = (f32x4){0.f, 0.f, 0.f, 0.f};
;         cur = nxt; cA = nA; cB = nB; ++ui;
.LBB0_990:
	s_ashr_i32 s17, s16, 31
	s_lshl_b64 s[18:19], s[16:17], 19
	v_readlane_b32 s20, v253, 45
	v_readlane_b32 s21, v253, 46
	s_add_u32 s18, s20, s18
	s_addc_u32 s19, s21, s19
	s_and_b64 s[20:21], s[2:3], exec
	s_cselect_b32 s17, s19, s25
	s_cselect_b32 s23, s18, s24
	s_ashr_i32 s15, s14, 31
	s_lshl_b64 s[20:21], s[14:15], 19
	s_add_u32 s20, s52, s20
	s_addc_u32 s21, s53, s21
	s_and_b64 s[28:29], s[2:3], exec
	s_cselect_b32 s15, s21, s27
	s_cselect_b32 s45, s20, s26
	s_add_u32 s24, s24, 0x40080
	s_addc_u32 s25, s25, 0
	s_add_u32 s46, s26, 0x100
	v_mov_b32_e32 v0, 0
	s_addc_u32 s47, s27, 0
	s_mov_b32 s48, -2
	v_mov_b32_e32 v1, v0
	v_mov_b32_e32 v2, v0
	v_mov_b32_e32 v3, v0
	v_mov_b32_e32 v4, v0
	s_waitcnt lgkmcnt(0)
	v_mov_b32_e32 v5, v0
	v_mov_b32_e32 v6, v0
	v_mov_b32_e32 v7, v0
	v_mov_b32_e32 v16, v0
	v_mov_b32_e32 v17, v0
	v_mov_b32_e32 v18, v0
	v_mov_b32_e32 v19, v0
	v_mov_b32_e32 v20, v0
	v_mov_b32_e32 v21, v0
	v_mov_b32_e32 v22, v0
	v_mov_b32_e32 v23, v0
	v_mov_b32_e32 v32, v0
	v_mov_b32_e32 v33, v0
	v_mov_b32_e32 v34, v0
	v_mov_b32_e32 v35, v0
	v_mov_b32_e32 v36, v0
	v_mov_b32_e32 v37, v0
	v_mov_b32_e32 v38, v0
	v_mov_b32_e32 v39, v0
	v_mov_b32_e32 v48, v0
	v_mov_b32_e32 v49, v0
	v_mov_b32_e32 v50, v0
	v_mov_b32_e32 v51, v0
	v_mov_b32_e32 v52, v0
	v_mov_b32_e32 v53, v0
	v_mov_b32_e32 v54, v0
	v_mov_b32_e32 v55, v0
	v_mov_b32_e32 v8, v0
	v_mov_b32_e32 v9, v0
	v_mov_b32_e32 v10, v0
	v_mov_b32_e32 v11, v0
	v_mov_b32_e32 v12, v0
	v_mov_b32_e32 v13, v0
	v_mov_b32_e32 v14, v0
	v_mov_b32_e32 v15, v0
	v_mov_b32_e32 v24, v0
	v_mov_b32_e32 v25, v0
	v_mov_b32_e32 v26, v0
	v_mov_b32_e32 v27, v0
	v_mov_b32_e32 v28, v0
	v_mov_b32_e32 v29, v0
	v_mov_b32_e32 v30, v0
	v_mov_b32_e32 v31, v0
	v_mov_b32_e32 v40, v0
	v_mov_b32_e32 v41, v0
	v_mov_b32_e32 v42, v0
	v_mov_b32_e32 v43, v0
	v_mov_b32_e32 v44, v0
	v_mov_b32_e32 v45, v0
	v_mov_b32_e32 v46, v0
	v_mov_b32_e32 v47, v0
	v_mov_b32_e32 v56, v0
	v_mov_b32_e32 v57, v0
	v_mov_b32_e32 v58, v0
	v_mov_b32_e32 v59, v0
	v_mov_b32_e32 v60, v0
	v_mov_b32_e32 v61, v0
	v_mov_b32_e32 v62, v0
	v_mov_b32_e32 v63, v0
	v_mov_b32_e32 v64, v0
	v_mov_b32_e32 v65, v0
	v_mov_b32_e32 v66, v0
	v_mov_b32_e32 v67, v0
	v_mov_b32_e32 v68, v0
	v_mov_b32_e32 v69, v0
	v_mov_b32_e32 v70, v0
	v_mov_b32_e32 v71, v0
	v_mov_b32_e32 v80, v0
	v_mov_b32_e32 v81, v0
	v_mov_b32_e32 v82, v0
	v_mov_b32_e32 v83, v0
	v_mov_b32_e32 v84, v0
	v_mov_b32_e32 v85, v0
	v_mov_b32_e32 v86, v0
	v_mov_b32_e32 v87, v0
	v_mov_b32_e32 v96, v0
	v_mov_b32_e32 v97, v0
	v_mov_b32_e32 v98, v0
	v_mov_b32_e32 v99, v0
	v_mov_b32_e32 v100, v0
	v_mov_b32_e32 v101, v0
	v_mov_b32_e32 v102, v0
	v_mov_b32_e32 v103, v0
	v_mov_b32_e32 v112, v0
	v_mov_b32_e32 v113, v0
	v_mov_b32_e32 v114, v0
	v_mov_b32_e32 v115, v0
	v_mov_b32_e32 v116, v0
	v_mov_b32_e32 v117, v0
	v_mov_b32_e32 v118, v0
	v_mov_b32_e32 v119, v0
	v_mov_b32_e32 v72, v0
	v_mov_b32_e32 v73, v0
	v_mov_b32_e32 v74, v0
	v_mov_b32_e32 v75, v0
	v_mov_b32_e32 v76, v0
	v_mov_b32_e32 v77, v0
	v_mov_b32_e32 v78, v0
	v_mov_b32_e32 v79, v0
	v_mov_b32_e32 v88, v0
	v_mov_b32_e32 v89, v0
	v_mov_b32_e32 v90, v0
	v_mov_b32_e32 v91, v0
	v_mov_b32_e32 v92, v0
	v_mov_b32_e32 v93, v0
	v_mov_b32_e32 v94, v0
	v_mov_b32_e32 v95, v0
	v_mov_b32_e32 v104, v0
	v_mov_b32_e32 v105, v0
	v_mov_b32_e32 v106, v0
	v_mov_b32_e32 v107, v0
	v_mov_b32_e32 v108, v0
	v_mov_b32_e32 v109, v0
	v_mov_b32_e32 v110, v0
	v_mov_b32_e32 v111, v0
	v_mov_b32_e32 v120, v0
	v_mov_b32_e32 v121, v0
	v_mov_b32_e32 v122, v0
	v_mov_b32_e32 v123, v0
	v_mov_b32_e32 v124, v0
	v_mov_b32_e32 v125, v0
	v_mov_b32_e32 v126, v0
	v_mov_b32_e32 v127, v0
	v_readfirstlane_b32 s98, v197
	s_nop 3
	s_cmpk_gt_u32 s98, 0xff
	s_cbranch_scc0 .Lkp_2
	s_setprio 1
.Lkp_2:
.LBB0_991:
	s_cmp_eq_u32 s48, -2
	s_cbranch_scc0 .Lp9h_a
	v_lshl_add_u32 v144, s22, 8, v148
	v_lshlrev_b32_e32 v144, 5, v144
	v_lshrrev_b32_e32 v145, 4, v154
	v_lshl_add_u32 v144, v145, 3, v144
	s_add_u32 s98, s64, 0x13bec000
	s_addc_u32 s99, s65, 0
	s_add_u32 s100, s98, 0x1000
	s_addc_u32 s101, s99, 0
	global_load_dwordx2 v[230:231], v144, s[98:99]
	global_load_dwordx2 v[232:233], v144, s[98:99] offset:512
	global_load_dwordx2 v[234:235], v144, s[98:99] offset:1024
	global_load_dwordx2 v[236:237], v144, s[98:99] offset:1536
	global_load_dwordx2 v[238:239], v144, s[100:101]
	global_load_dwordx2 v[240:241], v144, s[100:101] offset:512
	global_load_dwordx2 v[242:243], v144, s[100:101] offset:1024
	global_load_dwordx2 v[244:245], v144, s[100:101] offset:1536

; #define PG8_STAGE(bufoff, gbase, voff) do { _Pragma("unroll") for (int _i = 0; _i < 2; ++_i) \
;         __builtin_amdgcn_global_load_lds((const unsigned*)((const char*)(gbase) + (voff)[_i]), (PG8_LAS unsigned*)(lds + (bufoff) + ldsw + _i * 8192), 16, 0, 0); } while (0)
; #define PG8_LDA(dst, b, h) do { _Pragma("unroll") for (int m = 0; m < 4; ++m) _Pragma("unroll") for (int k = 0; k < 2; ++k) dst[m][k] = *(const PG8_LAS bf16x8*)(lds + PG8_SA(b, h) + aoff + m * 2048 + k * 1024); } while (0)
; #define PG8_LDB(dst, b, h) do { _Pragma("unroll") for (int n = 0; n < 2; ++n) _Pragma("unroll") for (int k = 0; k < 2; ++k) dst[n][k] = *(const PG8_LAS bf16x8*)(lds + PG8_SB(b, h) + boff + n * 2048 + k * 1024); } while (0)
; #define PG8_MMA(ai, bj, At, Bt) do { __builtin_amdgcn_s_setprio(1); _Pragma("unroll") for (int m = 0; m < 4; ++m) _Pragma("unroll") for (int n = 0; n < 2; ++n) _Pragma("unroll") for (int k = 0; k < 2; ++k) \
;         acc[ai][bj][m][n] = __builtin_amdgcn_mfma_f32_16x16x32_bf16(Bt[n][k], At[m][k], acc[ai][bj][m][n], 0, 0, 0); __builtin_amdgcn_s_setprio(0); } while (0)
; #define PG8_WAIT_V(n) asm volatile("s_waitcnt vmcnt(" #n ")" ::: "memory")
; #define PG8_WAIT_L(n) asm volatile("s_waitcnt lgkmcnt(" #n ")" ::: "memory")
; #define PG8_BAR __builtin_amdgcn_s_barrier()
; template <class Epi, class Sched, bool ALIGN_EPI = false, bool SP2 = false>
; __device__ __forceinline__ void gemm_phase(PG8_LAS unsigned char* lds, const Gemm g, const Sched& S, const Epi& E) {
;     ...
;             const char* a1 = cA + (size_t)(t + 1) * kstep;
;             const char* a2 = last ? nA : cA + (size_t)(t + 2) * kstep; const char* b2 = last ? nB : cB + (size_t)(t + 2) * kstep;
;             const char* a3 = a2 + kstep; const char* b3 = b2 + kstep;
;             if (last && has_next) S.a_ready(nxt);
;             if constexpr (SP2) {
;             PG8_LDB(B0, 0, 0); PG8_LDB(B1, 0, 1); PG8_SCHED; PG8_LDA(At, 0, 0); PG8_STAGE(PG8_SA(1, 1), a1 + hstep, voffA);
;             PG8_WAIT_V(8); PG8_WAIT_L(0); PG8_BAR; PG8_MMA(0, 0, At, B0); PG8_MMA(0, 1, At, B1); PG8_BAR; PG8_SCHED;
;             PG8_LDA(At, 0, 1); PG8_STAGE(PG8_SB(0, 0), b2, voffB); PG8_STAGE(PG8_SB(0, 1), b2 + hstep, voffB); PG8_STAGE(PG8_SA(0, 0), a2, voffA);
;             PG8_WAIT_V(8); PG8_WAIT_L(0); PG8_BAR; PG8_MMA(1, 0, At, B0); PG8_MMA(1, 1, At, B1); PG8_BAR; PG8_SCHED;
.Lp9h_b:
	ds_read_b128 v[144:147], v151
	ds_read_b128 v[156:159], v151 offset:1024
	ds_read_b128 v[160:163], v151 offset:2048
	ds_read_b128 v[164:167], v151 offset:3072
	ds_read_b128 v[168:171], v152
	ds_read_b128 v[172:175], v152 offset:1024
	ds_read_b128 v[176:179], v152 offset:2048
	ds_read_b128 v[180:183], v152 offset:3072
	s_add_u32 s26, s24, 0xfffc0080
	s_addc_u32 s27, s25, -1
	s_cmp_eq_u32 s48, 12
	s_cselect_b32 s29, s17, s27
	s_cselect_b32 s28, s23, s26
	s_cselect_b32 s27, s15, s47
	s_cselect_b32 s26, s45, s46
	v_lshl_add_u64 v[218:219], s[24:25], 0, v[136:137]
	s_add_i32 m0, s31, 0xc000
	ds_read_b128 v[184:187], v153
	ds_read_b128 v[188:191], v153 offset:1024
	ds_read_b128 v[192:195], v153 offset:2048
	ds_read_b128 v[198:201], v153 offset:3072
	ds_read_b128 v[202:205], v153 offset:4096
	ds_read_b128 v[206:209], v153 offset:5120
	ds_read_b128 v[210:213], v153 offset:6144
	ds_read_b128 v[214:217], v153 offset:7168
	global_load_lds_dwordx4 v[218:219], off
	v_lshl_add_u64 v[218:219], s[24:25], 0, v[138:139]
	s_add_i32 m0, s31, 0xe000
	s_nop 0
	global_load_lds_dwordx4 v[218:219], off
	s_waitcnt vmcnt(8)
	s_waitcnt lgkmcnt(0)
	s_barrier
	s_waitcnt lgkmcnt(0)
	v_mfma_f32_16x16x32_bf16 v[124:127], v[144:147], v[184:187], v[124:127]
	v_mfma_f32_16x16x32_bf16 v[120:123], v[160:163], v[184:187], v[120:123]
	v_mfma_f32_16x16x32_bf16 v[108:111], v[144:147], v[192:195], v[108:111]
	v_mfma_f32_16x16x32_bf16 v[104:107], v[160:163], v[192:195], v[104:107]
	v_mfma_f32_16x16x32_bf16 v[92:95], v[144:147], v[202:205], v[92:95]
	v_mfma_f32_16x16x32_bf16 v[88:91], v[160:163], v[202:205], v[88:91]
	v_mfma_f32_16x16x32_bf16 v[76:79], v[144:147], v[210:213], v[76:79]
	v_mfma_f32_16x16x32_bf16 v[72:75], v[160:163], v[210:213], v[72:75]
	v_mfma_f32_16x16x32_bf16 v[124:127], v[156:159], v[188:191], v[124:127]
	v_mfma_f32_16x16x32_bf16 v[120:123], v[164:167], v[188:191], v[120:123]
	v_mfma_f32_16x16x32_bf16 v[108:111], v[156:159], v[198:201], v[108:111]
	v_mfma_f32_16x16x32_bf16 v[104:107], v[164:167], v[198:201], v[104:107]
	v_mfma_f32_16x16x32_bf16 v[92:95], v[156:159], v[206:209], v[92:95]
	v_mfma_f32_16x16x32_bf16 v[88:91], v[164:167], v[206:209], v[88:91]
	v_mfma_f32_16x16x32_bf16 v[76:79], v[156:159], v[214:217], v[76:79]
	v_mfma_f32_16x16x32_bf16 v[72:75], v[164:167], v[214:217], v[72:75]
	v_mfma_f32_16x16x32_bf16 v[116:119], v[168:171], v[184:187], v[116:119]
	v_mfma_f32_16x16x32_bf16 v[112:115], v[176:179], v[184:187], v[112:115]
	v_mfma_f32_16x16x32_bf16 v[100:103], v[168:171], v[192:195], v[100:103]
	v_mfma_f32_16x16x32_bf16 v[96:99], v[176:179], v[192:195], v[96:99]
	v_mfma_f32_16x16x32_bf16 v[84:87], v[168:171], v[202:205], v[84:87]
	v_mfma_f32_16x16x32_bf16 v[80:83], v[176:179], v[202:205], v[80:83]
	v_mfma_f32_16x16x32_bf16 v[68:71], v[168:171], v[210:213], v[68:71]
	v_mfma_f32_16x16x32_bf16 v[64:67], v[176:179], v[210:213], v[64:67]
	v_mfma_f32_16x16x32_bf16 v[116:119], v[172:175], v[188:191], v[116:119]
	v_mfma_f32_16x16x32_bf16 v[112:115], v[180:183], v[188:191], v[112:115]
	v_mfma_f32_16x16x32_bf16 v[100:103], v[172:175], v[198:201], v[100:103]
	v_mfma_f32_16x16x32_bf16 v[96:99], v[180:183], v[198:201], v[96:99]
	v_mfma_f32_16x16x32_bf16 v[84:87], v[172:175], v[206:209], v[84:87]
	v_mfma_f32_16x16x32_bf16 v[80:83], v[180:183], v[206:209], v[80:83]
	v_mfma_f32_16x16x32_bf16 v[68:71], v[172:175], v[214:217], v[68:71]
	v_mfma_f32_16x16x32_bf16 v[64:67], v[180:183], v[214:217], v[64:67]
	s_barrier
	s_add_i32 s49, s42, s30
	v_lshl_add_u64 v[218:219], s[26:27], 0, v[130:131]
	s_mov_b32 m0, s49
	ds_read_b128 v[184:187], v153 offset:16384
	ds_read_b128 v[188:191], v153 offset:17408
	ds_read_b128 v[192:195], v153 offset:18432
	ds_read_b128 v[198:201], v153 offset:19456
	ds_read_b128 v[202:205], v153 offset:20480
	ds_read_b128 v[206:209], v153 offset:21504
	ds_read_b128 v[210:213], v153 offset:22528
	ds_read_b128 v[214:217], v153 offset:23552
	global_load_lds_dwordx4 v[218:219], off
	s_add_i32 m0, s49, 0x2000
	s_add_u32 s50, s26, 0x40000
	v_lshl_add_u64 v[220:221], s[26:27], 0, v[134:135]
	s_addc_u32 s51, s27, 0
	s_add_i32 s49, s43, s30
	global_load_lds_dwordx4 v[220:221], off
	v_lshl_add_u64 v[222:223], s[50:51], 0, v[130:131]
	s_mov_b32 m0, s49
	v_lshl_add_u64 v[224:225], s[28:29], 0, v[132:133]
	global_load_lds_dwordx4 v[222:223], off
	v_lshl_add_u64 v[222:223], s[50:51], 0, v[134:135]
	s_add_i32 m0, s49, 0x2000
	s_nop 0
	global_load_lds_dwordx4 v[222:223], off
	v_lshl_add_u64 v[222:223], s[28:29], 0, v[128:129]
	s_mov_b32 m0, s31
	s_nop 0
	global_load_lds_dwordx4 v[222:223], off
	s_mov_b32 m0, s33
	s_nop 0
	global_load_lds_dwordx4 v[224:225], off
	s_waitcnt vmcnt(8)
	s_waitcnt lgkmcnt(0)
	s_barrier
; #define PG8_STAGE(bufoff, gbase, voff) do { _Pragma("unroll") for (int _i = 0; _i < 2; ++_i) \
;         __builtin_amdgcn_global_load_lds((const unsigned*)((const char*)(gbase) + (voff)[_i]), (PG8_LAS unsigned*)(lds + (bufoff) + ldsw + _i * 8192), 16, 0, 0); } while (0)
; #define PG8_LDA(dst, b, h) do { _Pragma("unroll") for (int m = 0; m < 4; ++m) _Pragma("unroll") for (int k = 0; k < 2; ++k) dst[m][k] = *(const PG8_LAS bf16x8*)(lds + PG8_SA(b, h) + aoff + m * 2048 + k * 1024); } while (0)
; #define PG8_LDB(dst, b, h) do { _Pragma("unroll") for (int n = 0; n < 2; ++n) _Pragma("unroll") for (int k = 0; k < 2; ++k) dst[n][k] = *(const PG8_LAS bf16x8*)(lds + PG8_SB(b, h) + boff + n * 2048 + k * 1024); } while (0)
; #define PG8_MMA(ai, bj, At, Bt) do { __builtin_amdgcn_s_setprio(1); _Pragma("unroll") for (int m = 0; m < 4; ++m) _Pragma("unroll") for (int n = 0; n < 2; ++n) _Pragma("unroll") for (int k = 0; k < 2; ++k) \
;         acc[ai][bj][m][n] = __builtin_amdgcn_mfma_f32_16x16x32_bf16(Bt[n][k], At[m][k], acc[ai][bj][m][n], 0, 0, 0); __builtin_amdgcn_s_setprio(0); } while (0)
; #define PG8_WAIT_V(n) asm volatile("s_waitcnt vmcnt(" #n ")" ::: "memory")
; #define PG8_WAIT_L(n) asm volatile("s_waitcnt lgkmcnt(" #n ")" ::: "memory")
; #define PG8_BAR __builtin_amdgcn_s_barrier()
; #define PG8_SCHED __builtin_amdgcn_sched_barrier(0)
; template <class Epi, class Sched, bool ALIGN_EPI = false, bool SP2 = false>
; __device__ __forceinline__ void gemm_phase(PG8_LAS unsigned char* lds, const Gemm g, const Sched& S, const Epi& E) {
;     ...
;             PG8_WAIT_V(8); PG8_WAIT_L(0); PG8_BAR; PG8_MMA(1, 0, At, B0); PG8_MMA(1, 1, At, B1); PG8_BAR; PG8_SCHED;
;             PG8_LDB(B0, 1, 0); PG8_LDB(B1, 1, 1); PG8_SCHED; PG8_LDA(At, 1, 0); PG8_STAGE(PG8_SA(0, 1), a2 + hstep, voffA);
;             PG8_WAIT_V(8); PG8_WAIT_L(0); PG8_BAR; PG8_MMA(0, 0, At, B0); PG8_MMA(0, 1, At, B1); PG8_BAR; PG8_SCHED;
	s_waitcnt lgkmcnt(0)
	v_mfma_f32_16x16x32_bf16 v[60:63], v[144:147], v[184:187], v[60:63]
	v_mfma_f32_16x16x32_bf16 v[56:59], v[160:163], v[184:187], v[56:59]
	v_mfma_f32_16x16x32_bf16 v[44:47], v[144:147], v[192:195], v[44:47]
	v_mfma_f32_16x16x32_bf16 v[40:43], v[160:163], v[192:195], v[40:43]
	v_mfma_f32_16x16x32_bf16 v[28:31], v[144:147], v[202:205], v[28:31]
	v_mfma_f32_16x16x32_bf16 v[24:27], v[160:163], v[202:205], v[24:27]
	v_mfma_f32_16x16x32_bf16 v[12:15], v[144:147], v[210:213], v[12:15]
	v_mfma_f32_16x16x32_bf16 v[8:11], v[160:163], v[210:213], v[8:11]
	v_mfma_f32_16x16x32_bf16 v[60:63], v[156:159], v[188:191], v[60:63]
	v_mfma_f32_16x16x32_bf16 v[56:59], v[164:167], v[188:191], v[56:59]
	v_mfma_f32_16x16x32_bf16 v[44:47], v[156:159], v[198:201], v[44:47]
	v_mfma_f32_16x16x32_bf16 v[40:43], v[164:167], v[198:201], v[40:43]
	v_mfma_f32_16x16x32_bf16 v[28:31], v[156:159], v[206:209], v[28:31]
	v_mfma_f32_16x16x32_bf16 v[24:27], v[164:167], v[206:209], v[24:27]
	v_mfma_f32_16x16x32_bf16 v[12:15], v[156:159], v[214:217], v[12:15]
	v_mfma_f32_16x16x32_bf16 v[8:11], v[164:167], v[214:217], v[8:11]
	v_mfma_f32_16x16x32_bf16 v[52:55], v[168:171], v[184:187], v[52:55]
	v_mfma_f32_16x16x32_bf16 v[48:51], v[176:179], v[184:187], v[48:51]
	v_mfma_f32_16x16x32_bf16 v[36:39], v[168:171], v[192:195], v[36:39]
	v_mfma_f32_16x16x32_bf16 v[32:35], v[176:179], v[192:195], v[32:35]
	v_mfma_f32_16x16x32_bf16 v[20:23], v[168:171], v[202:205], v[20:23]
	v_mfma_f32_16x16x32_bf16 v[16:19], v[176:179], v[202:205], v[16:19]
	v_mfma_f32_16x16x32_bf16 v[4:7], v[168:171], v[210:213], v[4:7]
	v_mfma_f32_16x16x32_bf16 v[0:3], v[176:179], v[210:213], v[0:3]
	v_mfma_f32_16x16x32_bf16 v[52:55], v[172:175], v[188:191], v[52:55]
	v_mfma_f32_16x16x32_bf16 v[48:51], v[180:183], v[188:191], v[48:51]
	v_mfma_f32_16x16x32_bf16 v[36:39], v[172:175], v[198:201], v[36:39]
	v_mfma_f32_16x16x32_bf16 v[32:35], v[180:183], v[198:201], v[32:35]
	v_mfma_f32_16x16x32_bf16 v[20:23], v[172:175], v[206:209], v[20:23]
	v_mfma_f32_16x16x32_bf16 v[16:19], v[180:183], v[206:209], v[16:19]
	v_mfma_f32_16x16x32_bf16 v[4:7], v[172:175], v[214:217], v[4:7]
	v_mfma_f32_16x16x32_bf16 v[0:3], v[180:183], v[214:217], v[0:3]
	s_barrier
	s_add_i32 s49, 0, 0x18000
	v_add_u32_e32 v155, s49, v149
	s_add_i32 s50, 0, 0x1c000
	ds_read_b128 v[144:147], v155
	ds_read_b128 v[156:159], v155 offset:1024
	ds_read_b128 v[160:163], v155 offset:2048
	ds_read_b128 v[164:167], v155 offset:3072
	v_add_u32_e32 v155, s50, v149
	ds_read_b128 v[168:171], v155
	ds_read_b128 v[172:175], v155 offset:1024
	ds_read_b128 v[176:179], v155 offset:2048
	ds_read_b128 v[180:183], v155 offset:3072
	s_add_u32 s28, s28, 0x40000
	s_addc_u32 s29, s29, 0
	s_mov_b32 m0, s34
	v_lshl_add_u64 v[226:227], s[28:29], 0, v[128:129]
	ds_read_b128 v[184:187], v153 offset:32768
	ds_read_b128 v[188:191], v153 offset:33792
	ds_read_b128 v[192:195], v153 offset:34816
	ds_read_b128 v[198:201], v153 offset:35840
	ds_read_b128 v[202:205], v153 offset:36864
	ds_read_b128 v[206:209], v153 offset:37888
	ds_read_b128 v[210:213], v153 offset:38912
	ds_read_b128 v[214:217], v153 offset:39936
	global_load_lds_dwordx4 v[226:227], off
	v_lshl_add_u64 v[226:227], s[28:29], 0, v[132:133]
	s_mov_b32 m0, s35
	s_nop 0
	global_load_lds_dwordx4 v[226:227], off
	s_waitcnt vmcnt(8)
	s_waitcnt lgkmcnt(0)
	s_barrier
	s_waitcnt lgkmcnt(0)
	v_mfma_f32_16x16x32_bf16 v[124:127], v[144:147], v[184:187], v[124:127]
	v_mfma_f32_16x16x32_bf16 v[120:123], v[160:163], v[184:187], v[120:123]
	v_mfma_f32_16x16x32_bf16 v[108:111], v[144:147], v[192:195], v[108:111]
	v_mfma_f32_16x16x32_bf16 v[104:107], v[160:163], v[192:195], v[104:107]
	v_mfma_f32_16x16x32_bf16 v[92:95], v[144:147], v[202:205], v[92:95]
	v_mfma_f32_16x16x32_bf16 v[88:91], v[160:163], v[202:205], v[88:91]
	v_mfma_f32_16x16x32_bf16 v[76:79], v[144:147], v[210:213], v[76:79]
	v_mfma_f32_16x16x32_bf16 v[72:75], v[160:163], v[210:213], v[72:75]
	v_mfma_f32_16x16x32_bf16 v[124:127], v[156:159], v[188:191], v[124:127]
	v_mfma_f32_16x16x32_bf16 v[120:123], v[164:167], v[188:191], v[120:123]
	v_mfma_f32_16x16x32_bf16 v[108:111], v[156:159], v[198:201], v[108:111]
	v_mfma_f32_16x16x32_bf16 v[104:107], v[164:167], v[198:201], v[104:107]
	v_mfma_f32_16x16x32_bf16 v[92:95], v[156:159], v[206:209], v[92:95]
	v_mfma_f32_16x16x32_bf16 v[88:91], v[164:167], v[206:209], v[88:91]
	v_mfma_f32_16x16x32_bf16 v[76:79], v[156:159], v[214:217], v[76:79]
	v_mfma_f32_16x16x32_bf16 v[72:75], v[164:167], v[214:217], v[72:75]
	v_mfma_f32_16x16x32_bf16 v[116:119], v[168:171], v[184:187], v[116:119]
	v_mfma_f32_16x16x32_bf16 v[112:115], v[176:179], v[184:187], v[112:115]
	v_mfma_f32_16x16x32_bf16 v[100:103], v[168:171], v[192:195], v[100:103]
	v_mfma_f32_16x16x32_bf16 v[96:99], v[176:179], v[192:195], v[96:99]
	v_mfma_f32_16x16x32_bf16 v[84:87], v[168:171], v[202:205], v[84:87]
	v_mfma_f32_16x16x32_bf16 v[80:83], v[176:179], v[202:205], v[80:83]
	v_mfma_f32_16x16x32_bf16 v[68:71], v[168:171], v[210:213], v[68:71]
	v_mfma_f32_16x16x32_bf16 v[64:67], v[176:179], v[210:213], v[64:67]
	v_mfma_f32_16x16x32_bf16 v[116:119], v[172:175], v[188:191], v[116:119]
	v_mfma_f32_16x16x32_bf16 v[112:115], v[180:183], v[188:191], v[112:115]
	v_mfma_f32_16x16x32_bf16 v[100:103], v[172:175], v[198:201], v[100:103]
	v_mfma_f32_16x16x32_bf16 v[96:99], v[180:183], v[198:201], v[96:99]
	v_mfma_f32_16x16x32_bf16 v[84:87], v[172:175], v[206:209], v[84:87]
	v_mfma_f32_16x16x32_bf16 v[80:83], v[180:183], v[206:209], v[80:83]
	v_mfma_f32_16x16x32_bf16 v[68:71], v[172:175], v[214:217], v[68:71]
	v_mfma_f32_16x16x32_bf16 v[64:67], v[180:183], v[214:217], v[64:67]
	s_barrier
; #define PG8_STAGE(bufoff, gbase, voff) do { _Pragma("unroll") for (int _i = 0; _i < 2; ++_i) \
;         __builtin_amdgcn_global_load_lds((const unsigned*)((const char*)(gbase) + (voff)[_i]), (PG8_LAS unsigned*)(lds + (bufoff) + ldsw + _i * 8192), 16, 0, 0); } while (0)
; #define PG8_LDA(dst, b, h) do { _Pragma("unroll") for (int m = 0; m < 4; ++m) _Pragma("unroll") for (int k = 0; k < 2; ++k) dst[m][k] = *(const PG8_LAS bf16x8*)(lds + PG8_SA(b, h) + aoff + m * 2048 + k * 1024); } while (0)
; #define PG8_MMA(ai, bj, At, Bt) do { __builtin_amdgcn_s_setprio(1); _Pragma("unroll") for (int m = 0; m < 4; ++m) _Pragma("unroll") for (int n = 0; n < 2; ++n) _Pragma("unroll") for (int k = 0; k < 2; ++k) \
;         acc[ai][bj][m][n] = __builtin_amdgcn_mfma_f32_16x16x32_bf16(Bt[n][k], At[m][k], acc[ai][bj][m][n], 0, 0, 0); __builtin_amdgcn_s_setprio(0); } while (0)
; #define PG8_WAIT_V(n) asm volatile("s_waitcnt vmcnt(" #n ")" ::: "memory")
; #define PG8_WAIT_L(n) asm volatile("s_waitcnt lgkmcnt(" #n ")" ::: "memory")
; #define PG8_BAR __builtin_amdgcn_s_barrier()
; #define PG8_SCHED __builtin_amdgcn_sched_barrier(0)
; template <class Epi, class Sched, bool ALIGN_EPI = false, bool SP2 = false>
; __device__ __forceinline__ void gemm_phase(PG8_LAS unsigned char* lds, const Gemm g, const Sched& S, const Epi& E) {
;     ...
;         for (int t = 0; t < nt; t += 2) {
;     ...
;             PG8_LDA(At, 1, 1); PG8_STAGE(PG8_SB(1, 0), b3, voffB); PG8_STAGE(PG8_SB(1, 1), b3 + hstep, voffB); PG8_STAGE(PG8_SA(1, 0), a3, voffA);
;             PG8_WAIT_V(8); PG8_WAIT_L(0); PG8_BAR; PG8_MMA(1, 0, At, B0); PG8_MMA(1, 1, At, B1); PG8_BAR; PG8_SCHED;
;     ...
;         if constexpr (ALIGN_EPI) { if (wr == 0) PG8_BAR; }
	s_add_i32 s28, s49, s30
	v_lshl_add_u64 v[218:219], v[218:219], 0, s[10:11]
	s_mov_b32 m0, s28
	ds_read_b128 v[184:187], v153 offset:49152
	ds_read_b128 v[188:191], v153 offset:50176
	ds_read_b128 v[192:195], v153 offset:51200
	ds_read_b128 v[198:201], v153 offset:52224
	ds_read_b128 v[202:205], v153 offset:53248
	ds_read_b128 v[206:209], v153 offset:54272
	ds_read_b128 v[210:213], v153 offset:55296
	ds_read_b128 v[214:217], v153 offset:56320
	global_load_lds_dwordx4 v[218:219], off
	s_add_i32 m0, s28, 0x2000
	s_add_u32 s26, s26, 0x40080
	v_lshl_add_u64 v[218:219], v[220:221], 0, s[10:11]
	s_addc_u32 s27, s27, 0
	s_add_i32 s28, s50, s30
	global_load_lds_dwordx4 v[218:219], off
	v_lshl_add_u64 v[218:219], s[26:27], 0, v[130:131]
	s_mov_b32 m0, s28
	s_nop 0
	global_load_lds_dwordx4 v[218:219], off
	v_lshl_add_u64 v[218:219], s[26:27], 0, v[134:135]
	s_add_i32 m0, s28, 0x2000
	s_nop 0
	global_load_lds_dwordx4 v[218:219], off
	v_lshl_add_u64 v[218:219], v[222:223], 0, s[10:11]
	s_mov_b32 m0, s39
	s_nop 0
	global_load_lds_dwordx4 v[218:219], off
	v_lshl_add_u64 v[218:219], v[224:225], 0, s[10:11]
	s_mov_b32 m0, s40
	s_nop 0
	global_load_lds_dwordx4 v[218:219], off
	s_waitcnt vmcnt(8)
	s_waitcnt lgkmcnt(0)
	s_barrier
	s_waitcnt lgkmcnt(0)
	v_mfma_f32_16x16x32_bf16 v[60:63], v[144:147], v[184:187], v[60:63]
	v_mfma_f32_16x16x32_bf16 v[56:59], v[160:163], v[184:187], v[56:59]
	v_mfma_f32_16x16x32_bf16 v[44:47], v[144:147], v[192:195], v[44:47]
	v_mfma_f32_16x16x32_bf16 v[40:43], v[160:163], v[192:195], v[40:43]
	v_mfma_f32_16x16x32_bf16 v[28:31], v[144:147], v[202:205], v[28:31]
	v_mfma_f32_16x16x32_bf16 v[24:27], v[160:163], v[202:205], v[24:27]
	v_mfma_f32_16x16x32_bf16 v[12:15], v[144:147], v[210:213], v[12:15]
	v_mfma_f32_16x16x32_bf16 v[8:11], v[160:163], v[210:213], v[8:11]
	v_mfma_f32_16x16x32_bf16 v[60:63], v[156:159], v[188:191], v[60:63]
	v_mfma_f32_16x16x32_bf16 v[56:59], v[164:167], v[188:191], v[56:59]
	v_mfma_f32_16x16x32_bf16 v[44:47], v[156:159], v[198:201], v[44:47]
	v_mfma_f32_16x16x32_bf16 v[40:43], v[164:167], v[198:201], v[40:43]
	v_mfma_f32_16x16x32_bf16 v[28:31], v[156:159], v[206:209], v[28:31]
	v_mfma_f32_16x16x32_bf16 v[24:27], v[164:167], v[206:209], v[24:27]
	v_mfma_f32_16x16x32_bf16 v[12:15], v[156:159], v[214:217], v[12:15]
	v_mfma_f32_16x16x32_bf16 v[8:11], v[164:167], v[214:217], v[8:11]
	v_mfma_f32_16x16x32_bf16 v[52:55], v[168:171], v[184:187], v[52:55]
	v_mfma_f32_16x16x32_bf16 v[48:51], v[176:179], v[184:187], v[48:51]
	v_mfma_f32_16x16x32_bf16 v[36:39], v[168:171], v[192:195], v[36:39]
	v_mfma_f32_16x16x32_bf16 v[32:35], v[176:179], v[192:195], v[32:35]
	v_mfma_f32_16x16x32_bf16 v[20:23], v[168:171], v[202:205], v[20:23]
	v_mfma_f32_16x16x32_bf16 v[16:19], v[176:179], v[202:205], v[16:19]
	v_mfma_f32_16x16x32_bf16 v[4:7], v[168:171], v[210:213], v[4:7]
	v_mfma_f32_16x16x32_bf16 v[0:3], v[176:179], v[210:213], v[0:3]
	v_mfma_f32_16x16x32_bf16 v[52:55], v[172:175], v[188:191], v[52:55]
	v_mfma_f32_16x16x32_bf16 v[48:51], v[180:183], v[188:191], v[48:51]
	v_mfma_f32_16x16x32_bf16 v[36:39], v[172:175], v[198:201], v[36:39]
	v_mfma_f32_16x16x32_bf16 v[32:35], v[180:183], v[198:201], v[32:35]
	v_mfma_f32_16x16x32_bf16 v[20:23], v[172:175], v[206:209], v[20:23]
	v_mfma_f32_16x16x32_bf16 v[16:19], v[180:183], v[206:209], v[16:19]
	v_mfma_f32_16x16x32_bf16 v[4:7], v[172:175], v[214:217], v[4:7]
	v_mfma_f32_16x16x32_bf16 v[0:3], v[180:183], v[214:217], v[0:3]
	s_barrier
	s_add_i32 s48, s48, 2
	s_add_u32 s24, s24, 0x100
	s_addc_u32 s25, s25, 0
	s_add_u32 s46, s46, 0x100
	s_addc_u32 s47, s47, 0
	s_cmp_gt_u32 s48, 13
	s_cbranch_scc0 .LBB0_991
	s_setprio 0
	s_and_b64 vcc, exec, s[12:13]
	s_cbranch_vccz .LBB0_994
	s_barrier

; #define PG8_STAGE(bufoff, gbase, voff) do { _Pragma("unroll") for (int _i = 0; _i < 2; ++_i) \
;         __builtin_amdgcn_global_load_lds((const unsigned*)((const char*)(gbase) + (voff)[_i]), (PG8_LAS unsigned*)(lds + (bufoff) + ldsw + _i * 8192), 16, 0, 0); } while (0)
; #define PG8_LDA(dst, b, h) do { _Pragma("unroll") for (int m = 0; m < 4; ++m) _Pragma("unroll") for (int k = 0; k < 2; ++k) dst[m][k] = *(const PG8_LAS bf16x8*)(lds + PG8_SA(b, h) + aoff + m * 2048 + k * 1024); } while (0)
; #define PG8_LDB(dst, b, h) do { _Pragma("unroll") for (int n = 0; n < 2; ++n) _Pragma("unroll") for (int k = 0; k < 2; ++k) dst[n][k] = *(const PG8_LAS bf16x8*)(lds + PG8_SB(b, h) + boff + n * 2048 + k * 1024); } while (0)
; #define PG8_SCHED __builtin_amdgcn_sched_barrier(0)
; template <class Epi, class Sched, bool ALIGN_EPI = false, bool SP2 = false>
; __device__ __forceinline__ void gemm_phase(PG8_LAS unsigned char* lds, const Gemm g, const Sched& S, const Epi& E) {
;     ...
;         const bool has_next = S.next(ui + 1, nxt);
;         const char* nA = has_next ? (const char*)g.A + (size_t)nxt.pm * tstep : cA; const char* nB = has_next ? (const char*)g.Bt + (size_t)nxt.pn * tstep : cB;
;         for (int t = 0; t < nt; t += 2) {
;             const bool last = (t == nt - 2);
;             const char* a1 = cA + (size_t)(t + 1) * kstep;
;             const char* a2 = last ? nA : cA + (size_t)(t + 2) * kstep; const char* b2 = last ? nB : cB + (size_t)(t + 2) * kstep;
;             const char* a3 = a2 + kstep; const char* b3 = b2 + kstep;
;             if (last && has_next) S.a_ready(nxt);
;             if constexpr (SP2) {
;             PG8_LDB(B0, 0, 0); PG8_LDB(B1, 0, 1); PG8_SCHED; PG8_LDA(At, 0, 0); PG8_STAGE(PG8_SA(1, 1), a1 + hstep, voffA);
;     ...
; #pragma unroll
;         for (int a = 0; a < 2; ++a)
; #pragma unroll
;             for (int b = 0; b < 2; ++b)
; #pragma unroll
;                 for (int m = 0; m < 4; ++m)
; #pragma unroll
;                     for (int n = 0; n < 2; ++n) acc[a][b][m][n] = (f32x4){0.f, 0.f, 0.f, 0.f};
;         cur = nxt; cA = nA; cB = nB; ++ui;
.LBB0_1145:
	s_ashr_i32 s19, s18, 31
	s_lshl_b64 s[20:21], s[18:19], 19
	s_add_u32 s20, s80, s20
	s_addc_u32 s21, s81, s21
	s_and_b64 s[22:23], s[0:1], exec
	s_cselect_b32 s3, s21, s27
	s_cselect_b32 s19, s20, s26
	s_ashr_i32 s17, s16, 31
	s_lshl_b64 s[22:23], s[16:17], 19
	s_add_u32 s22, s56, s22
	s_addc_u32 s23, s57, s23
	s_and_b64 s[30:31], s[0:1], exec
	s_cselect_b32 s17, s23, s29
	s_cselect_b32 s47, s22, s28
	s_add_u32 s26, s26, 0x40080
	s_addc_u32 s27, s27, 0
	s_add_u32 s48, s28, 0x100
	v_mov_b32_e32 v0, 0
	s_addc_u32 s49, s29, 0
	s_mov_b32 s50, -2
	v_mov_b32_e32 v1, v0
	v_mov_b32_e32 v2, v0
	v_mov_b32_e32 v3, v0
	v_mov_b32_e32 v8, v0
	v_mov_b32_e32 v9, v0
	v_mov_b32_e32 v10, v0
	v_mov_b32_e32 v11, v0
	v_mov_b32_e32 v16, v0
	v_mov_b32_e32 v17, v0
	v_mov_b32_e32 v18, v0
	v_mov_b32_e32 v19, v0
	v_mov_b32_e32 v24, v0
	v_mov_b32_e32 v25, v0
	v_mov_b32_e32 v26, v0
	v_mov_b32_e32 v27, v0
	v_mov_b32_e32 v32, v0
	v_mov_b32_e32 v33, v0
	v_mov_b32_e32 v34, v0
	v_mov_b32_e32 v35, v0
	v_mov_b32_e32 v40, v0
	v_mov_b32_e32 v41, v0
	v_mov_b32_e32 v42, v0
	v_mov_b32_e32 v43, v0
	v_mov_b32_e32 v48, v0
	v_mov_b32_e32 v49, v0
	v_mov_b32_e32 v50, v0
	v_mov_b32_e32 v51, v0
	v_mov_b32_e32 v56, v0
	v_mov_b32_e32 v57, v0
	v_mov_b32_e32 v58, v0
	v_mov_b32_e32 v59, v0
	v_mov_b32_e32 v4, v0
	v_mov_b32_e32 v5, v0
	v_mov_b32_e32 v6, v0
	v_mov_b32_e32 v7, v0
	v_mov_b32_e32 v12, v0
	v_mov_b32_e32 v13, v0
	v_mov_b32_e32 v14, v0
	v_mov_b32_e32 v15, v0
	v_mov_b32_e32 v20, v0
	v_mov_b32_e32 v21, v0
	v_mov_b32_e32 v22, v0
	v_mov_b32_e32 v23, v0
	v_mov_b32_e32 v28, v0
	v_mov_b32_e32 v29, v0
	v_mov_b32_e32 v30, v0
	v_mov_b32_e32 v31, v0
	v_mov_b32_e32 v36, v0
	v_mov_b32_e32 v37, v0
	v_mov_b32_e32 v38, v0
	v_mov_b32_e32 v39, v0
	v_mov_b32_e32 v44, v0
	v_mov_b32_e32 v45, v0
	v_mov_b32_e32 v46, v0
	v_mov_b32_e32 v47, v0
	v_mov_b32_e32 v52, v0
	v_mov_b32_e32 v53, v0
	v_mov_b32_e32 v54, v0
	v_mov_b32_e32 v55, v0
	v_mov_b32_e32 v60, v0
	v_mov_b32_e32 v61, v0
	v_mov_b32_e32 v62, v0
	v_mov_b32_e32 v63, v0
	v_mov_b32_e32 v64, v0
	v_mov_b32_e32 v65, v0
	v_mov_b32_e32 v66, v0
	v_mov_b32_e32 v67, v0
	v_mov_b32_e32 v72, v0
	v_mov_b32_e32 v73, v0
	v_mov_b32_e32 v74, v0
	v_mov_b32_e32 v75, v0
	v_mov_b32_e32 v80, v0
	v_mov_b32_e32 v81, v0
	v_mov_b32_e32 v82, v0
	v_mov_b32_e32 v83, v0
	v_mov_b32_e32 v88, v0
	v_mov_b32_e32 v89, v0
	v_mov_b32_e32 v90, v0
	v_mov_b32_e32 v91, v0
	v_mov_b32_e32 v96, v0
	v_mov_b32_e32 v97, v0
	v_mov_b32_e32 v98, v0
	v_mov_b32_e32 v99, v0
	v_mov_b32_e32 v104, v0
	v_mov_b32_e32 v105, v0
	v_mov_b32_e32 v106, v0
	v_mov_b32_e32 v107, v0
	v_mov_b32_e32 v112, v0
	v_mov_b32_e32 v113, v0
	v_mov_b32_e32 v114, v0
	v_mov_b32_e32 v115, v0
	v_mov_b32_e32 v120, v0
	v_mov_b32_e32 v121, v0
	v_mov_b32_e32 v122, v0
	v_mov_b32_e32 v123, v0
	v_mov_b32_e32 v68, v0
	v_mov_b32_e32 v69, v0
	v_mov_b32_e32 v70, v0
	v_mov_b32_e32 v71, v0
	v_mov_b32_e32 v76, v0
	v_mov_b32_e32 v77, v0
	v_mov_b32_e32 v78, v0
	v_mov_b32_e32 v79, v0
	v_mov_b32_e32 v84, v0
	v_mov_b32_e32 v85, v0
	v_mov_b32_e32 v86, v0
	v_mov_b32_e32 v87, v0
	v_mov_b32_e32 v92, v0
	v_mov_b32_e32 v93, v0
	v_mov_b32_e32 v94, v0
	v_mov_b32_e32 v95, v0
	v_mov_b32_e32 v100, v0
	v_mov_b32_e32 v101, v0
	v_mov_b32_e32 v102, v0
	v_mov_b32_e32 v103, v0
	v_mov_b32_e32 v108, v0
	v_mov_b32_e32 v109, v0
	v_mov_b32_e32 v110, v0
	v_mov_b32_e32 v111, v0
	v_mov_b32_e32 v116, v0
	v_mov_b32_e32 v117, v0
	v_mov_b32_e32 v118, v0
	v_mov_b32_e32 v119, v0
	v_mov_b32_e32 v124, v0
	v_mov_b32_e32 v125, v0
	v_mov_b32_e32 v126, v0
	v_mov_b32_e32 v127, v0
	v_readfirstlane_b32 s98, v197
	s_nop 3
	s_cmpk_gt_u32 s98, 0xff
	s_cbranch_scc0 .Lkp_1
	s_setprio 1
.Lkp_1:
.LBB0_1146:
	ds_read_b128 v[144:147], v153
	ds_read_b128 v[156:159], v153 offset:1024
	ds_read_b128 v[160:163], v153 offset:2048
	ds_read_b128 v[164:167], v153 offset:3072
	ds_read_b128 v[168:171], v154
	ds_read_b128 v[172:175], v154 offset:1024
	ds_read_b128 v[176:179], v154 offset:2048
	ds_read_b128 v[180:183], v154 offset:3072
	s_add_u32 s28, s26, 0xfffc0080
	s_addc_u32 s29, s27, -1
	s_cmp_eq_u32 s50, 12
	s_cselect_b32 s31, s3, s29
	s_cselect_b32 s30, s19, s28
	s_cselect_b32 s29, s17, s49
	s_cselect_b32 s28, s47, s48
	v_lshl_add_u64 v[218:219], s[26:27], 0, v[136:137]
	s_add_i32 m0, s25, 0xc000
	ds_read_b128 v[184:187], v155
	ds_read_b128 v[188:191], v155 offset:1024
	ds_read_b128 v[192:195], v155 offset:2048
	ds_read_b128 v[198:201], v155 offset:3072
	ds_read_b128 v[202:205], v155 offset:4096
	ds_read_b128 v[206:209], v155 offset:5120
	ds_read_b128 v[210:213], v155 offset:6144
	ds_read_b128 v[214:217], v155 offset:7168
	global_load_lds_dwordx4 v[218:219], off
	v_lshl_add_u64 v[218:219], s[26:27], 0, v[138:139]
	s_add_i32 m0, s25, 0xe000
	s_nop 0
	global_load_lds_dwordx4 v[218:219], off
	s_waitcnt vmcnt(8)
	s_waitcnt lgkmcnt(0)
	s_barrier
; #define PG8_STAGE(bufoff, gbase, voff) do { _Pragma("unroll") for (int _i = 0; _i < 2; ++_i) \
;         __builtin_amdgcn_global_load_lds((const unsigned*)((const char*)(gbase) + (voff)[_i]), (PG8_LAS unsigned*)(lds + (bufoff) + ldsw + _i * 8192), 16, 0, 0); } while (0)
; #define PG8_LDA(dst, b, h) do { _Pragma("unroll") for (int m = 0; m < 4; ++m) _Pragma("unroll") for (int k = 0; k < 2; ++k) dst[m][k] = *(const PG8_LAS bf16x8*)(lds + PG8_SA(b, h) + aoff + m * 2048 + k * 1024); } while (0)
; #define PG8_LDB(dst, b, h) do { _Pragma("unroll") for (int n = 0; n < 2; ++n) _Pragma("unroll") for (int k = 0; k < 2; ++k) dst[n][k] = *(const PG8_LAS bf16x8*)(lds + PG8_SB(b, h) + boff + n * 2048 + k * 1024); } while (0)
; #define PG8_MMA(ai, bj, At, Bt) do { __builtin_amdgcn_s_setprio(1); _Pragma("unroll") for (int m = 0; m < 4; ++m) _Pragma("unroll") for (int n = 0; n < 2; ++n) _Pragma("unroll") for (int k = 0; k < 2; ++k) \
;         acc[ai][bj][m][n] = __builtin_amdgcn_mfma_f32_16x16x32_bf16(Bt[n][k], At[m][k], acc[ai][bj][m][n], 0, 0, 0); __builtin_amdgcn_s_setprio(0); } while (0)
; #define PG8_WAIT_V(n) asm volatile("s_waitcnt vmcnt(" #n ")" ::: "memory")
; #define PG8_WAIT_L(n) asm volatile("s_waitcnt lgkmcnt(" #n ")" ::: "memory")
; #define PG8_BAR __builtin_amdgcn_s_barrier()
; #define PG8_SCHED __builtin_amdgcn_sched_barrier(0)
; template <class Epi, class Sched, bool ALIGN_EPI = false, bool SP2 = false>
; __device__ __forceinline__ void gemm_phase(PG8_LAS unsigned char* lds, const Gemm g, const Sched& S, const Epi& E) {
;     ...
;             PG8_LDB(B0, 0, 0); PG8_LDB(B1, 0, 1); PG8_SCHED; PG8_LDA(At, 0, 0); PG8_STAGE(PG8_SA(1, 1), a1 + hstep, voffA);
;             PG8_WAIT_V(8); PG8_WAIT_L(0); PG8_BAR; PG8_MMA(0, 0, At, B0); PG8_MMA(0, 1, At, B1); PG8_BAR; PG8_SCHED;
;             PG8_LDA(At, 0, 1); PG8_STAGE(PG8_SB(0, 0), b2, voffB); PG8_STAGE(PG8_SB(0, 1), b2 + hstep, voffB); PG8_STAGE(PG8_SA(0, 0), a2, voffA);
;             PG8_WAIT_V(8); PG8_WAIT_L(0); PG8_BAR; PG8_MMA(1, 0, At, B0); PG8_MMA(1, 1, At, B1); PG8_BAR; PG8_SCHED;
	s_waitcnt lgkmcnt(0)
	v_mfma_f32_16x16x32_bf16 v[124:127], v[144:147], v[184:187], v[124:127]
	v_mfma_f32_16x16x32_bf16 v[116:119], v[160:163], v[184:187], v[116:119]
	v_mfma_f32_16x16x32_bf16 v[108:111], v[144:147], v[192:195], v[108:111]
	v_mfma_f32_16x16x32_bf16 v[100:103], v[160:163], v[192:195], v[100:103]
	v_mfma_f32_16x16x32_bf16 v[92:95], v[144:147], v[202:205], v[92:95]
	v_mfma_f32_16x16x32_bf16 v[84:87], v[160:163], v[202:205], v[84:87]
	v_mfma_f32_16x16x32_bf16 v[76:79], v[144:147], v[210:213], v[76:79]
	v_mfma_f32_16x16x32_bf16 v[68:71], v[160:163], v[210:213], v[68:71]
	v_mfma_f32_16x16x32_bf16 v[124:127], v[156:159], v[188:191], v[124:127]
	v_mfma_f32_16x16x32_bf16 v[116:119], v[164:167], v[188:191], v[116:119]
	v_mfma_f32_16x16x32_bf16 v[108:111], v[156:159], v[198:201], v[108:111]
	v_mfma_f32_16x16x32_bf16 v[100:103], v[164:167], v[198:201], v[100:103]
	v_mfma_f32_16x16x32_bf16 v[92:95], v[156:159], v[206:209], v[92:95]
	v_mfma_f32_16x16x32_bf16 v[84:87], v[164:167], v[206:209], v[84:87]
	v_mfma_f32_16x16x32_bf16 v[76:79], v[156:159], v[214:217], v[76:79]
	v_mfma_f32_16x16x32_bf16 v[68:71], v[164:167], v[214:217], v[68:71]
	v_mfma_f32_16x16x32_bf16 v[120:123], v[168:171], v[184:187], v[120:123]
	v_mfma_f32_16x16x32_bf16 v[112:115], v[176:179], v[184:187], v[112:115]
	v_mfma_f32_16x16x32_bf16 v[104:107], v[168:171], v[192:195], v[104:107]
	v_mfma_f32_16x16x32_bf16 v[96:99], v[176:179], v[192:195], v[96:99]
	v_mfma_f32_16x16x32_bf16 v[88:91], v[168:171], v[202:205], v[88:91]
	v_mfma_f32_16x16x32_bf16 v[80:83], v[176:179], v[202:205], v[80:83]
	v_mfma_f32_16x16x32_bf16 v[72:75], v[168:171], v[210:213], v[72:75]
	v_mfma_f32_16x16x32_bf16 v[64:67], v[176:179], v[210:213], v[64:67]
	v_mfma_f32_16x16x32_bf16 v[120:123], v[172:175], v[188:191], v[120:123]
	v_mfma_f32_16x16x32_bf16 v[112:115], v[180:183], v[188:191], v[112:115]
	v_mfma_f32_16x16x32_bf16 v[104:107], v[172:175], v[198:201], v[104:107]
	v_mfma_f32_16x16x32_bf16 v[96:99], v[180:183], v[198:201], v[96:99]
	v_mfma_f32_16x16x32_bf16 v[88:91], v[172:175], v[206:209], v[88:91]
	v_mfma_f32_16x16x32_bf16 v[80:83], v[180:183], v[206:209], v[80:83]
	v_mfma_f32_16x16x32_bf16 v[72:75], v[172:175], v[214:217], v[72:75]
	v_mfma_f32_16x16x32_bf16 v[64:67], v[180:183], v[214:217], v[64:67]
	s_barrier
	s_add_i32 s51, s44, s33
	v_lshl_add_u64 v[218:219], s[28:29], 0, v[130:131]
	s_mov_b32 m0, s51
	ds_read_b128 v[184:187], v155 offset:16384
	ds_read_b128 v[188:191], v155 offset:17408
	ds_read_b128 v[192:195], v155 offset:18432
	ds_read_b128 v[198:201], v155 offset:19456
	ds_read_b128 v[202:205], v155 offset:20480
	ds_read_b128 v[206:209], v155 offset:21504
	ds_read_b128 v[210:213], v155 offset:22528
	ds_read_b128 v[214:217], v155 offset:23552
	global_load_lds_dwordx4 v[218:219], off
	s_add_i32 m0, s51, 0x2000
	s_add_u32 s52, s28, 0x40000
	v_lshl_add_u64 v[220:221], s[28:29], 0, v[134:135]
	s_addc_u32 s53, s29, 0
	s_add_i32 s51, s45, s33
	global_load_lds_dwordx4 v[220:221], off
	v_lshl_add_u64 v[222:223], s[52:53], 0, v[130:131]
	s_mov_b32 m0, s51
	v_lshl_add_u64 v[224:225], s[30:31], 0, v[132:133]
	global_load_lds_dwordx4 v[222:223], off
	v_lshl_add_u64 v[222:223], s[52:53], 0, v[134:135]
	s_add_i32 m0, s51, 0x2000
	s_nop 0
	global_load_lds_dwordx4 v[222:223], off
	v_lshl_add_u64 v[222:223], s[30:31], 0, v[128:129]
	s_mov_b32 m0, s25
	s_nop 0
	global_load_lds_dwordx4 v[222:223], off
	s_mov_b32 m0, s34
	s_nop 0
	global_load_lds_dwordx4 v[224:225], off
	s_waitcnt vmcnt(8)
	s_waitcnt lgkmcnt(0)
	s_barrier
	s_waitcnt lgkmcnt(0)
	v_mfma_f32_16x16x32_bf16 v[60:63], v[144:147], v[184:187], v[60:63]
	v_mfma_f32_16x16x32_bf16 v[52:55], v[160:163], v[184:187], v[52:55]
	v_mfma_f32_16x16x32_bf16 v[44:47], v[144:147], v[192:195], v[44:47]
	v_mfma_f32_16x16x32_bf16 v[36:39], v[160:163], v[192:195], v[36:39]
	v_mfma_f32_16x16x32_bf16 v[28:31], v[144:147], v[202:205], v[28:31]
	v_mfma_f32_16x16x32_bf16 v[20:23], v[160:163], v[202:205], v[20:23]
	v_mfma_f32_16x16x32_bf16 v[12:15], v[144:147], v[210:213], v[12:15]
	v_mfma_f32_16x16x32_bf16 v[4:7], v[160:163], v[210:213], v[4:7]
	v_mfma_f32_16x16x32_bf16 v[60:63], v[156:159], v[188:191], v[60:63]
	v_mfma_f32_16x16x32_bf16 v[52:55], v[164:167], v[188:191], v[52:55]
	v_mfma_f32_16x16x32_bf16 v[44:47], v[156:159], v[198:201], v[44:47]
	v_mfma_f32_16x16x32_bf16 v[36:39], v[164:167], v[198:201], v[36:39]
	v_mfma_f32_16x16x32_bf16 v[28:31], v[156:159], v[206:209], v[28:31]
	v_mfma_f32_16x16x32_bf16 v[20:23], v[164:167], v[206:209], v[20:23]
	v_mfma_f32_16x16x32_bf16 v[12:15], v[156:159], v[214:217], v[12:15]
	v_mfma_f32_16x16x32_bf16 v[4:7], v[164:167], v[214:217], v[4:7]
	v_mfma_f32_16x16x32_bf16 v[56:59], v[168:171], v[184:187], v[56:59]
	v_mfma_f32_16x16x32_bf16 v[48:51], v[176:179], v[184:187], v[48:51]
	v_mfma_f32_16x16x32_bf16 v[40:43], v[168:171], v[192:195], v[40:43]
	v_mfma_f32_16x16x32_bf16 v[32:35], v[176:179], v[192:195], v[32:35]
	v_mfma_f32_16x16x32_bf16 v[24:27], v[168:171], v[202:205], v[24:27]
	v_mfma_f32_16x16x32_bf16 v[16:19], v[176:179], v[202:205], v[16:19]
	v_mfma_f32_16x16x32_bf16 v[8:11], v[168:171], v[210:213], v[8:11]
	v_mfma_f32_16x16x32_bf16 v[0:3], v[176:179], v[210:213], v[0:3]
	v_mfma_f32_16x16x32_bf16 v[56:59], v[172:175], v[188:191], v[56:59]
	v_mfma_f32_16x16x32_bf16 v[48:51], v[180:183], v[188:191], v[48:51]
	v_mfma_f32_16x16x32_bf16 v[40:43], v[172:175], v[198:201], v[40:43]
	v_mfma_f32_16x16x32_bf16 v[32:35], v[180:183], v[198:201], v[32:35]
	v_mfma_f32_16x16x32_bf16 v[24:27], v[172:175], v[206:209], v[24:27]
	v_mfma_f32_16x16x32_bf16 v[16:19], v[180:183], v[206:209], v[16:19]
	v_mfma_f32_16x16x32_bf16 v[8:11], v[172:175], v[214:217], v[8:11]
	v_mfma_f32_16x16x32_bf16 v[0:3], v[180:183], v[214:217], v[0:3]
	s_barrier
; #define PG8_STAGE(bufoff, gbase, voff) do { _Pragma("unroll") for (int _i = 0; _i < 2; ++_i) \
;         __builtin_amdgcn_global_load_lds((const unsigned*)((const char*)(gbase) + (voff)[_i]), (PG8_LAS unsigned*)(lds + (bufoff) + ldsw + _i * 8192), 16, 0, 0); } while (0)
; #define PG8_LDA(dst, b, h) do { _Pragma("unroll") for (int m = 0; m < 4; ++m) _Pragma("unroll") for (int k = 0; k < 2; ++k) dst[m][k] = *(const PG8_LAS bf16x8*)(lds + PG8_SA(b, h) + aoff + m * 2048 + k * 1024); } while (0)
; #define PG8_LDB(dst, b, h) do { _Pragma("unroll") for (int n = 0; n < 2; ++n) _Pragma("unroll") for (int k = 0; k < 2; ++k) dst[n][k] = *(const PG8_LAS bf16x8*)(lds + PG8_SB(b, h) + boff + n * 2048 + k * 1024); } while (0)
; #define PG8_MMA(ai, bj, At, Bt) do { __builtin_amdgcn_s_setprio(1); _Pragma("unroll") for (int m = 0; m < 4; ++m) _Pragma("unroll") for (int n = 0; n < 2; ++n) _Pragma("unroll") for (int k = 0; k < 2; ++k) \
;         acc[ai][bj][m][n] = __builtin_amdgcn_mfma_f32_16x16x32_bf16(Bt[n][k], At[m][k], acc[ai][bj][m][n], 0, 0, 0); __builtin_amdgcn_s_setprio(0); } while (0)
; #define PG8_WAIT_V(n) asm volatile("s_waitcnt vmcnt(" #n ")" ::: "memory")
; #define PG8_WAIT_L(n) asm volatile("s_waitcnt lgkmcnt(" #n ")" ::: "memory")
; #define PG8_BAR __builtin_amdgcn_s_barrier()
; #define PG8_SCHED __builtin_amdgcn_sched_barrier(0)
; template <class Epi, class Sched, bool ALIGN_EPI = false, bool SP2 = false>
; __device__ __forceinline__ void gemm_phase(PG8_LAS unsigned char* lds, const Gemm g, const Sched& S, const Epi& E) {
;     ...
;             PG8_LDB(B0, 1, 0); PG8_LDB(B1, 1, 1); PG8_SCHED; PG8_LDA(At, 1, 0); PG8_STAGE(PG8_SA(0, 1), a2 + hstep, voffA);
;             PG8_WAIT_V(8); PG8_WAIT_L(0); PG8_BAR; PG8_MMA(0, 0, At, B0); PG8_MMA(0, 1, At, B1); PG8_BAR; PG8_SCHED;
	s_add_i32 s51, 0, 0x18000
	v_add_u32_e32 v148, s51, v151
	s_add_i32 s52, 0, 0x1c000
	ds_read_b128 v[144:147], v148
	ds_read_b128 v[156:159], v148 offset:1024
	ds_read_b128 v[160:163], v148 offset:2048
	ds_read_b128 v[164:167], v148 offset:3072
	v_add_u32_e32 v148, s52, v151
	ds_read_b128 v[168:171], v148
	ds_read_b128 v[172:175], v148 offset:1024
	ds_read_b128 v[176:179], v148 offset:2048
	ds_read_b128 v[180:183], v148 offset:3072
	s_add_u32 s30, s30, 0x40000
	s_addc_u32 s31, s31, 0
	s_mov_b32 m0, s35
	v_lshl_add_u64 v[226:227], s[30:31], 0, v[128:129]
	ds_read_b128 v[184:187], v155 offset:32768
	ds_read_b128 v[188:191], v155 offset:33792
	ds_read_b128 v[192:195], v155 offset:34816
	ds_read_b128 v[198:201], v155 offset:35840
	ds_read_b128 v[202:205], v155 offset:36864
	ds_read_b128 v[206:209], v155 offset:37888
	ds_read_b128 v[210:213], v155 offset:38912
	ds_read_b128 v[214:217], v155 offset:39936
	global_load_lds_dwordx4 v[226:227], off
	v_lshl_add_u64 v[226:227], s[30:31], 0, v[132:133]
	s_mov_b32 m0, s36
	s_nop 0
	global_load_lds_dwordx4 v[226:227], off
	s_waitcnt vmcnt(8)
	s_waitcnt lgkmcnt(0)
	s_barrier
	s_waitcnt lgkmcnt(0)
	v_mfma_f32_16x16x32_bf16 v[124:127], v[144:147], v[184:187], v[124:127]
	v_mfma_f32_16x16x32_bf16 v[116:119], v[160:163], v[184:187], v[116:119]
	v_mfma_f32_16x16x32_bf16 v[108:111], v[144:147], v[192:195], v[108:111]
	v_mfma_f32_16x16x32_bf16 v[100:103], v[160:163], v[192:195], v[100:103]
	v_mfma_f32_16x16x32_bf16 v[92:95], v[144:147], v[202:205], v[92:95]
	v_mfma_f32_16x16x32_bf16 v[84:87], v[160:163], v[202:205], v[84:87]
	v_mfma_f32_16x16x32_bf16 v[76:79], v[144:147], v[210:213], v[76:79]
	v_mfma_f32_16x16x32_bf16 v[68:71], v[160:163], v[210:213], v[68:71]
	v_mfma_f32_16x16x32_bf16 v[124:127], v[156:159], v[188:191], v[124:127]
	v_mfma_f32_16x16x32_bf16 v[116:119], v[164:167], v[188:191], v[116:119]
	v_mfma_f32_16x16x32_bf16 v[108:111], v[156:159], v[198:201], v[108:111]
	v_mfma_f32_16x16x32_bf16 v[100:103], v[164:167], v[198:201], v[100:103]
	v_mfma_f32_16x16x32_bf16 v[92:95], v[156:159], v[206:209], v[92:95]
	v_mfma_f32_16x16x32_bf16 v[84:87], v[164:167], v[206:209], v[84:87]
	v_mfma_f32_16x16x32_bf16 v[76:79], v[156:159], v[214:217], v[76:79]
	v_mfma_f32_16x16x32_bf16 v[68:71], v[164:167], v[214:217], v[68:71]
	v_mfma_f32_16x16x32_bf16 v[120:123], v[168:171], v[184:187], v[120:123]
	v_mfma_f32_16x16x32_bf16 v[112:115], v[176:179], v[184:187], v[112:115]
	v_mfma_f32_16x16x32_bf16 v[104:107], v[168:171], v[192:195], v[104:107]
	v_mfma_f32_16x16x32_bf16 v[96:99], v[176:179], v[192:195], v[96:99]
	v_mfma_f32_16x16x32_bf16 v[88:91], v[168:171], v[202:205], v[88:91]
	v_mfma_f32_16x16x32_bf16 v[80:83], v[176:179], v[202:205], v[80:83]
	v_mfma_f32_16x16x32_bf16 v[72:75], v[168:171], v[210:213], v[72:75]
	v_mfma_f32_16x16x32_bf16 v[64:67], v[176:179], v[210:213], v[64:67]
	v_mfma_f32_16x16x32_bf16 v[120:123], v[172:175], v[188:191], v[120:123]
	v_mfma_f32_16x16x32_bf16 v[112:115], v[180:183], v[188:191], v[112:115]
	v_mfma_f32_16x16x32_bf16 v[104:107], v[172:175], v[198:201], v[104:107]
	v_mfma_f32_16x16x32_bf16 v[96:99], v[180:183], v[198:201], v[96:99]
	v_mfma_f32_16x16x32_bf16 v[88:91], v[172:175], v[206:209], v[88:91]
	v_mfma_f32_16x16x32_bf16 v[80:83], v[180:183], v[206:209], v[80:83]
	v_mfma_f32_16x16x32_bf16 v[72:75], v[172:175], v[214:217], v[72:75]
	v_mfma_f32_16x16x32_bf16 v[64:67], v[180:183], v[214:217], v[64:67]
	s_barrier
; #define PG8_STAGE(bufoff, gbase, voff) do { _Pragma("unroll") for (int _i = 0; _i < 2; ++_i) \
;         __builtin_amdgcn_global_load_lds((const unsigned*)((const char*)(gbase) + (voff)[_i]), (PG8_LAS unsigned*)(lds + (bufoff) + ldsw + _i * 8192), 16, 0, 0); } while (0)
; #define PG8_LDA(dst, b, h) do { _Pragma("unroll") for (int m = 0; m < 4; ++m) _Pragma("unroll") for (int k = 0; k < 2; ++k) dst[m][k] = *(const PG8_LAS bf16x8*)(lds + PG8_SA(b, h) + aoff + m * 2048 + k * 1024); } while (0)
; #define PG8_MMA(ai, bj, At, Bt) do { __builtin_amdgcn_s_setprio(1); _Pragma("unroll") for (int m = 0; m < 4; ++m) _Pragma("unroll") for (int n = 0; n < 2; ++n) _Pragma("unroll") for (int k = 0; k < 2; ++k) \
;         acc[ai][bj][m][n] = __builtin_amdgcn_mfma_f32_16x16x32_bf16(Bt[n][k], At[m][k], acc[ai][bj][m][n], 0, 0, 0); __builtin_amdgcn_s_setprio(0); } while (0)
; #define PG8_WAIT_V(n) asm volatile("s_waitcnt vmcnt(" #n ")" ::: "memory")
; #define PG8_WAIT_L(n) asm volatile("s_waitcnt lgkmcnt(" #n ")" ::: "memory")
; #define PG8_BAR __builtin_amdgcn_s_barrier()
; #define PG8_SCHED __builtin_amdgcn_sched_barrier(0)
; template <class Epi, class Sched, bool ALIGN_EPI = false, bool SP2 = false>
; __device__ __forceinline__ void gemm_phase(PG8_LAS unsigned char* lds, const Gemm g, const Sched& S, const Epi& E) {
;     ...
;             PG8_LDA(At, 1, 1); PG8_STAGE(PG8_SB(1, 0), b3, voffB); PG8_STAGE(PG8_SB(1, 1), b3 + hstep, voffB); PG8_STAGE(PG8_SA(1, 0), a3, voffA);
;             PG8_WAIT_V(8); PG8_WAIT_L(0); PG8_BAR; PG8_MMA(1, 0, At, B0); PG8_MMA(1, 1, At, B1); PG8_BAR; PG8_SCHED;
	s_add_i32 s30, s51, s33
	v_lshl_add_u64 v[218:219], v[218:219], 0, s[12:13]
	s_mov_b32 m0, s30
	ds_read_b128 v[184:187], v155 offset:49152
	ds_read_b128 v[188:191], v155 offset:50176
	ds_read_b128 v[192:195], v155 offset:51200
	ds_read_b128 v[198:201], v155 offset:52224
	ds_read_b128 v[202:205], v155 offset:53248
	ds_read_b128 v[206:209], v155 offset:54272
	ds_read_b128 v[210:213], v155 offset:55296
	ds_read_b128 v[214:217], v155 offset:56320
	global_load_lds_dwordx4 v[218:219], off
	s_add_i32 m0, s30, 0x2000
	s_add_u32 s28, s28, 0x40080
	v_lshl_add_u64 v[218:219], v[220:221], 0, s[12:13]
	s_addc_u32 s29, s29, 0
	s_add_i32 s30, s52, s33
	global_load_lds_dwordx4 v[218:219], off
	v_lshl_add_u64 v[218:219], s[28:29], 0, v[130:131]
	s_mov_b32 m0, s30
	s_nop 0
	global_load_lds_dwordx4 v[218:219], off
	v_lshl_add_u64 v[218:219], s[28:29], 0, v[134:135]
	s_add_i32 m0, s30, 0x2000
	s_nop 0
	global_load_lds_dwordx4 v[218:219], off
	v_lshl_add_u64 v[218:219], v[222:223], 0, s[12:13]
	s_mov_b32 m0, s40
	s_nop 0
	global_load_lds_dwordx4 v[218:219], off
	v_lshl_add_u64 v[218:219], v[224:225], 0, s[12:13]
	s_mov_b32 m0, s41
	s_nop 0
	global_load_lds_dwordx4 v[218:219], off
	s_waitcnt vmcnt(8)
	s_waitcnt lgkmcnt(0)
	s_barrier
	s_waitcnt lgkmcnt(0)
	v_mfma_f32_16x16x32_bf16 v[60:63], v[144:147], v[184:187], v[60:63]
	v_mfma_f32_16x16x32_bf16 v[52:55], v[160:163], v[184:187], v[52:55]
	v_mfma_f32_16x16x32_bf16 v[44:47], v[144:147], v[192:195], v[44:47]
	v_mfma_f32_16x16x32_bf16 v[36:39], v[160:163], v[192:195], v[36:39]
	v_mfma_f32_16x16x32_bf16 v[28:31], v[144:147], v[202:205], v[28:31]
	v_mfma_f32_16x16x32_bf16 v[20:23], v[160:163], v[202:205], v[20:23]
	v_mfma_f32_16x16x32_bf16 v[12:15], v[144:147], v[210:213], v[12:15]
	v_mfma_f32_16x16x32_bf16 v[4:7], v[160:163], v[210:213], v[4:7]
	v_mfma_f32_16x16x32_bf16 v[60:63], v[156:159], v[188:191], v[60:63]
	v_mfma_f32_16x16x32_bf16 v[52:55], v[164:167], v[188:191], v[52:55]
	v_mfma_f32_16x16x32_bf16 v[44:47], v[156:159], v[198:201], v[44:47]
	v_mfma_f32_16x16x32_bf16 v[36:39], v[164:167], v[198:201], v[36:39]
	v_mfma_f32_16x16x32_bf16 v[28:31], v[156:159], v[206:209], v[28:31]
	v_mfma_f32_16x16x32_bf16 v[20:23], v[164:167], v[206:209], v[20:23]
	v_mfma_f32_16x16x32_bf16 v[12:15], v[156:159], v[214:217], v[12:15]
	v_mfma_f32_16x16x32_bf16 v[4:7], v[164:167], v[214:217], v[4:7]
	v_mfma_f32_16x16x32_bf16 v[56:59], v[168:171], v[184:187], v[56:59]
	v_mfma_f32_16x16x32_bf16 v[48:51], v[176:179], v[184:187], v[48:51]
	v_mfma_f32_16x16x32_bf16 v[40:43], v[168:171], v[192:195], v[40:43]
	v_mfma_f32_16x16x32_bf16 v[32:35], v[176:179], v[192:195], v[32:35]
	v_mfma_f32_16x16x32_bf16 v[24:27], v[168:171], v[202:205], v[24:27]
	v_mfma_f32_16x16x32_bf16 v[16:19], v[176:179], v[202:205], v[16:19]
	v_mfma_f32_16x16x32_bf16 v[8:11], v[168:171], v[210:213], v[8:11]
	v_mfma_f32_16x16x32_bf16 v[0:3], v[176:179], v[210:213], v[0:3]
	v_mfma_f32_16x16x32_bf16 v[56:59], v[172:175], v[188:191], v[56:59]
	v_mfma_f32_16x16x32_bf16 v[48:51], v[180:183], v[188:191], v[48:51]
	v_mfma_f32_16x16x32_bf16 v[40:43], v[172:175], v[198:201], v[40:43]
	v_mfma_f32_16x16x32_bf16 v[32:35], v[180:183], v[198:201], v[32:35]
	v_mfma_f32_16x16x32_bf16 v[24:27], v[172:175], v[206:209], v[24:27]
	v_mfma_f32_16x16x32_bf16 v[16:19], v[180:183], v[206:209], v[16:19]
	v_mfma_f32_16x16x32_bf16 v[8:11], v[172:175], v[214:217], v[8:11]
	v_mfma_f32_16x16x32_bf16 v[0:3], v[180:183], v[214:217], v[0:3]
	s_barrier
	s_add_i32 s50, s50, 2
	s_add_u32 s26, s26, 0x100
	s_addc_u32 s27, s27, 0
	s_add_u32 s48, s48, 0x100
	s_addc_u32 s49, s49, 0
	s_cmp_gt_u32 s50, 13
	s_cbranch_scc0 .LBB0_1146
	s_setprio 0
	s_and_b64 vcc, exec, s[14:15]
	s_cbranch_vccz .LBB0_1149
	s_barrier

; #define PG8_STAGE(bufoff, gbase, voff) do { _Pragma("unroll") for (int _i = 0; _i < 2; ++_i) \
;         __builtin_amdgcn_global_load_lds((const unsigned*)((const char*)(gbase) + (voff)[_i]), (PG8_LAS unsigned*)(lds + (bufoff) + ldsw + _i * 8192), 16, 0, 0); } while (0)
; #define PG8_LDA(dst, b, h) do { _Pragma("unroll") for (int m = 0; m < 4; ++m) _Pragma("unroll") for (int k = 0; k < 2; ++k) dst[m][k] = *(const PG8_LAS bf16x8*)(lds + PG8_SA(b, h) + aoff + m * 2048 + k * 1024); } while (0)
; #define PG8_LDB(dst, b, h) do { _Pragma("unroll") for (int n = 0; n < 2; ++n) _Pragma("unroll") for (int k = 0; k < 2; ++k) dst[n][k] = *(const PG8_LAS bf16x8*)(lds + PG8_SB(b, h) + boff + n * 2048 + k * 1024); } while (0)
; #define PG8_MMA(ai, bj, At, Bt) do { __builtin_amdgcn_s_setprio(1); _Pragma("unroll") for (int m = 0; m < 4; ++m) _Pragma("unroll") for (int n = 0; n < 2; ++n) _Pragma("unroll") for (int k = 0; k < 2; ++k) \
;         acc[ai][bj][m][n] = __builtin_amdgcn_mfma_f32_16x16x32_bf16(Bt[n][k], At[m][k], acc[ai][bj][m][n], 0, 0, 0); __builtin_amdgcn_s_setprio(0); } while (0)
; #define PG8_WAIT_V(n) asm volatile("s_waitcnt vmcnt(" #n ")" ::: "memory")
; #define PG8_WAIT_L(n) asm volatile("s_waitcnt lgkmcnt(" #n ")" ::: "memory")
; #define PG8_BAR __builtin_amdgcn_s_barrier()
; #define PG8_SCHED __builtin_amdgcn_sched_barrier(0)
; template <class Epi, class Sched, bool ALIGN_EPI = false, bool SP2 = false>
; __device__ __forceinline__ void gemm_phase(PG8_LAS unsigned char* lds, const Gemm g, const Sched& S, const Epi& E) {
;     ...
;             PG8_LDB(B0, 0, 0); PG8_LDB(B1, 0, 1); PG8_SCHED; PG8_LDA(At, 0, 0); PG8_STAGE(PG8_SA(1, 1), a1 + hstep, voffA);
;             PG8_WAIT_V(8); PG8_WAIT_L(0); PG8_BAR; PG8_MMA(0, 0, At, B0); PG8_MMA(0, 1, At, B1); PG8_BAR; PG8_SCHED;
;     ...
; #pragma unroll
;         for (int a = 0; a < 2; ++a)
; #pragma unroll
;             for (int b = 0; b < 2; ++b)
; #pragma unroll
;                 for (int m = 0; m < 4; ++m)
; #pragma unroll
;                     for (int n = 0; n < 2; ++n) acc[a][b][m][n] = (f32x4){0.f, 0.f, 0.f, 0.f};
;         cur = nxt; cA = nA; cB = nB; ++ui;
.LBB0_1238:
	s_add_u32 s18, s18, 0xb0080
	s_addc_u32 s19, s19, 0
	s_add_u32 s42, s20, 0x100
	v_mov_b32_e32 v0, 0
	s_addc_u32 s43, s21, 0
	s_mov_b32 s44, -2
	v_mov_b32_e32 v1, v0
	v_mov_b32_e32 v2, v0
	v_mov_b32_e32 v3, v0
	v_mov_b32_e32 v4, v0
	s_waitcnt lgkmcnt(0)
	v_mov_b32_e32 v5, v0
	v_mov_b32_e32 v6, v0
	v_mov_b32_e32 v7, v0
	v_mov_b32_e32 v16, v0
	v_mov_b32_e32 v17, v0
	v_mov_b32_e32 v18, v0
	v_mov_b32_e32 v19, v0
	v_mov_b32_e32 v20, v0
	v_mov_b32_e32 v21, v0
	v_mov_b32_e32 v22, v0
	v_mov_b32_e32 v23, v0
	v_mov_b32_e32 v32, v0
	v_mov_b32_e32 v33, v0
	v_mov_b32_e32 v34, v0
	v_mov_b32_e32 v35, v0
	v_mov_b32_e32 v36, v0
	v_mov_b32_e32 v37, v0
	v_mov_b32_e32 v38, v0
	v_mov_b32_e32 v39, v0
	v_mov_b32_e32 v48, v0
	v_mov_b32_e32 v49, v0
	v_mov_b32_e32 v50, v0
	v_mov_b32_e32 v51, v0
	v_mov_b32_e32 v52, v0
	v_mov_b32_e32 v53, v0
	v_mov_b32_e32 v54, v0
	v_mov_b32_e32 v55, v0
	v_mov_b32_e32 v8, v0
	v_mov_b32_e32 v9, v0
	v_mov_b32_e32 v10, v0
	v_mov_b32_e32 v11, v0
	v_mov_b32_e32 v12, v0
	v_mov_b32_e32 v13, v0
	v_mov_b32_e32 v14, v0
	v_mov_b32_e32 v15, v0
	v_mov_b32_e32 v24, v0
	v_mov_b32_e32 v25, v0
	v_mov_b32_e32 v26, v0
	v_mov_b32_e32 v27, v0
	v_mov_b32_e32 v28, v0
	v_mov_b32_e32 v29, v0
	v_mov_b32_e32 v30, v0
	v_mov_b32_e32 v31, v0
	v_mov_b32_e32 v40, v0
	v_mov_b32_e32 v41, v0
	v_mov_b32_e32 v42, v0
	v_mov_b32_e32 v43, v0
	v_mov_b32_e32 v44, v0
	v_mov_b32_e32 v45, v0
	v_mov_b32_e32 v46, v0
	v_mov_b32_e32 v47, v0
	v_mov_b32_e32 v56, v0
	v_mov_b32_e32 v57, v0
	v_mov_b32_e32 v58, v0
	v_mov_b32_e32 v59, v0
	v_mov_b32_e32 v60, v0
	v_mov_b32_e32 v61, v0
	v_mov_b32_e32 v62, v0
	v_mov_b32_e32 v63, v0
	v_mov_b32_e32 v64, v0
	v_mov_b32_e32 v65, v0
	v_mov_b32_e32 v66, v0
	v_mov_b32_e32 v67, v0
	v_mov_b32_e32 v68, v0
	v_mov_b32_e32 v69, v0
	v_mov_b32_e32 v70, v0
	v_mov_b32_e32 v71, v0
	v_mov_b32_e32 v80, v0
	v_mov_b32_e32 v81, v0
	v_mov_b32_e32 v82, v0
	v_mov_b32_e32 v83, v0
	v_mov_b32_e32 v84, v0
	v_mov_b32_e32 v85, v0
	v_mov_b32_e32 v86, v0
	v_mov_b32_e32 v87, v0
	v_mov_b32_e32 v96, v0
	v_mov_b32_e32 v97, v0
	v_mov_b32_e32 v98, v0
	v_mov_b32_e32 v99, v0
	v_mov_b32_e32 v100, v0
	v_mov_b32_e32 v101, v0
	v_mov_b32_e32 v102, v0
	v_mov_b32_e32 v103, v0
	v_mov_b32_e32 v112, v0
	v_mov_b32_e32 v113, v0
	v_mov_b32_e32 v114, v0
	v_mov_b32_e32 v115, v0
	v_mov_b32_e32 v116, v0
	v_mov_b32_e32 v117, v0
	v_mov_b32_e32 v118, v0
	v_mov_b32_e32 v119, v0
	v_mov_b32_e32 v72, v0
	v_mov_b32_e32 v73, v0
	v_mov_b32_e32 v74, v0
	v_mov_b32_e32 v75, v0
	v_mov_b32_e32 v76, v0
	v_mov_b32_e32 v77, v0
	v_mov_b32_e32 v78, v0
	v_mov_b32_e32 v79, v0
	v_mov_b32_e32 v88, v0
	v_mov_b32_e32 v89, v0
	v_mov_b32_e32 v90, v0
	v_mov_b32_e32 v91, v0
	v_mov_b32_e32 v92, v0
	v_mov_b32_e32 v93, v0
	v_mov_b32_e32 v94, v0
	v_mov_b32_e32 v95, v0
	v_mov_b32_e32 v104, v0
	v_mov_b32_e32 v105, v0
	v_mov_b32_e32 v106, v0
	v_mov_b32_e32 v107, v0
	v_mov_b32_e32 v108, v0
	v_mov_b32_e32 v109, v0
	v_mov_b32_e32 v110, v0
	v_mov_b32_e32 v111, v0
	v_mov_b32_e32 v120, v0
	v_mov_b32_e32 v121, v0
	v_mov_b32_e32 v122, v0
	v_mov_b32_e32 v123, v0
	v_mov_b32_e32 v124, v0
	v_mov_b32_e32 v125, v0
	v_mov_b32_e32 v126, v0
	v_mov_b32_e32 v127, v0
	v_readfirstlane_b32 s98, v197
	s_nop 3
	s_cmpk_gt_u32 s98, 0xff
	s_cbranch_scc0 .Lkp_0
	s_setprio 1
.Lkp_0:
.LBB0_1239:
	ds_read_b128 v[144:147], v151
	ds_read_b128 v[156:159], v151 offset:1024
	ds_read_b128 v[160:163], v151 offset:2048
	ds_read_b128 v[164:167], v151 offset:3072
	ds_read_b128 v[168:171], v152
	ds_read_b128 v[172:175], v152 offset:1024
	ds_read_b128 v[176:179], v152 offset:2048
	ds_read_b128 v[180:183], v152 offset:3072
	s_add_u32 s20, s18, 0xfff50080
	s_addc_u32 s21, s19, -1
	s_cmp_eq_u32 s44, 40
	s_cselect_b32 s23, s5, s21
	s_cselect_b32 s22, s4, s20
	s_cselect_b32 s21, s17, s43
	s_cselect_b32 s20, s16, s42
	v_lshl_add_u64 v[218:219], s[18:19], 0, v[136:137]
	s_add_i32 m0, s25, 0xc000
	ds_read_b128 v[184:187], v153
	ds_read_b128 v[188:191], v153 offset:1024
	ds_read_b128 v[192:195], v153 offset:2048
	ds_read_b128 v[198:201], v153 offset:3072
	ds_read_b128 v[202:205], v153 offset:4096
	ds_read_b128 v[206:209], v153 offset:5120
	ds_read_b128 v[210:213], v153 offset:6144
	ds_read_b128 v[214:217], v153 offset:7168
	global_load_lds_dwordx4 v[218:219], off
	v_lshl_add_u64 v[218:219], s[18:19], 0, v[138:139]
	s_add_i32 m0, s25, 0xe000
	s_nop 0
	global_load_lds_dwordx4 v[218:219], off
	s_waitcnt vmcnt(8)
	s_waitcnt lgkmcnt(0)
	s_barrier
	s_waitcnt lgkmcnt(0)
	v_mfma_f32_16x16x32_bf16 v[124:127], v[144:147], v[184:187], v[124:127]
	v_mfma_f32_16x16x32_bf16 v[120:123], v[160:163], v[184:187], v[120:123]
	v_mfma_f32_16x16x32_bf16 v[108:111], v[144:147], v[192:195], v[108:111]
	v_mfma_f32_16x16x32_bf16 v[104:107], v[160:163], v[192:195], v[104:107]
	v_mfma_f32_16x16x32_bf16 v[92:95], v[144:147], v[202:205], v[92:95]
	v_mfma_f32_16x16x32_bf16 v[88:91], v[160:163], v[202:205], v[88:91]
	v_mfma_f32_16x16x32_bf16 v[76:79], v[144:147], v[210:213], v[76:79]
	v_mfma_f32_16x16x32_bf16 v[72:75], v[160:163], v[210:213], v[72:75]
	v_mfma_f32_16x16x32_bf16 v[124:127], v[156:159], v[188:191], v[124:127]
	v_mfma_f32_16x16x32_bf16 v[120:123], v[164:167], v[188:191], v[120:123]
	v_mfma_f32_16x16x32_bf16 v[108:111], v[156:159], v[198:201], v[108:111]
	v_mfma_f32_16x16x32_bf16 v[104:107], v[164:167], v[198:201], v[104:107]
	v_mfma_f32_16x16x32_bf16 v[92:95], v[156:159], v[206:209], v[92:95]
	v_mfma_f32_16x16x32_bf16 v[88:91], v[164:167], v[206:209], v[88:91]
	v_mfma_f32_16x16x32_bf16 v[76:79], v[156:159], v[214:217], v[76:79]
	v_mfma_f32_16x16x32_bf16 v[72:75], v[164:167], v[214:217], v[72:75]
	v_mfma_f32_16x16x32_bf16 v[116:119], v[168:171], v[184:187], v[116:119]
	v_mfma_f32_16x16x32_bf16 v[112:115], v[176:179], v[184:187], v[112:115]
	v_mfma_f32_16x16x32_bf16 v[100:103], v[168:171], v[192:195], v[100:103]
	v_mfma_f32_16x16x32_bf16 v[96:99], v[176:179], v[192:195], v[96:99]
	v_mfma_f32_16x16x32_bf16 v[84:87], v[168:171], v[202:205], v[84:87]
	v_mfma_f32_16x16x32_bf16 v[80:83], v[176:179], v[202:205], v[80:83]
	v_mfma_f32_16x16x32_bf16 v[68:71], v[168:171], v[210:213], v[68:71]
	v_mfma_f32_16x16x32_bf16 v[64:67], v[176:179], v[210:213], v[64:67]
	v_mfma_f32_16x16x32_bf16 v[116:119], v[172:175], v[188:191], v[116:119]
	v_mfma_f32_16x16x32_bf16 v[112:115], v[180:183], v[188:191], v[112:115]
	v_mfma_f32_16x16x32_bf16 v[100:103], v[172:175], v[198:201], v[100:103]
	v_mfma_f32_16x16x32_bf16 v[96:99], v[180:183], v[198:201], v[96:99]
	v_mfma_f32_16x16x32_bf16 v[84:87], v[172:175], v[206:209], v[84:87]
	v_mfma_f32_16x16x32_bf16 v[80:83], v[180:183], v[206:209], v[80:83]
	v_mfma_f32_16x16x32_bf16 v[68:71], v[172:175], v[214:217], v[68:71]
	v_mfma_f32_16x16x32_bf16 v[64:67], v[180:183], v[214:217], v[64:67]
	s_barrier
; #define PG8_STAGE(bufoff, gbase, voff) do { _Pragma("unroll") for (int _i = 0; _i < 2; ++_i) \
;         __builtin_amdgcn_global_load_lds((const unsigned*)((const char*)(gbase) + (voff)[_i]), (PG8_LAS unsigned*)(lds + (bufoff) + ldsw + _i * 8192), 16, 0, 0); } while (0)
; #define PG8_LDA(dst, b, h) do { _Pragma("unroll") for (int m = 0; m < 4; ++m) _Pragma("unroll") for (int k = 0; k < 2; ++k) dst[m][k] = *(const PG8_LAS bf16x8*)(lds + PG8_SA(b, h) + aoff + m * 2048 + k * 1024); } while (0)
; #define PG8_LDB(dst, b, h) do { _Pragma("unroll") for (int n = 0; n < 2; ++n) _Pragma("unroll") for (int k = 0; k < 2; ++k) dst[n][k] = *(const PG8_LAS bf16x8*)(lds + PG8_SB(b, h) + boff + n * 2048 + k * 1024); } while (0)
; #define PG8_MMA(ai, bj, At, Bt) do { __builtin_amdgcn_s_setprio(1); _Pragma("unroll") for (int m = 0; m < 4; ++m) _Pragma("unroll") for (int n = 0; n < 2; ++n) _Pragma("unroll") for (int k = 0; k < 2; ++k) \
;         acc[ai][bj][m][n] = __builtin_amdgcn_mfma_f32_16x16x32_bf16(Bt[n][k], At[m][k], acc[ai][bj][m][n], 0, 0, 0); __builtin_amdgcn_s_setprio(0); } while (0)
; #define PG8_WAIT_V(n) asm volatile("s_waitcnt vmcnt(" #n ")" ::: "memory")
; #define PG8_WAIT_L(n) asm volatile("s_waitcnt lgkmcnt(" #n ")" ::: "memory")
; #define PG8_BAR __builtin_amdgcn_s_barrier()
; #define PG8_SCHED __builtin_amdgcn_sched_barrier(0)
; template <class Epi, class Sched, bool ALIGN_EPI = false, bool SP2 = false>
; __device__ __forceinline__ void gemm_phase(PG8_LAS unsigned char* lds, const Gemm g, const Sched& S, const Epi& E) {
;     ...
;             PG8_LDA(At, 0, 1); PG8_STAGE(PG8_SB(0, 0), b2, voffB); PG8_STAGE(PG8_SB(0, 1), b2 + hstep, voffB); PG8_STAGE(PG8_SA(0, 0), a2, voffA);
;             PG8_WAIT_V(8); PG8_WAIT_L(0); PG8_BAR; PG8_MMA(1, 0, At, B0); PG8_MMA(1, 1, At, B1); PG8_BAR; PG8_SCHED;
;             PG8_LDB(B0, 1, 0); PG8_LDB(B1, 1, 1); PG8_SCHED; PG8_LDA(At, 1, 0); PG8_STAGE(PG8_SA(0, 1), a2 + hstep, voffA);
;             PG8_WAIT_V(8); PG8_WAIT_L(0); PG8_BAR; PG8_MMA(0, 0, At, B0); PG8_MMA(0, 1, At, B1); PG8_BAR; PG8_SCHED;
	s_add_i32 s45, s36, s24
	v_lshl_add_u64 v[218:219], s[20:21], 0, v[130:131]
	s_mov_b32 m0, s45
	ds_read_b128 v[184:187], v153 offset:16384
	ds_read_b128 v[188:191], v153 offset:17408
	ds_read_b128 v[192:195], v153 offset:18432
	ds_read_b128 v[198:201], v153 offset:19456
	ds_read_b128 v[202:205], v153 offset:20480
	ds_read_b128 v[206:209], v153 offset:21504
	ds_read_b128 v[210:213], v153 offset:22528
	ds_read_b128 v[214:217], v153 offset:23552
	global_load_lds_dwordx4 v[218:219], off
	s_add_i32 m0, s45, 0x2000
	s_add_u32 s46, s20, 0xb0000
	v_lshl_add_u64 v[220:221], s[20:21], 0, v[134:135]
	s_addc_u32 s47, s21, 0
	s_add_i32 s45, s37, s24
	global_load_lds_dwordx4 v[220:221], off
	v_lshl_add_u64 v[222:223], s[46:47], 0, v[130:131]
	s_mov_b32 m0, s45
	v_lshl_add_u64 v[224:225], s[22:23], 0, v[132:133]
	global_load_lds_dwordx4 v[222:223], off
	v_lshl_add_u64 v[222:223], s[46:47], 0, v[134:135]
	s_add_i32 m0, s45, 0x2000
	s_nop 0
	global_load_lds_dwordx4 v[222:223], off
	v_lshl_add_u64 v[222:223], s[22:23], 0, v[128:129]
	s_mov_b32 m0, s25
	s_nop 0
	global_load_lds_dwordx4 v[222:223], off
	s_mov_b32 m0, s26
	s_nop 0
	global_load_lds_dwordx4 v[224:225], off
	s_waitcnt vmcnt(8)
	s_waitcnt lgkmcnt(0)
	s_barrier
	s_waitcnt lgkmcnt(0)
	v_mfma_f32_16x16x32_bf16 v[60:63], v[144:147], v[184:187], v[60:63]
	v_mfma_f32_16x16x32_bf16 v[56:59], v[160:163], v[184:187], v[56:59]
	v_mfma_f32_16x16x32_bf16 v[44:47], v[144:147], v[192:195], v[44:47]
	v_mfma_f32_16x16x32_bf16 v[40:43], v[160:163], v[192:195], v[40:43]
	v_mfma_f32_16x16x32_bf16 v[28:31], v[144:147], v[202:205], v[28:31]
	v_mfma_f32_16x16x32_bf16 v[24:27], v[160:163], v[202:205], v[24:27]
	v_mfma_f32_16x16x32_bf16 v[12:15], v[144:147], v[210:213], v[12:15]
	v_mfma_f32_16x16x32_bf16 v[8:11], v[160:163], v[210:213], v[8:11]
	v_mfma_f32_16x16x32_bf16 v[60:63], v[156:159], v[188:191], v[60:63]
	v_mfma_f32_16x16x32_bf16 v[56:59], v[164:167], v[188:191], v[56:59]
	v_mfma_f32_16x16x32_bf16 v[44:47], v[156:159], v[198:201], v[44:47]
	v_mfma_f32_16x16x32_bf16 v[40:43], v[164:167], v[198:201], v[40:43]
	v_mfma_f32_16x16x32_bf16 v[28:31], v[156:159], v[206:209], v[28:31]
	v_mfma_f32_16x16x32_bf16 v[24:27], v[164:167], v[206:209], v[24:27]
	v_mfma_f32_16x16x32_bf16 v[12:15], v[156:159], v[214:217], v[12:15]
	v_mfma_f32_16x16x32_bf16 v[8:11], v[164:167], v[214:217], v[8:11]
	v_mfma_f32_16x16x32_bf16 v[52:55], v[168:171], v[184:187], v[52:55]
	v_mfma_f32_16x16x32_bf16 v[48:51], v[176:179], v[184:187], v[48:51]
	v_mfma_f32_16x16x32_bf16 v[36:39], v[168:171], v[192:195], v[36:39]
	v_mfma_f32_16x16x32_bf16 v[32:35], v[176:179], v[192:195], v[32:35]
	v_mfma_f32_16x16x32_bf16 v[20:23], v[168:171], v[202:205], v[20:23]
	v_mfma_f32_16x16x32_bf16 v[16:19], v[176:179], v[202:205], v[16:19]
	v_mfma_f32_16x16x32_bf16 v[4:7], v[168:171], v[210:213], v[4:7]
	v_mfma_f32_16x16x32_bf16 v[0:3], v[176:179], v[210:213], v[0:3]
	v_mfma_f32_16x16x32_bf16 v[52:55], v[172:175], v[188:191], v[52:55]
	v_mfma_f32_16x16x32_bf16 v[48:51], v[180:183], v[188:191], v[48:51]
	v_mfma_f32_16x16x32_bf16 v[36:39], v[172:175], v[198:201], v[36:39]
	v_mfma_f32_16x16x32_bf16 v[32:35], v[180:183], v[198:201], v[32:35]
	v_mfma_f32_16x16x32_bf16 v[20:23], v[172:175], v[206:209], v[20:23]
	v_mfma_f32_16x16x32_bf16 v[16:19], v[180:183], v[206:209], v[16:19]
	v_mfma_f32_16x16x32_bf16 v[4:7], v[172:175], v[214:217], v[4:7]
	v_mfma_f32_16x16x32_bf16 v[0:3], v[180:183], v[214:217], v[0:3]
	s_barrier
	s_add_i32 s45, 0, 0x18000
	v_add_u32_e32 v155, s45, v149
	s_add_i32 s46, 0, 0x1c000
	ds_read_b128 v[144:147], v155
	ds_read_b128 v[156:159], v155 offset:1024
	ds_read_b128 v[160:163], v155 offset:2048
	ds_read_b128 v[164:167], v155 offset:3072
	v_add_u32_e32 v155, s46, v149
	ds_read_b128 v[168:171], v155
	ds_read_b128 v[172:175], v155 offset:1024
	ds_read_b128 v[176:179], v155 offset:2048
	ds_read_b128 v[180:183], v155 offset:3072
	s_add_u32 s22, s22, 0xb0000
	s_addc_u32 s23, s23, 0
	s_mov_b32 m0, s27
	v_lshl_add_u64 v[226:227], s[22:23], 0, v[128:129]
	ds_read_b128 v[184:187], v153 offset:32768
	ds_read_b128 v[188:191], v153 offset:33792
	ds_read_b128 v[192:195], v153 offset:34816
	ds_read_b128 v[198:201], v153 offset:35840
	ds_read_b128 v[202:205], v153 offset:36864
	ds_read_b128 v[206:209], v153 offset:37888
	ds_read_b128 v[210:213], v153 offset:38912
	ds_read_b128 v[214:217], v153 offset:39936
	global_load_lds_dwordx4 v[226:227], off
	v_lshl_add_u64 v[226:227], s[22:23], 0, v[132:133]
	s_mov_b32 m0, s28
	s_nop 0
	global_load_lds_dwordx4 v[226:227], off
	s_waitcnt vmcnt(8)
	s_waitcnt lgkmcnt(0)
	s_barrier
; #define PG8_STAGE(bufoff, gbase, voff) do { _Pragma("unroll") for (int _i = 0; _i < 2; ++_i) \
;         __builtin_amdgcn_global_load_lds((const unsigned*)((const char*)(gbase) + (voff)[_i]), (PG8_LAS unsigned*)(lds + (bufoff) + ldsw + _i * 8192), 16, 0, 0); } while (0)
; #define PG8_LDA(dst, b, h) do { _Pragma("unroll") for (int m = 0; m < 4; ++m) _Pragma("unroll") for (int k = 0; k < 2; ++k) dst[m][k] = *(const PG8_LAS bf16x8*)(lds + PG8_SA(b, h) + aoff + m * 2048 + k * 1024); } while (0)
; #define PG8_MMA(ai, bj, At, Bt) do { __builtin_amdgcn_s_setprio(1); _Pragma("unroll") for (int m = 0; m < 4; ++m) _Pragma("unroll") for (int n = 0; n < 2; ++n) _Pragma("unroll") for (int k = 0; k < 2; ++k) \
;         acc[ai][bj][m][n] = __builtin_amdgcn_mfma_f32_16x16x32_bf16(Bt[n][k], At[m][k], acc[ai][bj][m][n], 0, 0, 0); __builtin_amdgcn_s_setprio(0); } while (0)
; #define PG8_WAIT_V(n) asm volatile("s_waitcnt vmcnt(" #n ")" ::: "memory")
; #define PG8_WAIT_L(n) asm volatile("s_waitcnt lgkmcnt(" #n ")" ::: "memory")
; #define PG8_BAR __builtin_amdgcn_s_barrier()
; #define PG8_SCHED __builtin_amdgcn_sched_barrier(0)
; template <class Epi, class Sched, bool ALIGN_EPI = false, bool SP2 = false>
; __device__ __forceinline__ void gemm_phase(PG8_LAS unsigned char* lds, const Gemm g, const Sched& S, const Epi& E) {
;     ...
;             PG8_WAIT_V(8); PG8_WAIT_L(0); PG8_BAR; PG8_MMA(0, 0, At, B0); PG8_MMA(0, 1, At, B1); PG8_BAR; PG8_SCHED;
;             PG8_LDA(At, 1, 1); PG8_STAGE(PG8_SB(1, 0), b3, voffB); PG8_STAGE(PG8_SB(1, 1), b3 + hstep, voffB); PG8_STAGE(PG8_SA(1, 0), a3, voffA);
;             PG8_WAIT_V(8); PG8_WAIT_L(0); PG8_BAR; PG8_MMA(1, 0, At, B0); PG8_MMA(1, 1, At, B1); PG8_BAR; PG8_SCHED;
	s_waitcnt lgkmcnt(0)
	v_mfma_f32_16x16x32_bf16 v[124:127], v[144:147], v[184:187], v[124:127]
	v_mfma_f32_16x16x32_bf16 v[120:123], v[160:163], v[184:187], v[120:123]
	v_mfma_f32_16x16x32_bf16 v[108:111], v[144:147], v[192:195], v[108:111]
	v_mfma_f32_16x16x32_bf16 v[104:107], v[160:163], v[192:195], v[104:107]
	v_mfma_f32_16x16x32_bf16 v[92:95], v[144:147], v[202:205], v[92:95]
	v_mfma_f32_16x16x32_bf16 v[88:91], v[160:163], v[202:205], v[88:91]
	v_mfma_f32_16x16x32_bf16 v[76:79], v[144:147], v[210:213], v[76:79]
	v_mfma_f32_16x16x32_bf16 v[72:75], v[160:163], v[210:213], v[72:75]
	v_mfma_f32_16x16x32_bf16 v[124:127], v[156:159], v[188:191], v[124:127]
	v_mfma_f32_16x16x32_bf16 v[120:123], v[164:167], v[188:191], v[120:123]
	v_mfma_f32_16x16x32_bf16 v[108:111], v[156:159], v[198:201], v[108:111]
	v_mfma_f32_16x16x32_bf16 v[104:107], v[164:167], v[198:201], v[104:107]
	v_mfma_f32_16x16x32_bf16 v[92:95], v[156:159], v[206:209], v[92:95]
	v_mfma_f32_16x16x32_bf16 v[88:91], v[164:167], v[206:209], v[88:91]
	v_mfma_f32_16x16x32_bf16 v[76:79], v[156:159], v[214:217], v[76:79]
	v_mfma_f32_16x16x32_bf16 v[72:75], v[164:167], v[214:217], v[72:75]
	v_mfma_f32_16x16x32_bf16 v[116:119], v[168:171], v[184:187], v[116:119]
	v_mfma_f32_16x16x32_bf16 v[112:115], v[176:179], v[184:187], v[112:115]
	v_mfma_f32_16x16x32_bf16 v[100:103], v[168:171], v[192:195], v[100:103]
	v_mfma_f32_16x16x32_bf16 v[96:99], v[176:179], v[192:195], v[96:99]
	v_mfma_f32_16x16x32_bf16 v[84:87], v[168:171], v[202:205], v[84:87]
	v_mfma_f32_16x16x32_bf16 v[80:83], v[176:179], v[202:205], v[80:83]
	v_mfma_f32_16x16x32_bf16 v[68:71], v[168:171], v[210:213], v[68:71]
	v_mfma_f32_16x16x32_bf16 v[64:67], v[176:179], v[210:213], v[64:67]
	v_mfma_f32_16x16x32_bf16 v[116:119], v[172:175], v[188:191], v[116:119]
	v_mfma_f32_16x16x32_bf16 v[112:115], v[180:183], v[188:191], v[112:115]
	v_mfma_f32_16x16x32_bf16 v[100:103], v[172:175], v[198:201], v[100:103]
	v_mfma_f32_16x16x32_bf16 v[96:99], v[180:183], v[198:201], v[96:99]
	v_mfma_f32_16x16x32_bf16 v[84:87], v[172:175], v[206:209], v[84:87]
	v_mfma_f32_16x16x32_bf16 v[80:83], v[180:183], v[206:209], v[80:83]
	v_mfma_f32_16x16x32_bf16 v[68:71], v[172:175], v[214:217], v[68:71]
	v_mfma_f32_16x16x32_bf16 v[64:67], v[180:183], v[214:217], v[64:67]
	s_barrier
	s_add_i32 s22, s45, s24
	v_lshl_add_u64 v[218:219], v[218:219], 0, s[12:13]
	s_mov_b32 m0, s22
	ds_read_b128 v[184:187], v153 offset:49152
	ds_read_b128 v[188:191], v153 offset:50176
	ds_read_b128 v[192:195], v153 offset:51200
	ds_read_b128 v[198:201], v153 offset:52224
	ds_read_b128 v[202:205], v153 offset:53248
	ds_read_b128 v[206:209], v153 offset:54272
	ds_read_b128 v[210:213], v153 offset:55296
	ds_read_b128 v[214:217], v153 offset:56320
	global_load_lds_dwordx4 v[218:219], off
	s_add_i32 m0, s22, 0x2000
	s_add_u32 s20, s20, 0xb0080
	v_lshl_add_u64 v[218:219], v[220:221], 0, s[12:13]
	s_addc_u32 s21, s21, 0
	s_add_i32 s22, s46, s24
	global_load_lds_dwordx4 v[218:219], off
	v_lshl_add_u64 v[218:219], s[20:21], 0, v[130:131]
	s_mov_b32 m0, s22
	s_nop 0
	global_load_lds_dwordx4 v[218:219], off
	v_lshl_add_u64 v[218:219], s[20:21], 0, v[134:135]
	s_add_i32 m0, s22, 0x2000
	s_nop 0
	global_load_lds_dwordx4 v[218:219], off
	v_lshl_add_u64 v[218:219], v[222:223], 0, s[12:13]
	s_mov_b32 m0, s33
	s_nop 0
	global_load_lds_dwordx4 v[218:219], off
	v_lshl_add_u64 v[218:219], v[224:225], 0, s[12:13]
	s_mov_b32 m0, s34
	s_nop 0
	global_load_lds_dwordx4 v[218:219], off
	s_waitcnt vmcnt(8)
	s_waitcnt lgkmcnt(0)
	s_barrier
	s_waitcnt lgkmcnt(0)
	v_mfma_f32_16x16x32_bf16 v[60:63], v[144:147], v[184:187], v[60:63]
	v_mfma_f32_16x16x32_bf16 v[56:59], v[160:163], v[184:187], v[56:59]
	v_mfma_f32_16x16x32_bf16 v[44:47], v[144:147], v[192:195], v[44:47]
	v_mfma_f32_16x16x32_bf16 v[40:43], v[160:163], v[192:195], v[40:43]
	v_mfma_f32_16x16x32_bf16 v[28:31], v[144:147], v[202:205], v[28:31]
	v_mfma_f32_16x16x32_bf16 v[24:27], v[160:163], v[202:205], v[24:27]
	v_mfma_f32_16x16x32_bf16 v[12:15], v[144:147], v[210:213], v[12:15]
	v_mfma_f32_16x16x32_bf16 v[8:11], v[160:163], v[210:213], v[8:11]
	v_mfma_f32_16x16x32_bf16 v[60:63], v[156:159], v[188:191], v[60:63]
	v_mfma_f32_16x16x32_bf16 v[56:59], v[164:167], v[188:191], v[56:59]
	v_mfma_f32_16x16x32_bf16 v[44:47], v[156:159], v[198:201], v[44:47]
	v_mfma_f32_16x16x32_bf16 v[40:43], v[164:167], v[198:201], v[40:43]
	v_mfma_f32_16x16x32_bf16 v[28:31], v[156:159], v[206:209], v[28:31]
	v_mfma_f32_16x16x32_bf16 v[24:27], v[164:167], v[206:209], v[24:27]
	v_mfma_f32_16x16x32_bf16 v[12:15], v[156:159], v[214:217], v[12:15]
	v_mfma_f32_16x16x32_bf16 v[8:11], v[164:167], v[214:217], v[8:11]
	v_mfma_f32_16x16x32_bf16 v[52:55], v[168:171], v[184:187], v[52:55]
	v_mfma_f32_16x16x32_bf16 v[48:51], v[176:179], v[184:187], v[48:51]
	v_mfma_f32_16x16x32_bf16 v[36:39], v[168:171], v[192:195], v[36:39]
	v_mfma_f32_16x16x32_bf16 v[32:35], v[176:179], v[192:195], v[32:35]
	v_mfma_f32_16x16x32_bf16 v[20:23], v[168:171], v[202:205], v[20:23]
	v_mfma_f32_16x16x32_bf16 v[16:19], v[176:179], v[202:205], v[16:19]
	v_mfma_f32_16x16x32_bf16 v[4:7], v[168:171], v[210:213], v[4:7]
	v_mfma_f32_16x16x32_bf16 v[0:3], v[176:179], v[210:213], v[0:3]
	v_mfma_f32_16x16x32_bf16 v[52:55], v[172:175], v[188:191], v[52:55]
	v_mfma_f32_16x16x32_bf16 v[48:51], v[180:183], v[188:191], v[48:51]
	v_mfma_f32_16x16x32_bf16 v[36:39], v[172:175], v[198:201], v[36:39]
	v_mfma_f32_16x16x32_bf16 v[32:35], v[180:183], v[198:201], v[32:35]
	v_mfma_f32_16x16x32_bf16 v[20:23], v[172:175], v[206:209], v[20:23]
	v_mfma_f32_16x16x32_bf16 v[16:19], v[180:183], v[206:209], v[16:19]
	v_mfma_f32_16x16x32_bf16 v[4:7], v[172:175], v[214:217], v[4:7]
	v_mfma_f32_16x16x32_bf16 v[0:3], v[180:183], v[214:217], v[0:3]
	s_barrier
	s_add_i32 s44, s44, 2
	s_add_u32 s18, s18, 0x100
	s_addc_u32 s19, s19, 0
	s_add_u32 s42, s42, 0x100
	s_addc_u32 s43, s43, 0
	s_cmp_gt_u32 s44, 41
	s_cbranch_scc0 .LBB0_1239
	s_setprio 0
	s_and_b64 vcc, exec, s[14:15]
	s_cbranch_vccz .LBB0_1242
	s_barrier
